# phase 0: nt (streaming) policy on the read-once f32 weight / input row loads
# speedup vs baseline: 1.0032x; 1.0032x over previous
.LBB0_9:
	s_cmpk_gt_i32 s92, 0xbff
	s_mov_b64 s[2:3], -1
	s_cbranch_scc0 .LBB0_115
	s_cmpk_gt_u32 s92, 0xfff
	s_cbranch_scc0 .LBB0_112
	s_cmpk_gt_u32 s92, 0x13ff
	s_cbranch_scc0 .LBB0_109
	s_cmpk_gt_u32 s92, 0x17ff
	s_cbranch_scc0 .LBB0_82
	s_cmpk_gt_u32 s92, 0x1bff
	s_cbranch_scc0 .LBB0_55
	s_cmpk_gt_u32 s92, 0x1fff
	s_cbranch_scc0 .LBB0_52
	s_cmpk_gt_u32 s92, 0x2fff
	s_cbranch_scc0 .LBB0_25
	s_cmpk_gt_u32 s92, 0x3fff
	s_cbranch_scc0 .LBB0_22
	s_and_b32 s18, s21, 0x7c0
	s_cmpk_gt_u32 s92, 0x4fff
	v_or_b32_e32 v10, s18, v115
	v_or_b32_e32 v9, s18, v116
	v_or_b32_e32 v8, s18, v117
	v_or_b32_e32 v7, s18, v118
	v_or_b32_e32 v6, s18, v119
	v_or_b32_e32 v5, s18, v120
	v_or_b32_e32 v4, s18, v121
	s_cbranch_scc0 .LBB0_19
	s_and_b32 s19, s85, 0x1ffc0
	v_or_b32_e32 v11, s19, v72
	s_lshl_b32 s14, s18, 2
	v_lshl_add_u64 v[2:3], v[78:79], 0, s[14:15]
	v_lshlrev_b32_e32 v12, 13, v11
	v_mov_b32_e32 v13, v75
	v_lshl_add_u64 v[2:3], v[2:3], 0, v[12:13]
	v_add_co_u32_e32 v16, vcc, 0x8000, v2
	s_mov_b64 s[2:3], s[28:29]
	s_nop 0
	v_addc_co_u32_e32 v17, vcc, 0, v3, vcc
	v_add_co_u32_e32 v20, vcc, 0x10000, v2
	global_load_dwordx4 v[12:15], v[2:3], off nt
	s_nop 0
	global_load_dwordx4 v[16:19], v[16:17], off nt
	v_addc_co_u32_e32 v21, vcc, 0, v3, vcc
	v_add_co_u32_e32 v24, vcc, 0x18000, v2
	s_lshl_b32 s14, s19, 1
	s_nop 0
	v_addc_co_u32_e32 v25, vcc, 0, v3, vcc
	v_add_co_u32_e32 v28, vcc, 0x20000, v2
	global_load_dwordx4 v[20:23], v[20:21], off nt
	s_nop 0
	global_load_dwordx4 v[24:27], v[24:25], off nt
	v_addc_co_u32_e32 v29, vcc, 0, v3, vcc
	v_add_co_u32_e32 v32, vcc, 0x28000, v2
	s_add_u32 s2, s2, s14
	s_nop 0
	v_addc_co_u32_e32 v33, vcc, 0, v3, vcc
	v_add_co_u32_e32 v36, vcc, 0x30000, v2
	global_load_dwordx4 v[28:31], v[28:29], off nt
	s_nop 0
	global_load_dwordx4 v[32:35], v[32:33], off nt
	v_addc_co_u32_e32 v37, vcc, 0, v3, vcc
	v_add_co_u32_e32 v40, vcc, 0x38000, v2
	s_addc_u32 s3, s3, 0
	s_nop 0
	v_addc_co_u32_e32 v41, vcc, 0, v3, vcc
	v_add_co_u32_e32 v44, vcc, 0x40000, v2
	global_load_dwordx4 v[36:39], v[36:37], off nt
	s_nop 0
	global_load_dwordx4 v[40:43], v[40:41], off nt
	v_addc_co_u32_e32 v45, vcc, 0, v3, vcc
	v_add_co_u32_e32 v48, vcc, 0x48000, v2
	s_nop 1
	v_addc_co_u32_e32 v49, vcc, 0, v3, vcc
	v_add_co_u32_e32 v52, vcc, 0x50000, v2
	global_load_dwordx4 v[44:47], v[44:45], off nt
	s_nop 0
	global_load_dwordx4 v[48:51], v[48:49], off nt
	v_addc_co_u32_e32 v53, vcc, 0, v3, vcc
	v_add_co_u32_e32 v56, vcc, 0x58000, v2
	s_nop 1
	v_addc_co_u32_e32 v57, vcc, 0, v3, vcc
	v_add_co_u32_e32 v60, vcc, 0x60000, v2
	global_load_dwordx4 v[52:55], v[52:53], off nt
	s_nop 0
	global_load_dwordx4 v[56:59], v[56:57], off nt
	v_addc_co_u32_e32 v61, vcc, 0, v3, vcc
	v_add_co_u32_e32 v64, vcc, 0x68000, v2
	s_nop 1
	v_addc_co_u32_e32 v65, vcc, 0, v3, vcc
	v_add_co_u32_e32 v68, vcc, 0x70000, v2
	global_load_dwordx4 v[60:63], v[60:61], off nt
	s_nop 0
	global_load_dwordx4 v[64:67], v[64:65], off nt
	v_addc_co_u32_e32 v69, vcc, 0, v3, vcc
	v_add_co_u32_e32 v2, vcc, 0x78000, v2
	s_nop 1
	v_addc_co_u32_e32 v3, vcc, 0, v3, vcc
	global_load_dwordx4 v[128:131], v[68:69], off nt
	global_load_dwordx4 v[132:135], v[2:3], off nt
	v_lshl_add_u64 v[2:3], s[2:3], 0, v[74:75]
	v_lshl_add_u64 v[2:3], v[2:3], 0, s[40:41]
	s_mov_b64 s[2:3], 0
	s_waitcnt vmcnt(14)
	ds_write2_b32 v99, v12, v16 offset1:4
	ds_write2_b32 v99, v13, v17 offset0:65 offset1:69
	ds_write2_b32 v99, v14, v18 offset0:130 offset1:134
	ds_write2_b32 v99, v15, v19 offset0:195 offset1:199
	s_waitcnt vmcnt(12)
	ds_write2_b32 v99, v20, v24 offset0:8 offset1:12
	ds_write2_b32 v99, v21, v25 offset0:73 offset1:77
	ds_write2_b32 v99, v22, v26 offset0:138 offset1:142
	ds_write2_b32 v99, v23, v27 offset0:203 offset1:207
	s_waitcnt vmcnt(10)
	ds_write2_b32 v99, v28, v32 offset0:16 offset1:20
	ds_write2_b32 v99, v29, v33 offset0:81 offset1:85
	ds_write2_b32 v99, v30, v34 offset0:146 offset1:150
	ds_write2_b32 v99, v31, v35 offset0:211 offset1:215
	s_waitcnt vmcnt(8)
	ds_write2_b32 v99, v36, v40 offset0:24 offset1:28
	ds_write2_b32 v99, v37, v41 offset0:89 offset1:93
	ds_write2_b32 v99, v38, v42 offset0:154 offset1:158
	ds_write2_b32 v99, v39, v43 offset0:219 offset1:223
	s_waitcnt vmcnt(6)
	ds_write2_b32 v99, v44, v48 offset0:32 offset1:36
	ds_write2_b32 v99, v45, v49 offset0:97 offset1:101
	ds_write2_b32 v99, v46, v50 offset0:162 offset1:166
	ds_write2_b32 v99, v47, v51 offset0:227 offset1:231
	s_waitcnt vmcnt(4)
	ds_write2_b32 v99, v52, v56 offset0:40 offset1:44
	ds_write2_b32 v99, v53, v57 offset0:105 offset1:109
	ds_write2_b32 v99, v54, v58 offset0:170 offset1:174
	ds_write2_b32 v99, v55, v59 offset0:235 offset1:239
	s_waitcnt vmcnt(2)
	ds_write2_b32 v99, v60, v64 offset0:48 offset1:52
	ds_write2_b32 v99, v61, v65 offset0:113 offset1:117
	ds_write2_b32 v99, v62, v66 offset0:178 offset1:182
	ds_write2_b32 v99, v63, v67 offset0:243 offset1:247
	s_waitcnt vmcnt(0)
	ds_write2_b32 v99, v128, v132 offset0:56 offset1:60
	ds_write2_b32 v99, v129, v133 offset0:121 offset1:125
	ds_write2_b32 v99, v130, v134 offset0:186 offset1:190
	ds_write2_b32 v99, v131, v135 offset0:251 offset1:255
	s_waitcnt lgkmcnt(0)
	ds_read2_b32 v[12:13], v123 offset1:1
	ds_read2_b32 v[14:15], v123 offset0:2 offset1:3
	ds_read2_b32 v[16:17], v123 offset0:4 offset1:5
	ds_read2_b32 v[18:19], v123 offset0:6 offset1:7
	s_waitcnt lgkmcnt(3)
	v_and_b32_sdwa v20, v12, v124 dst_sel:DWORD dst_unused:UNUSED_PAD src0_sel:WORD_1 src1_sel:DWORD
	s_waitcnt lgkmcnt(2)
	v_and_b32_sdwa v11, v14, v124 dst_sel:DWORD dst_unused:UNUSED_PAD src0_sel:WORD_1 src1_sel:DWORD
	v_add3_u32 v11, v14, v11, s89
	v_and_b32_sdwa v14, v15, v124 dst_sel:DWORD dst_unused:UNUSED_PAD src0_sel:WORD_1 src1_sel:DWORD
	v_add3_u32 v12, v12, v20, s89
	v_and_b32_sdwa v20, v13, v124 dst_sel:DWORD dst_unused:UNUSED_PAD src0_sel:WORD_1 src1_sel:DWORD
	v_add3_u32 v14, v15, v14, s89
	v_add3_u32 v13, v13, v20, s89
	v_and_b32_e32 v14, 0xffff0000, v14
	v_and_b32_e32 v15, 0xffff0000, v13
	v_or_b32_sdwa v13, v14, v11 dst_sel:DWORD dst_unused:UNUSED_PAD src0_sel:DWORD src1_sel:WORD_1
	s_waitcnt lgkmcnt(1)
	v_and_b32_sdwa v14, v16, v124 dst_sel:DWORD dst_unused:UNUSED_PAD src0_sel:WORD_1 src1_sel:DWORD
	v_add3_u32 v14, v16, v14, s89
	v_and_b32_sdwa v16, v17, v124 dst_sel:DWORD dst_unused:UNUSED_PAD src0_sel:WORD_1 src1_sel:DWORD
	v_or_b32_sdwa v12, v15, v12 dst_sel:DWORD dst_unused:UNUSED_PAD src0_sel:DWORD src1_sel:WORD_1
	s_waitcnt lgkmcnt(0)
	v_and_b32_sdwa v15, v19, v124 dst_sel:DWORD dst_unused:UNUSED_PAD src0_sel:WORD_1 src1_sel:DWORD
	v_add3_u32 v16, v17, v16, s89
	v_and_b32_sdwa v11, v18, v124 dst_sel:DWORD dst_unused:UNUSED_PAD src0_sel:WORD_1 src1_sel:DWORD
	v_add3_u32 v15, v19, v15, s89
	v_and_b32_e32 v16, 0xffff0000, v16
	v_add3_u32 v11, v18, v11, s89
	v_and_b32_e32 v15, 0xffff0000, v15
	v_or_b32_sdwa v14, v16, v14 dst_sel:DWORD dst_unused:UNUSED_PAD src0_sel:DWORD src1_sel:WORD_1
	v_lshlrev_b32_e32 v16, 14, v10
	v_mov_b32_e32 v17, v75
	v_or_b32_sdwa v15, v15, v11 dst_sel:DWORD dst_unused:UNUSED_PAD src0_sel:DWORD src1_sel:WORD_1
	v_lshl_add_u64 v[16:17], v[2:3], 0, v[16:17]
	global_store_dwordx4 v[16:17], v[12:15], off
	ds_read2_b32 v[12:13], v125 offset1:1
	ds_read2_b32 v[14:15], v126 offset1:1
	v_add_u32_e32 v11, 0x830, v123
	v_add_u32_e32 v18, 0x838, v123
	ds_read2_b32 v[16:17], v11 offset1:1
	ds_read2_b32 v[18:19], v18 offset1:1
	s_waitcnt lgkmcnt(3)
	v_and_b32_sdwa v20, v12, v124 dst_sel:DWORD dst_unused:UNUSED_PAD src0_sel:WORD_1 src1_sel:DWORD
	s_waitcnt lgkmcnt(2)
	v_and_b32_sdwa v11, v14, v124 dst_sel:DWORD dst_unused:UNUSED_PAD src0_sel:WORD_1 src1_sel:DWORD
	v_add3_u32 v11, v14, v11, s89
	v_and_b32_sdwa v14, v15, v124 dst_sel:DWORD dst_unused:UNUSED_PAD src0_sel:WORD_1 src1_sel:DWORD
	v_add3_u32 v12, v12, v20, s89
	v_and_b32_sdwa v20, v13, v124 dst_sel:DWORD dst_unused:UNUSED_PAD src0_sel:WORD_1 src1_sel:DWORD
	v_add3_u32 v14, v15, v14, s89
	v_add3_u32 v13, v13, v20, s89
	v_and_b32_e32 v14, 0xffff0000, v14
	v_and_b32_e32 v15, 0xffff0000, v13
	v_or_b32_sdwa v13, v14, v11 dst_sel:DWORD dst_unused:UNUSED_PAD src0_sel:DWORD src1_sel:WORD_1
	s_waitcnt lgkmcnt(1)
	v_and_b32_sdwa v14, v16, v124 dst_sel:DWORD dst_unused:UNUSED_PAD src0_sel:WORD_1 src1_sel:DWORD
	v_add3_u32 v14, v16, v14, s89
	v_and_b32_sdwa v16, v17, v124 dst_sel:DWORD dst_unused:UNUSED_PAD src0_sel:WORD_1 src1_sel:DWORD
	v_or_b32_sdwa v12, v15, v12 dst_sel:DWORD dst_unused:UNUSED_PAD src0_sel:DWORD src1_sel:WORD_1
	s_waitcnt lgkmcnt(0)
	v_and_b32_sdwa v15, v19, v124 dst_sel:DWORD dst_unused:UNUSED_PAD src0_sel:WORD_1 src1_sel:DWORD
	v_add3_u32 v16, v17, v16, s89
	v_and_b32_sdwa v11, v18, v124 dst_sel:DWORD dst_unused:UNUSED_PAD src0_sel:WORD_1 src1_sel:DWORD
	v_add3_u32 v15, v19, v15, s89
	v_and_b32_e32 v16, 0xffff0000, v16
	v_add3_u32 v11, v18, v11, s89
	v_and_b32_e32 v15, 0xffff0000, v15
	v_or_b32_sdwa v14, v16, v14 dst_sel:DWORD dst_unused:UNUSED_PAD src0_sel:DWORD src1_sel:WORD_1
	v_lshlrev_b32_e32 v16, 14, v9
	v_mov_b32_e32 v17, v75
	v_or_b32_sdwa v15, v15, v11 dst_sel:DWORD dst_unused:UNUSED_PAD src0_sel:DWORD src1_sel:WORD_1
	v_lshl_add_u64 v[16:17], v[2:3], 0, v[16:17]
	global_store_dwordx4 v[16:17], v[12:15], off
	v_add_u32_e32 v11, 0x1040, v123
	v_add_u32_e32 v18, 0x1058, v123
	v_add_u32_e32 v14, 0x1048, v123
	ds_read2_b32 v[12:13], v11 offset1:1
	ds_read2_b32 v[14:15], v14 offset1:1
	v_add_u32_e32 v11, 0x1050, v123
	ds_read2_b32 v[16:17], v11 offset1:1
	ds_read2_b32 v[18:19], v18 offset1:1
	s_waitcnt lgkmcnt(3)
	v_and_b32_sdwa v20, v12, v124 dst_sel:DWORD dst_unused:UNUSED_PAD src0_sel:WORD_1 src1_sel:DWORD
	s_waitcnt lgkmcnt(2)
	v_and_b32_sdwa v11, v14, v124 dst_sel:DWORD dst_unused:UNUSED_PAD src0_sel:WORD_1 src1_sel:DWORD
	v_add3_u32 v11, v14, v11, s89
	v_and_b32_sdwa v14, v15, v124 dst_sel:DWORD dst_unused:UNUSED_PAD src0_sel:WORD_1 src1_sel:DWORD
	v_add3_u32 v12, v12, v20, s89
	v_and_b32_sdwa v20, v13, v124 dst_sel:DWORD dst_unused:UNUSED_PAD src0_sel:WORD_1 src1_sel:DWORD
	v_add3_u32 v14, v15, v14, s89
	v_add3_u32 v13, v13, v20, s89
	v_and_b32_e32 v14, 0xffff0000, v14
	v_and_b32_e32 v15, 0xffff0000, v13
	v_or_b32_sdwa v13, v14, v11 dst_sel:DWORD dst_unused:UNUSED_PAD src0_sel:DWORD src1_sel:WORD_1
	s_waitcnt lgkmcnt(1)
	v_and_b32_sdwa v14, v16, v124 dst_sel:DWORD dst_unused:UNUSED_PAD src0_sel:WORD_1 src1_sel:DWORD
	v_add3_u32 v14, v16, v14, s89
	v_and_b32_sdwa v16, v17, v124 dst_sel:DWORD dst_unused:UNUSED_PAD src0_sel:WORD_1 src1_sel:DWORD
	v_or_b32_sdwa v12, v15, v12 dst_sel:DWORD dst_unused:UNUSED_PAD src0_sel:DWORD src1_sel:WORD_1
	s_waitcnt lgkmcnt(0)
	v_and_b32_sdwa v15, v19, v124 dst_sel:DWORD dst_unused:UNUSED_PAD src0_sel:WORD_1 src1_sel:DWORD
	v_add3_u32 v16, v17, v16, s89
	v_and_b32_sdwa v11, v18, v124 dst_sel:DWORD dst_unused:UNUSED_PAD src0_sel:WORD_1 src1_sel:DWORD
	v_add3_u32 v15, v19, v15, s89
	v_and_b32_e32 v16, 0xffff0000, v16
	v_add3_u32 v11, v18, v11, s89
	v_and_b32_e32 v15, 0xffff0000, v15
	v_or_b32_sdwa v14, v16, v14 dst_sel:DWORD dst_unused:UNUSED_PAD src0_sel:DWORD src1_sel:WORD_1
	v_lshlrev_b32_e32 v16, 14, v8
	v_mov_b32_e32 v17, v75
	v_or_b32_sdwa v15, v15, v11 dst_sel:DWORD dst_unused:UNUSED_PAD src0_sel:DWORD src1_sel:WORD_1
	v_lshl_add_u64 v[16:17], v[2:3], 0, v[16:17]
	global_store_dwordx4 v[16:17], v[12:15], off
	v_add_u32_e32 v11, 0x1860, v123
	v_add_u32_e32 v18, 0x1878, v123
	v_add_u32_e32 v14, 0x1868, v123
	ds_read2_b32 v[12:13], v11 offset1:1
	ds_read2_b32 v[14:15], v14 offset1:1
	v_add_u32_e32 v11, 0x1870, v123
	ds_read2_b32 v[16:17], v11 offset1:1
	ds_read2_b32 v[18:19], v18 offset1:1
	s_waitcnt lgkmcnt(3)
	v_and_b32_sdwa v20, v12, v124 dst_sel:DWORD dst_unused:UNUSED_PAD src0_sel:WORD_1 src1_sel:DWORD
	s_waitcnt lgkmcnt(2)
	v_and_b32_sdwa v11, v14, v124 dst_sel:DWORD dst_unused:UNUSED_PAD src0_sel:WORD_1 src1_sel:DWORD
	v_add3_u32 v11, v14, v11, s89
	v_and_b32_sdwa v14, v15, v124 dst_sel:DWORD dst_unused:UNUSED_PAD src0_sel:WORD_1 src1_sel:DWORD
	v_add3_u32 v12, v12, v20, s89
	v_and_b32_sdwa v20, v13, v124 dst_sel:DWORD dst_unused:UNUSED_PAD src0_sel:WORD_1 src1_sel:DWORD
	v_add3_u32 v14, v15, v14, s89
	v_add3_u32 v13, v13, v20, s89
	v_and_b32_e32 v14, 0xffff0000, v14
	v_and_b32_e32 v15, 0xffff0000, v13
	v_or_b32_sdwa v13, v14, v11 dst_sel:DWORD dst_unused:UNUSED_PAD src0_sel:DWORD src1_sel:WORD_1
	s_waitcnt lgkmcnt(1)
	v_and_b32_sdwa v14, v16, v124 dst_sel:DWORD dst_unused:UNUSED_PAD src0_sel:WORD_1 src1_sel:DWORD
	v_add3_u32 v14, v16, v14, s89
	v_and_b32_sdwa v16, v17, v124 dst_sel:DWORD dst_unused:UNUSED_PAD src0_sel:WORD_1 src1_sel:DWORD
	v_or_b32_sdwa v12, v15, v12 dst_sel:DWORD dst_unused:UNUSED_PAD src0_sel:DWORD src1_sel:WORD_1
	s_waitcnt lgkmcnt(0)
	v_and_b32_sdwa v15, v19, v124 dst_sel:DWORD dst_unused:UNUSED_PAD src0_sel:WORD_1 src1_sel:DWORD
	v_add3_u32 v16, v17, v16, s89
	v_and_b32_sdwa v11, v18, v124 dst_sel:DWORD dst_unused:UNUSED_PAD src0_sel:WORD_1 src1_sel:DWORD
	v_add3_u32 v15, v19, v15, s89
	v_and_b32_e32 v16, 0xffff0000, v16
	v_add3_u32 v11, v18, v11, s89
	v_and_b32_e32 v15, 0xffff0000, v15
	v_or_b32_sdwa v14, v16, v14 dst_sel:DWORD dst_unused:UNUSED_PAD src0_sel:DWORD src1_sel:WORD_1
	v_lshlrev_b32_e32 v16, 14, v7
	v_mov_b32_e32 v17, v75
	v_or_b32_sdwa v15, v15, v11 dst_sel:DWORD dst_unused:UNUSED_PAD src0_sel:DWORD src1_sel:WORD_1
	v_lshl_add_u64 v[16:17], v[2:3], 0, v[16:17]
	global_store_dwordx4 v[16:17], v[12:15], off
	v_add_u32_e32 v11, 0x2080, v123
	v_add_u32_e32 v18, 0x2098, v123
	v_add_u32_e32 v14, 0x2088, v123
	ds_read2_b32 v[12:13], v11 offset1:1
	ds_read2_b32 v[14:15], v14 offset1:1
	v_add_u32_e32 v11, 0x2090, v123
	ds_read2_b32 v[16:17], v11 offset1:1
	ds_read2_b32 v[18:19], v18 offset1:1
	s_waitcnt lgkmcnt(3)
	v_and_b32_sdwa v20, v12, v124 dst_sel:DWORD dst_unused:UNUSED_PAD src0_sel:WORD_1 src1_sel:DWORD
	s_waitcnt lgkmcnt(2)
	v_and_b32_sdwa v11, v14, v124 dst_sel:DWORD dst_unused:UNUSED_PAD src0_sel:WORD_1 src1_sel:DWORD
	v_add3_u32 v11, v14, v11, s89
	v_and_b32_sdwa v14, v15, v124 dst_sel:DWORD dst_unused:UNUSED_PAD src0_sel:WORD_1 src1_sel:DWORD
	v_add3_u32 v12, v12, v20, s89
	v_and_b32_sdwa v20, v13, v124 dst_sel:DWORD dst_unused:UNUSED_PAD src0_sel:WORD_1 src1_sel:DWORD
	v_add3_u32 v14, v15, v14, s89
	v_add3_u32 v13, v13, v20, s89
	v_and_b32_e32 v14, 0xffff0000, v14
	v_and_b32_e32 v15, 0xffff0000, v13
	v_or_b32_sdwa v13, v14, v11 dst_sel:DWORD dst_unused:UNUSED_PAD src0_sel:DWORD src1_sel:WORD_1
	s_waitcnt lgkmcnt(1)
	v_and_b32_sdwa v14, v16, v124 dst_sel:DWORD dst_unused:UNUSED_PAD src0_sel:WORD_1 src1_sel:DWORD
	v_add3_u32 v14, v16, v14, s89
	v_and_b32_sdwa v16, v17, v124 dst_sel:DWORD dst_unused:UNUSED_PAD src0_sel:WORD_1 src1_sel:DWORD
	v_or_b32_sdwa v12, v15, v12 dst_sel:DWORD dst_unused:UNUSED_PAD src0_sel:DWORD src1_sel:WORD_1
	s_waitcnt lgkmcnt(0)
	v_and_b32_sdwa v15, v19, v124 dst_sel:DWORD dst_unused:UNUSED_PAD src0_sel:WORD_1 src1_sel:DWORD
	v_add3_u32 v16, v17, v16, s89
	v_and_b32_sdwa v11, v18, v124 dst_sel:DWORD dst_unused:UNUSED_PAD src0_sel:WORD_1 src1_sel:DWORD
	v_add3_u32 v15, v19, v15, s89
	v_and_b32_e32 v16, 0xffff0000, v16
	v_add3_u32 v11, v18, v11, s89
	v_and_b32_e32 v15, 0xffff0000, v15
	v_or_b32_sdwa v14, v16, v14 dst_sel:DWORD dst_unused:UNUSED_PAD src0_sel:DWORD src1_sel:WORD_1
	v_lshlrev_b32_e32 v16, 14, v6
	v_mov_b32_e32 v17, v75
	v_or_b32_sdwa v15, v15, v11 dst_sel:DWORD dst_unused:UNUSED_PAD src0_sel:DWORD src1_sel:WORD_1
	v_lshl_add_u64 v[16:17], v[2:3], 0, v[16:17]
	global_store_dwordx4 v[16:17], v[12:15], off
	v_add_u32_e32 v11, 0x28a0, v123
	v_add_u32_e32 v18, 0x28b8, v123
	v_add_u32_e32 v14, 0x28a8, v123
	ds_read2_b32 v[12:13], v11 offset1:1
	ds_read2_b32 v[14:15], v14 offset1:1
	v_add_u32_e32 v11, 0x28b0, v123
	ds_read2_b32 v[16:17], v11 offset1:1
	ds_read2_b32 v[18:19], v18 offset1:1
	s_waitcnt lgkmcnt(3)
	v_and_b32_sdwa v20, v12, v124 dst_sel:DWORD dst_unused:UNUSED_PAD src0_sel:WORD_1 src1_sel:DWORD
	s_waitcnt lgkmcnt(2)
	v_and_b32_sdwa v11, v14, v124 dst_sel:DWORD dst_unused:UNUSED_PAD src0_sel:WORD_1 src1_sel:DWORD
	v_add3_u32 v11, v14, v11, s89
	v_and_b32_sdwa v14, v15, v124 dst_sel:DWORD dst_unused:UNUSED_PAD src0_sel:WORD_1 src1_sel:DWORD
	v_add3_u32 v12, v12, v20, s89
	v_and_b32_sdwa v20, v13, v124 dst_sel:DWORD dst_unused:UNUSED_PAD src0_sel:WORD_1 src1_sel:DWORD
	v_add3_u32 v14, v15, v14, s89
	v_add3_u32 v13, v13, v20, s89
	v_and_b32_e32 v14, 0xffff0000, v14
	v_and_b32_e32 v15, 0xffff0000, v13
	v_or_b32_sdwa v13, v14, v11 dst_sel:DWORD dst_unused:UNUSED_PAD src0_sel:DWORD src1_sel:WORD_1
	s_waitcnt lgkmcnt(1)
	v_and_b32_sdwa v14, v16, v124 dst_sel:DWORD dst_unused:UNUSED_PAD src0_sel:WORD_1 src1_sel:DWORD
	v_add3_u32 v14, v16, v14, s89
	v_and_b32_sdwa v16, v17, v124 dst_sel:DWORD dst_unused:UNUSED_PAD src0_sel:WORD_1 src1_sel:DWORD
	v_or_b32_sdwa v12, v15, v12 dst_sel:DWORD dst_unused:UNUSED_PAD src0_sel:DWORD src1_sel:WORD_1
	s_waitcnt lgkmcnt(0)
	v_and_b32_sdwa v15, v19, v124 dst_sel:DWORD dst_unused:UNUSED_PAD src0_sel:WORD_1 src1_sel:DWORD
	v_add3_u32 v16, v17, v16, s89
	v_and_b32_sdwa v11, v18, v124 dst_sel:DWORD dst_unused:UNUSED_PAD src0_sel:WORD_1 src1_sel:DWORD
	v_add3_u32 v15, v19, v15, s89
	v_and_b32_e32 v16, 0xffff0000, v16
	v_add3_u32 v11, v18, v11, s89
	v_and_b32_e32 v15, 0xffff0000, v15
	v_or_b32_sdwa v14, v16, v14 dst_sel:DWORD dst_unused:UNUSED_PAD src0_sel:DWORD src1_sel:WORD_1
	v_lshlrev_b32_e32 v16, 14, v5
	v_mov_b32_e32 v17, v75
	v_or_b32_sdwa v15, v15, v11 dst_sel:DWORD dst_unused:UNUSED_PAD src0_sel:DWORD src1_sel:WORD_1
	v_lshl_add_u64 v[16:17], v[2:3], 0, v[16:17]
	global_store_dwordx4 v[16:17], v[12:15], off
	v_add_u32_e32 v11, 0x30c0, v123
	v_add_u32_e32 v18, 0x30d8, v123
	v_add_u32_e32 v14, 0x30c8, v123
	ds_read2_b32 v[12:13], v11 offset1:1
	ds_read2_b32 v[14:15], v14 offset1:1
	v_add_u32_e32 v11, 0x30d0, v123
	ds_read2_b32 v[16:17], v11 offset1:1
	ds_read2_b32 v[18:19], v18 offset1:1
	s_waitcnt lgkmcnt(3)
	v_and_b32_sdwa v20, v12, v124 dst_sel:DWORD dst_unused:UNUSED_PAD src0_sel:WORD_1 src1_sel:DWORD
	s_waitcnt lgkmcnt(2)
	v_and_b32_sdwa v11, v14, v124 dst_sel:DWORD dst_unused:UNUSED_PAD src0_sel:WORD_1 src1_sel:DWORD
	v_add3_u32 v11, v14, v11, s89
	v_and_b32_sdwa v14, v15, v124 dst_sel:DWORD dst_unused:UNUSED_PAD src0_sel:WORD_1 src1_sel:DWORD
	v_add3_u32 v12, v12, v20, s89
	v_and_b32_sdwa v20, v13, v124 dst_sel:DWORD dst_unused:UNUSED_PAD src0_sel:WORD_1 src1_sel:DWORD
	v_add3_u32 v14, v15, v14, s89
	v_add3_u32 v13, v13, v20, s89
	v_and_b32_e32 v14, 0xffff0000, v14
	v_and_b32_e32 v15, 0xffff0000, v13
	v_or_b32_sdwa v13, v14, v11 dst_sel:DWORD dst_unused:UNUSED_PAD src0_sel:DWORD src1_sel:WORD_1
	s_waitcnt lgkmcnt(1)
	v_and_b32_sdwa v14, v16, v124 dst_sel:DWORD dst_unused:UNUSED_PAD src0_sel:WORD_1 src1_sel:DWORD
	v_add3_u32 v14, v16, v14, s89
	v_and_b32_sdwa v16, v17, v124 dst_sel:DWORD dst_unused:UNUSED_PAD src0_sel:WORD_1 src1_sel:DWORD
	v_or_b32_sdwa v12, v15, v12 dst_sel:DWORD dst_unused:UNUSED_PAD src0_sel:DWORD src1_sel:WORD_1
	s_waitcnt lgkmcnt(0)
	v_and_b32_sdwa v15, v19, v124 dst_sel:DWORD dst_unused:UNUSED_PAD src0_sel:WORD_1 src1_sel:DWORD
	v_add3_u32 v16, v17, v16, s89
	v_and_b32_sdwa v11, v18, v124 dst_sel:DWORD dst_unused:UNUSED_PAD src0_sel:WORD_1 src1_sel:DWORD
	v_add3_u32 v15, v19, v15, s89
	v_and_b32_e32 v16, 0xffff0000, v16
	v_add3_u32 v11, v18, v11, s89
	v_and_b32_e32 v15, 0xffff0000, v15
	v_or_b32_sdwa v14, v16, v14 dst_sel:DWORD dst_unused:UNUSED_PAD src0_sel:DWORD src1_sel:WORD_1
	v_lshlrev_b32_e32 v16, 14, v4
	v_mov_b32_e32 v17, v75
	v_or_b32_sdwa v15, v15, v11 dst_sel:DWORD dst_unused:UNUSED_PAD src0_sel:DWORD src1_sel:WORD_1
	v_lshl_add_u64 v[16:17], v[2:3], 0, v[16:17]
	global_store_dwordx4 v[16:17], v[12:15], off
	v_add_u32_e32 v11, 0x38e0, v123
	v_add_u32_e32 v18, 0x38f8, v123
	v_add_u32_e32 v14, 0x38e8, v123
	ds_read2_b32 v[12:13], v11 offset1:1
	ds_read2_b32 v[14:15], v14 offset1:1
	v_add_u32_e32 v11, 0x38f0, v123
	ds_read2_b32 v[16:17], v11 offset1:1
	ds_read2_b32 v[18:19], v18 offset1:1
	s_waitcnt lgkmcnt(3)
	v_and_b32_sdwa v20, v12, v124 dst_sel:DWORD dst_unused:UNUSED_PAD src0_sel:WORD_1 src1_sel:DWORD
	s_waitcnt lgkmcnt(2)
	v_and_b32_sdwa v11, v14, v124 dst_sel:DWORD dst_unused:UNUSED_PAD src0_sel:WORD_1 src1_sel:DWORD
	v_add3_u32 v12, v12, v20, s89
	v_add3_u32 v11, v14, v11, s89
	v_and_b32_sdwa v14, v15, v124 dst_sel:DWORD dst_unused:UNUSED_PAD src0_sel:WORD_1 src1_sel:DWORD
	v_and_b32_sdwa v20, v13, v124 dst_sel:DWORD dst_unused:UNUSED_PAD src0_sel:WORD_1 src1_sel:DWORD
	v_add3_u32 v14, v15, v14, s89
	v_add3_u32 v13, v13, v20, s89
	v_and_b32_e32 v14, 0xffff0000, v14
	v_and_b32_e32 v15, 0xffff0000, v13
	v_or_b32_sdwa v13, v14, v11 dst_sel:DWORD dst_unused:UNUSED_PAD src0_sel:DWORD src1_sel:WORD_1
	v_or_b32_sdwa v12, v15, v12 dst_sel:DWORD dst_unused:UNUSED_PAD src0_sel:DWORD src1_sel:WORD_1
	s_waitcnt lgkmcnt(1)
	v_and_b32_sdwa v14, v16, v124 dst_sel:DWORD dst_unused:UNUSED_PAD src0_sel:WORD_1 src1_sel:DWORD
	s_waitcnt lgkmcnt(0)
	v_and_b32_sdwa v15, v19, v124 dst_sel:DWORD dst_unused:UNUSED_PAD src0_sel:WORD_1 src1_sel:DWORD
	v_and_b32_sdwa v11, v18, v124 dst_sel:DWORD dst_unused:UNUSED_PAD src0_sel:WORD_1 src1_sel:DWORD
	v_add3_u32 v14, v16, v14, s89
	v_and_b32_sdwa v16, v17, v124 dst_sel:DWORD dst_unused:UNUSED_PAD src0_sel:WORD_1 src1_sel:DWORD
	v_add3_u32 v15, v19, v15, s89
	v_add3_u32 v11, v18, v11, s89
	v_add3_u32 v16, v17, v16, s89
	v_and_b32_e32 v15, 0xffff0000, v15
	v_and_b32_e32 v16, 0xffff0000, v16
	v_or_b32_sdwa v15, v15, v11 dst_sel:DWORD dst_unused:UNUSED_PAD src0_sel:DWORD src1_sel:WORD_1
	v_or_b32_e32 v11, s18, v122
	v_or_b32_sdwa v14, v16, v14 dst_sel:DWORD dst_unused:UNUSED_PAD src0_sel:DWORD src1_sel:WORD_1
	v_lshlrev_b32_e32 v16, 14, v11
	v_mov_b32_e32 v17, v75
	v_lshl_add_u64 v[2:3], v[2:3], 0, v[16:17]
	global_store_dwordx4 v[2:3], v[12:15], off
	s_waitcnt lgkmcnt(0)
.LBB0_19:
	s_andn2_b64 vcc, exec, s[2:3]
	s_cbranch_vccnz .LBB0_21
	s_add_i32 s14, s85, 0x2000
	s_and_b32 s19, s14, 0x1ffc0
	v_or_b32_e32 v11, s19, v72
	s_lshl_b32 s14, s18, 2
	v_lshl_add_u64 v[2:3], v[76:77], 0, s[14:15]
	v_lshlrev_b32_e32 v12, 13, v11
	v_mov_b32_e32 v13, v75
	v_lshl_add_u64 v[2:3], v[2:3], 0, v[12:13]
	v_add_co_u32_e32 v16, vcc, 0x8000, v2
	s_mov_b64 s[2:3], s[28:29]
	s_nop 0
	v_addc_co_u32_e32 v17, vcc, 0, v3, vcc
	v_add_co_u32_e32 v20, vcc, 0x10000, v2
	global_load_dwordx4 v[12:15], v[2:3], off nt
	s_nop 0
	global_load_dwordx4 v[16:19], v[16:17], off nt
	v_addc_co_u32_e32 v21, vcc, 0, v3, vcc
	v_add_co_u32_e32 v24, vcc, 0x18000, v2
	s_lshl_b32 s14, s19, 1
	s_nop 0
	v_addc_co_u32_e32 v25, vcc, 0, v3, vcc
	v_add_co_u32_e32 v28, vcc, 0x20000, v2
	global_load_dwordx4 v[20:23], v[20:21], off nt
	s_nop 0
	global_load_dwordx4 v[24:27], v[24:25], off nt
	v_addc_co_u32_e32 v29, vcc, 0, v3, vcc
	v_add_co_u32_e32 v32, vcc, 0x28000, v2
	s_add_u32 s2, s2, s14
	s_nop 0
	v_addc_co_u32_e32 v33, vcc, 0, v3, vcc
	v_add_co_u32_e32 v36, vcc, 0x30000, v2
	global_load_dwordx4 v[28:31], v[28:29], off nt
	s_nop 0
	global_load_dwordx4 v[32:35], v[32:33], off nt
	v_addc_co_u32_e32 v37, vcc, 0, v3, vcc
	v_add_co_u32_e32 v40, vcc, 0x38000, v2
	s_addc_u32 s3, s3, 0
	s_nop 0
	v_addc_co_u32_e32 v41, vcc, 0, v3, vcc
	v_add_co_u32_e32 v44, vcc, 0x40000, v2
	global_load_dwordx4 v[36:39], v[36:37], off nt
	s_nop 0
	global_load_dwordx4 v[40:43], v[40:41], off nt
	v_addc_co_u32_e32 v45, vcc, 0, v3, vcc
	v_add_co_u32_e32 v48, vcc, 0x48000, v2
	v_lshlrev_b32_e32 v10, 14, v10
	s_nop 0
	v_addc_co_u32_e32 v49, vcc, 0, v3, vcc
	v_add_co_u32_e32 v52, vcc, 0x50000, v2
	global_load_dwordx4 v[44:47], v[44:45], off nt
	s_nop 0
	global_load_dwordx4 v[48:51], v[48:49], off nt
	v_addc_co_u32_e32 v53, vcc, 0, v3, vcc
	v_add_co_u32_e32 v56, vcc, 0x58000, v2
	v_lshlrev_b32_e32 v8, 14, v8
	s_nop 0
	v_addc_co_u32_e32 v57, vcc, 0, v3, vcc
	v_add_co_u32_e32 v60, vcc, 0x60000, v2
	global_load_dwordx4 v[52:55], v[52:53], off nt
	s_nop 0
	global_load_dwordx4 v[56:59], v[56:57], off nt
	v_addc_co_u32_e32 v61, vcc, 0, v3, vcc
	v_add_co_u32_e32 v64, vcc, 0x68000, v2
	v_lshlrev_b32_e32 v6, 14, v6
	s_nop 0
	v_addc_co_u32_e32 v65, vcc, 0, v3, vcc
	v_add_co_u32_e32 v68, vcc, 0x70000, v2
	global_load_dwordx4 v[60:63], v[60:61], off nt
	s_nop 0
	global_load_dwordx4 v[64:67], v[64:65], off nt
	v_addc_co_u32_e32 v69, vcc, 0, v3, vcc
	v_add_co_u32_e32 v2, vcc, 0x78000, v2
	v_lshlrev_b32_e32 v4, 14, v4
	s_nop 0
	v_addc_co_u32_e32 v3, vcc, 0, v3, vcc
	global_load_dwordx4 v[128:131], v[68:69], off nt
	global_load_dwordx4 v[132:135], v[2:3], off nt
	v_lshl_add_u64 v[2:3], s[2:3], 0, v[74:75]
	v_lshl_add_u64 v[2:3], v[2:3], 0, s[44:45]
	s_waitcnt vmcnt(14)
	ds_write2_b32 v99, v12, v16 offset1:4
	ds_write2_b32 v99, v13, v17 offset0:65 offset1:69
	ds_write2_b32 v99, v14, v18 offset0:130 offset1:134
	ds_write2_b32 v99, v15, v19 offset0:195 offset1:199
	s_waitcnt vmcnt(12)
	ds_write2_b32 v99, v20, v24 offset0:8 offset1:12
	ds_write2_b32 v99, v21, v25 offset0:73 offset1:77
	ds_write2_b32 v99, v22, v26 offset0:138 offset1:142
	ds_write2_b32 v99, v23, v27 offset0:203 offset1:207
	s_waitcnt vmcnt(10)
	ds_write2_b32 v99, v28, v32 offset0:16 offset1:20
	ds_write2_b32 v99, v29, v33 offset0:81 offset1:85
	ds_write2_b32 v99, v30, v34 offset0:146 offset1:150
	ds_write2_b32 v99, v31, v35 offset0:211 offset1:215
	s_waitcnt vmcnt(8)
	ds_write2_b32 v99, v36, v40 offset0:24 offset1:28
	ds_write2_b32 v99, v37, v41 offset0:89 offset1:93
	ds_write2_b32 v99, v38, v42 offset0:154 offset1:158
	ds_write2_b32 v99, v39, v43 offset0:219 offset1:223
	s_waitcnt vmcnt(6)
	ds_write2_b32 v99, v44, v48 offset0:32 offset1:36
	ds_write2_b32 v99, v45, v49 offset0:97 offset1:101
	ds_write2_b32 v99, v46, v50 offset0:162 offset1:166
	ds_write2_b32 v99, v47, v51 offset0:227 offset1:231
	s_waitcnt vmcnt(4)
	ds_write2_b32 v99, v52, v56 offset0:40 offset1:44
	ds_write2_b32 v99, v53, v57 offset0:105 offset1:109
	ds_write2_b32 v99, v54, v58 offset0:170 offset1:174
	ds_write2_b32 v99, v55, v59 offset0:235 offset1:239
	s_waitcnt vmcnt(2)
	ds_write2_b32 v99, v60, v64 offset0:48 offset1:52
	ds_write2_b32 v99, v61, v65 offset0:113 offset1:117
	ds_write2_b32 v99, v62, v66 offset0:178 offset1:182
	ds_write2_b32 v99, v63, v67 offset0:243 offset1:247
	s_waitcnt vmcnt(0)
	ds_write2_b32 v99, v128, v132 offset0:56 offset1:60
	ds_write2_b32 v99, v129, v133 offset0:121 offset1:125
	ds_write2_b32 v99, v130, v134 offset0:186 offset1:190
	ds_write2_b32 v99, v131, v135 offset0:251 offset1:255
	s_waitcnt lgkmcnt(0)
	ds_read2_b32 v[12:13], v123 offset1:1
	ds_read2_b32 v[14:15], v123 offset0:2 offset1:3
	ds_read2_b32 v[16:17], v123 offset0:4 offset1:5
	ds_read2_b32 v[18:19], v123 offset0:6 offset1:7
	s_waitcnt lgkmcnt(3)
	v_and_b32_sdwa v20, v12, v124 dst_sel:DWORD dst_unused:UNUSED_PAD src0_sel:WORD_1 src1_sel:DWORD
	s_waitcnt lgkmcnt(2)
	v_and_b32_sdwa v11, v14, v124 dst_sel:DWORD dst_unused:UNUSED_PAD src0_sel:WORD_1 src1_sel:DWORD
	v_add3_u32 v12, v12, v20, s89
	v_add3_u32 v11, v14, v11, s89
	v_and_b32_sdwa v14, v15, v124 dst_sel:DWORD dst_unused:UNUSED_PAD src0_sel:WORD_1 src1_sel:DWORD
	v_and_b32_sdwa v20, v13, v124 dst_sel:DWORD dst_unused:UNUSED_PAD src0_sel:WORD_1 src1_sel:DWORD
	v_add3_u32 v14, v15, v14, s89
	v_add3_u32 v13, v13, v20, s89
	v_and_b32_e32 v14, 0xffff0000, v14
	v_and_b32_e32 v15, 0xffff0000, v13
	v_or_b32_sdwa v13, v14, v11 dst_sel:DWORD dst_unused:UNUSED_PAD src0_sel:DWORD src1_sel:WORD_1
	v_or_b32_sdwa v12, v15, v12 dst_sel:DWORD dst_unused:UNUSED_PAD src0_sel:DWORD src1_sel:WORD_1
	s_waitcnt lgkmcnt(1)
	v_and_b32_sdwa v14, v16, v124 dst_sel:DWORD dst_unused:UNUSED_PAD src0_sel:WORD_1 src1_sel:DWORD
	s_waitcnt lgkmcnt(0)
	v_and_b32_sdwa v15, v19, v124 dst_sel:DWORD dst_unused:UNUSED_PAD src0_sel:WORD_1 src1_sel:DWORD
	v_and_b32_sdwa v11, v18, v124 dst_sel:DWORD dst_unused:UNUSED_PAD src0_sel:WORD_1 src1_sel:DWORD
	v_add3_u32 v14, v16, v14, s89
	v_and_b32_sdwa v16, v17, v124 dst_sel:DWORD dst_unused:UNUSED_PAD src0_sel:WORD_1 src1_sel:DWORD
	v_add3_u32 v15, v19, v15, s89
	v_add3_u32 v11, v18, v11, s89
	v_add3_u32 v16, v17, v16, s89
	v_and_b32_e32 v15, 0xffff0000, v15
	v_and_b32_e32 v16, 0xffff0000, v16
	v_or_b32_sdwa v15, v15, v11 dst_sel:DWORD dst_unused:UNUSED_PAD src0_sel:DWORD src1_sel:WORD_1
	v_mov_b32_e32 v11, v75
	v_or_b32_sdwa v14, v16, v14 dst_sel:DWORD dst_unused:UNUSED_PAD src0_sel:DWORD src1_sel:WORD_1
	v_lshl_add_u64 v[10:11], v[2:3], 0, v[10:11]
	global_store_dwordx4 v[10:11], v[12:15], off
	ds_read2_b32 v[10:11], v125 offset1:1
	ds_read2_b32 v[12:13], v126 offset1:1
	v_add_u32_e32 v14, 0x830, v123
	v_add_u32_e32 v16, 0x838, v123
	ds_read2_b32 v[14:15], v14 offset1:1
	ds_read2_b32 v[16:17], v16 offset1:1
	s_waitcnt lgkmcnt(3)
	v_and_b32_sdwa v19, v10, v124 dst_sel:DWORD dst_unused:UNUSED_PAD src0_sel:WORD_1 src1_sel:DWORD
	s_waitcnt lgkmcnt(2)
	v_and_b32_sdwa v18, v12, v124 dst_sel:DWORD dst_unused:UNUSED_PAD src0_sel:WORD_1 src1_sel:DWORD
	v_add3_u32 v12, v12, v18, s89
	v_and_b32_sdwa v18, v13, v124 dst_sel:DWORD dst_unused:UNUSED_PAD src0_sel:WORD_1 src1_sel:DWORD
	v_add3_u32 v10, v10, v19, s89
	v_and_b32_sdwa v19, v11, v124 dst_sel:DWORD dst_unused:UNUSED_PAD src0_sel:WORD_1 src1_sel:DWORD
	v_add3_u32 v13, v13, v18, s89
	v_add3_u32 v11, v11, v19, s89
	v_and_b32_e32 v13, 0xffff0000, v13
	v_and_b32_e32 v18, 0xffff0000, v11
	v_or_b32_sdwa v11, v13, v12 dst_sel:DWORD dst_unused:UNUSED_PAD src0_sel:DWORD src1_sel:WORD_1
	s_waitcnt lgkmcnt(0)
	v_and_b32_sdwa v12, v16, v124 dst_sel:DWORD dst_unused:UNUSED_PAD src0_sel:WORD_1 src1_sel:DWORD
	v_and_b32_sdwa v13, v14, v124 dst_sel:DWORD dst_unused:UNUSED_PAD src0_sel:WORD_1 src1_sel:DWORD
	v_add3_u32 v14, v14, v13, s89
	v_add3_u32 v12, v16, v12, s89
	v_and_b32_sdwa v13, v17, v124 dst_sel:DWORD dst_unused:UNUSED_PAD src0_sel:WORD_1 src1_sel:DWORD
	v_and_b32_sdwa v16, v15, v124 dst_sel:DWORD dst_unused:UNUSED_PAD src0_sel:WORD_1 src1_sel:DWORD
	v_add3_u32 v13, v17, v13, s89
	v_add3_u32 v15, v15, v16, s89
	v_and_b32_e32 v13, 0xffff0000, v13
	v_and_b32_e32 v15, 0xffff0000, v15
	v_or_b32_sdwa v13, v13, v12 dst_sel:DWORD dst_unused:UNUSED_PAD src0_sel:DWORD src1_sel:WORD_1
	v_or_b32_sdwa v12, v15, v14 dst_sel:DWORD dst_unused:UNUSED_PAD src0_sel:DWORD src1_sel:WORD_1
	v_lshlrev_b32_e32 v14, 14, v9
	v_mov_b32_e32 v15, v75
	v_or_b32_sdwa v10, v18, v10 dst_sel:DWORD dst_unused:UNUSED_PAD src0_sel:DWORD src1_sel:WORD_1
	v_lshl_add_u64 v[14:15], v[2:3], 0, v[14:15]
	global_store_dwordx4 v[14:15], v[10:13], off
	v_add_u32_e32 v9, 0x1040, v123
	v_add_u32_e32 v16, 0x1058, v123
	v_add_u32_e32 v12, 0x1048, v123
	ds_read2_b32 v[10:11], v9 offset1:1
	ds_read2_b32 v[12:13], v12 offset1:1
	v_add_u32_e32 v9, 0x1050, v123
	ds_read2_b32 v[14:15], v9 offset1:1
	ds_read2_b32 v[16:17], v16 offset1:1
	s_waitcnt lgkmcnt(3)
	v_and_b32_sdwa v18, v10, v124 dst_sel:DWORD dst_unused:UNUSED_PAD src0_sel:WORD_1 src1_sel:DWORD
	s_waitcnt lgkmcnt(2)
	v_and_b32_sdwa v9, v12, v124 dst_sel:DWORD dst_unused:UNUSED_PAD src0_sel:WORD_1 src1_sel:DWORD
	v_add3_u32 v10, v10, v18, s89
	v_add3_u32 v9, v12, v9, s89
	v_and_b32_sdwa v12, v13, v124 dst_sel:DWORD dst_unused:UNUSED_PAD src0_sel:WORD_1 src1_sel:DWORD
	v_and_b32_sdwa v18, v11, v124 dst_sel:DWORD dst_unused:UNUSED_PAD src0_sel:WORD_1 src1_sel:DWORD
	v_add3_u32 v12, v13, v12, s89
	v_add3_u32 v11, v11, v18, s89
	v_and_b32_e32 v12, 0xffff0000, v12
	v_and_b32_e32 v13, 0xffff0000, v11
	v_or_b32_sdwa v11, v12, v9 dst_sel:DWORD dst_unused:UNUSED_PAD src0_sel:DWORD src1_sel:WORD_1
	v_or_b32_sdwa v10, v13, v10 dst_sel:DWORD dst_unused:UNUSED_PAD src0_sel:DWORD src1_sel:WORD_1
	s_waitcnt lgkmcnt(1)
	v_and_b32_sdwa v12, v14, v124 dst_sel:DWORD dst_unused:UNUSED_PAD src0_sel:WORD_1 src1_sel:DWORD
	s_waitcnt lgkmcnt(0)
	v_and_b32_sdwa v13, v17, v124 dst_sel:DWORD dst_unused:UNUSED_PAD src0_sel:WORD_1 src1_sel:DWORD
	v_and_b32_sdwa v9, v16, v124 dst_sel:DWORD dst_unused:UNUSED_PAD src0_sel:WORD_1 src1_sel:DWORD
	v_add3_u32 v12, v14, v12, s89
	v_and_b32_sdwa v14, v15, v124 dst_sel:DWORD dst_unused:UNUSED_PAD src0_sel:WORD_1 src1_sel:DWORD
	v_add3_u32 v13, v17, v13, s89
	v_add3_u32 v9, v16, v9, s89
	v_add3_u32 v14, v15, v14, s89
	v_and_b32_e32 v13, 0xffff0000, v13
	v_and_b32_e32 v14, 0xffff0000, v14
	v_or_b32_sdwa v13, v13, v9 dst_sel:DWORD dst_unused:UNUSED_PAD src0_sel:DWORD src1_sel:WORD_1
	v_mov_b32_e32 v9, v75
	v_or_b32_sdwa v12, v14, v12 dst_sel:DWORD dst_unused:UNUSED_PAD src0_sel:DWORD src1_sel:WORD_1
	v_lshl_add_u64 v[8:9], v[2:3], 0, v[8:9]
	global_store_dwordx4 v[8:9], v[10:13], off
	v_add_u32_e32 v8, 0x1860, v123
	v_add_u32_e32 v14, 0x1878, v123
	v_add_u32_e32 v10, 0x1868, v123
	ds_read2_b32 v[8:9], v8 offset1:1
	ds_read2_b32 v[10:11], v10 offset1:1
	v_add_u32_e32 v12, 0x1870, v123
	ds_read2_b32 v[12:13], v12 offset1:1
	ds_read2_b32 v[14:15], v14 offset1:1
	s_waitcnt lgkmcnt(3)
	v_and_b32_sdwa v17, v8, v124 dst_sel:DWORD dst_unused:UNUSED_PAD src0_sel:WORD_1 src1_sel:DWORD
	s_waitcnt lgkmcnt(2)
	v_and_b32_sdwa v16, v10, v124 dst_sel:DWORD dst_unused:UNUSED_PAD src0_sel:WORD_1 src1_sel:DWORD
	v_add3_u32 v10, v10, v16, s89
	v_and_b32_sdwa v16, v11, v124 dst_sel:DWORD dst_unused:UNUSED_PAD src0_sel:WORD_1 src1_sel:DWORD
	v_add3_u32 v8, v8, v17, s89
	v_and_b32_sdwa v17, v9, v124 dst_sel:DWORD dst_unused:UNUSED_PAD src0_sel:WORD_1 src1_sel:DWORD
	v_add3_u32 v11, v11, v16, s89
	v_add3_u32 v9, v9, v17, s89
	v_and_b32_e32 v11, 0xffff0000, v11
	v_and_b32_e32 v16, 0xffff0000, v9
	v_or_b32_sdwa v9, v11, v10 dst_sel:DWORD dst_unused:UNUSED_PAD src0_sel:DWORD src1_sel:WORD_1
	s_waitcnt lgkmcnt(0)
	v_and_b32_sdwa v10, v14, v124 dst_sel:DWORD dst_unused:UNUSED_PAD src0_sel:WORD_1 src1_sel:DWORD
	v_and_b32_sdwa v11, v12, v124 dst_sel:DWORD dst_unused:UNUSED_PAD src0_sel:WORD_1 src1_sel:DWORD
	v_add3_u32 v12, v12, v11, s89
	v_add3_u32 v10, v14, v10, s89
	v_and_b32_sdwa v11, v15, v124 dst_sel:DWORD dst_unused:UNUSED_PAD src0_sel:WORD_1 src1_sel:DWORD
	v_and_b32_sdwa v14, v13, v124 dst_sel:DWORD dst_unused:UNUSED_PAD src0_sel:WORD_1 src1_sel:DWORD
	v_add3_u32 v11, v15, v11, s89
	v_add3_u32 v13, v13, v14, s89
	v_and_b32_e32 v11, 0xffff0000, v11
	v_and_b32_e32 v13, 0xffff0000, v13
	v_or_b32_sdwa v11, v11, v10 dst_sel:DWORD dst_unused:UNUSED_PAD src0_sel:DWORD src1_sel:WORD_1
	v_or_b32_sdwa v10, v13, v12 dst_sel:DWORD dst_unused:UNUSED_PAD src0_sel:DWORD src1_sel:WORD_1
	v_lshlrev_b32_e32 v12, 14, v7
	v_mov_b32_e32 v13, v75
	v_or_b32_sdwa v8, v16, v8 dst_sel:DWORD dst_unused:UNUSED_PAD src0_sel:DWORD src1_sel:WORD_1
	v_lshl_add_u64 v[12:13], v[2:3], 0, v[12:13]
	global_store_dwordx4 v[12:13], v[8:11], off
	v_add_u32_e32 v7, 0x2080, v123
	v_add_u32_e32 v14, 0x2098, v123
	v_add_u32_e32 v10, 0x2088, v123
	ds_read2_b32 v[8:9], v7 offset1:1
	ds_read2_b32 v[10:11], v10 offset1:1
	v_add_u32_e32 v7, 0x2090, v123
	ds_read2_b32 v[12:13], v7 offset1:1
	ds_read2_b32 v[14:15], v14 offset1:1
	s_waitcnt lgkmcnt(3)
	v_and_b32_sdwa v16, v8, v124 dst_sel:DWORD dst_unused:UNUSED_PAD src0_sel:WORD_1 src1_sel:DWORD
	s_waitcnt lgkmcnt(2)
	v_and_b32_sdwa v7, v10, v124 dst_sel:DWORD dst_unused:UNUSED_PAD src0_sel:WORD_1 src1_sel:DWORD
	v_add3_u32 v8, v8, v16, s89
	v_add3_u32 v7, v10, v7, s89
	v_and_b32_sdwa v10, v11, v124 dst_sel:DWORD dst_unused:UNUSED_PAD src0_sel:WORD_1 src1_sel:DWORD
	v_and_b32_sdwa v16, v9, v124 dst_sel:DWORD dst_unused:UNUSED_PAD src0_sel:WORD_1 src1_sel:DWORD
	v_add3_u32 v10, v11, v10, s89
	v_add3_u32 v9, v9, v16, s89
	v_and_b32_e32 v10, 0xffff0000, v10
	v_and_b32_e32 v11, 0xffff0000, v9
	v_or_b32_sdwa v9, v10, v7 dst_sel:DWORD dst_unused:UNUSED_PAD src0_sel:DWORD src1_sel:WORD_1
	v_or_b32_sdwa v8, v11, v8 dst_sel:DWORD dst_unused:UNUSED_PAD src0_sel:DWORD src1_sel:WORD_1
	s_waitcnt lgkmcnt(1)
	v_and_b32_sdwa v10, v12, v124 dst_sel:DWORD dst_unused:UNUSED_PAD src0_sel:WORD_1 src1_sel:DWORD
	s_waitcnt lgkmcnt(0)
	v_and_b32_sdwa v11, v15, v124 dst_sel:DWORD dst_unused:UNUSED_PAD src0_sel:WORD_1 src1_sel:DWORD
	v_and_b32_sdwa v7, v14, v124 dst_sel:DWORD dst_unused:UNUSED_PAD src0_sel:WORD_1 src1_sel:DWORD
	v_add3_u32 v10, v12, v10, s89
	v_and_b32_sdwa v12, v13, v124 dst_sel:DWORD dst_unused:UNUSED_PAD src0_sel:WORD_1 src1_sel:DWORD
	v_add3_u32 v11, v15, v11, s89
	v_add3_u32 v7, v14, v7, s89
	v_add3_u32 v12, v13, v12, s89
	v_and_b32_e32 v11, 0xffff0000, v11
	v_and_b32_e32 v12, 0xffff0000, v12
	v_or_b32_sdwa v11, v11, v7 dst_sel:DWORD dst_unused:UNUSED_PAD src0_sel:DWORD src1_sel:WORD_1
	v_mov_b32_e32 v7, v75
	v_or_b32_sdwa v10, v12, v10 dst_sel:DWORD dst_unused:UNUSED_PAD src0_sel:DWORD src1_sel:WORD_1
	v_lshl_add_u64 v[6:7], v[2:3], 0, v[6:7]
	global_store_dwordx4 v[6:7], v[8:11], off
	v_add_u32_e32 v6, 0x28a0, v123
	v_add_u32_e32 v12, 0x28b8, v123
	v_add_u32_e32 v8, 0x28a8, v123
	ds_read2_b32 v[6:7], v6 offset1:1
	ds_read2_b32 v[8:9], v8 offset1:1
	v_add_u32_e32 v10, 0x28b0, v123
	ds_read2_b32 v[10:11], v10 offset1:1
	ds_read2_b32 v[12:13], v12 offset1:1
	s_waitcnt lgkmcnt(3)
	v_and_b32_sdwa v15, v6, v124 dst_sel:DWORD dst_unused:UNUSED_PAD src0_sel:WORD_1 src1_sel:DWORD
	s_waitcnt lgkmcnt(2)
	v_and_b32_sdwa v14, v8, v124 dst_sel:DWORD dst_unused:UNUSED_PAD src0_sel:WORD_1 src1_sel:DWORD
	v_add3_u32 v8, v8, v14, s89
	v_and_b32_sdwa v14, v9, v124 dst_sel:DWORD dst_unused:UNUSED_PAD src0_sel:WORD_1 src1_sel:DWORD
	v_add3_u32 v6, v6, v15, s89
	v_and_b32_sdwa v15, v7, v124 dst_sel:DWORD dst_unused:UNUSED_PAD src0_sel:WORD_1 src1_sel:DWORD
	v_add3_u32 v9, v9, v14, s89
	v_add3_u32 v7, v7, v15, s89
	v_and_b32_e32 v9, 0xffff0000, v9
	v_and_b32_e32 v14, 0xffff0000, v7
	v_or_b32_sdwa v7, v9, v8 dst_sel:DWORD dst_unused:UNUSED_PAD src0_sel:DWORD src1_sel:WORD_1
	s_waitcnt lgkmcnt(0)
	v_and_b32_sdwa v8, v12, v124 dst_sel:DWORD dst_unused:UNUSED_PAD src0_sel:WORD_1 src1_sel:DWORD
	v_and_b32_sdwa v9, v10, v124 dst_sel:DWORD dst_unused:UNUSED_PAD src0_sel:WORD_1 src1_sel:DWORD
	v_add3_u32 v10, v10, v9, s89
	v_add3_u32 v8, v12, v8, s89
	v_and_b32_sdwa v9, v13, v124 dst_sel:DWORD dst_unused:UNUSED_PAD src0_sel:WORD_1 src1_sel:DWORD
	v_and_b32_sdwa v12, v11, v124 dst_sel:DWORD dst_unused:UNUSED_PAD src0_sel:WORD_1 src1_sel:DWORD
	v_add3_u32 v9, v13, v9, s89
	v_add3_u32 v11, v11, v12, s89
	v_and_b32_e32 v9, 0xffff0000, v9
	v_and_b32_e32 v11, 0xffff0000, v11
	v_or_b32_sdwa v9, v9, v8 dst_sel:DWORD dst_unused:UNUSED_PAD src0_sel:DWORD src1_sel:WORD_1
	v_or_b32_sdwa v8, v11, v10 dst_sel:DWORD dst_unused:UNUSED_PAD src0_sel:DWORD src1_sel:WORD_1
	v_lshlrev_b32_e32 v10, 14, v5
	v_mov_b32_e32 v11, v75
	v_or_b32_sdwa v6, v14, v6 dst_sel:DWORD dst_unused:UNUSED_PAD src0_sel:DWORD src1_sel:WORD_1
	v_lshl_add_u64 v[10:11], v[2:3], 0, v[10:11]
	global_store_dwordx4 v[10:11], v[6:9], off
	v_add_u32_e32 v5, 0x30c0, v123
	v_add_u32_e32 v12, 0x30d8, v123
	v_add_u32_e32 v8, 0x30c8, v123
	ds_read2_b32 v[6:7], v5 offset1:1
	ds_read2_b32 v[8:9], v8 offset1:1
	v_add_u32_e32 v5, 0x30d0, v123
	ds_read2_b32 v[10:11], v5 offset1:1
	ds_read2_b32 v[12:13], v12 offset1:1
	s_waitcnt lgkmcnt(3)
	v_and_b32_sdwa v14, v6, v124 dst_sel:DWORD dst_unused:UNUSED_PAD src0_sel:WORD_1 src1_sel:DWORD
	s_waitcnt lgkmcnt(2)
	v_and_b32_sdwa v5, v8, v124 dst_sel:DWORD dst_unused:UNUSED_PAD src0_sel:WORD_1 src1_sel:DWORD
	v_add3_u32 v6, v6, v14, s89
	v_add3_u32 v5, v8, v5, s89
	v_and_b32_sdwa v8, v9, v124 dst_sel:DWORD dst_unused:UNUSED_PAD src0_sel:WORD_1 src1_sel:DWORD
	v_and_b32_sdwa v14, v7, v124 dst_sel:DWORD dst_unused:UNUSED_PAD src0_sel:WORD_1 src1_sel:DWORD
	v_add3_u32 v8, v9, v8, s89
	v_add3_u32 v7, v7, v14, s89
	v_and_b32_e32 v8, 0xffff0000, v8
	v_and_b32_e32 v9, 0xffff0000, v7
	v_or_b32_sdwa v7, v8, v5 dst_sel:DWORD dst_unused:UNUSED_PAD src0_sel:DWORD src1_sel:WORD_1
	v_or_b32_sdwa v6, v9, v6 dst_sel:DWORD dst_unused:UNUSED_PAD src0_sel:DWORD src1_sel:WORD_1
	s_waitcnt lgkmcnt(1)
	v_and_b32_sdwa v8, v10, v124 dst_sel:DWORD dst_unused:UNUSED_PAD src0_sel:WORD_1 src1_sel:DWORD
	s_waitcnt lgkmcnt(0)
	v_and_b32_sdwa v9, v13, v124 dst_sel:DWORD dst_unused:UNUSED_PAD src0_sel:WORD_1 src1_sel:DWORD
	v_and_b32_sdwa v5, v12, v124 dst_sel:DWORD dst_unused:UNUSED_PAD src0_sel:WORD_1 src1_sel:DWORD
	v_add3_u32 v8, v10, v8, s89
	v_and_b32_sdwa v10, v11, v124 dst_sel:DWORD dst_unused:UNUSED_PAD src0_sel:WORD_1 src1_sel:DWORD
	v_add3_u32 v9, v13, v9, s89
	v_add3_u32 v5, v12, v5, s89
	v_add3_u32 v10, v11, v10, s89
	v_and_b32_e32 v9, 0xffff0000, v9
	v_and_b32_e32 v10, 0xffff0000, v10
	v_or_b32_sdwa v9, v9, v5 dst_sel:DWORD dst_unused:UNUSED_PAD src0_sel:DWORD src1_sel:WORD_1
	v_mov_b32_e32 v5, v75
	v_or_b32_sdwa v8, v10, v8 dst_sel:DWORD dst_unused:UNUSED_PAD src0_sel:DWORD src1_sel:WORD_1
	v_lshl_add_u64 v[4:5], v[2:3], 0, v[4:5]
	global_store_dwordx4 v[4:5], v[6:9], off
	v_add_u32_e32 v4, 0x38e0, v123
	v_add_u32_e32 v10, 0x38f8, v123
	v_add_u32_e32 v6, 0x38e8, v123
	ds_read2_b32 v[4:5], v4 offset1:1
	ds_read2_b32 v[6:7], v6 offset1:1
	v_add_u32_e32 v8, 0x38f0, v123
	ds_read2_b32 v[8:9], v8 offset1:1
	ds_read2_b32 v[10:11], v10 offset1:1
	s_waitcnt lgkmcnt(3)
	v_and_b32_sdwa v13, v4, v124 dst_sel:DWORD dst_unused:UNUSED_PAD src0_sel:WORD_1 src1_sel:DWORD
	s_waitcnt lgkmcnt(2)
	v_and_b32_sdwa v12, v6, v124 dst_sel:DWORD dst_unused:UNUSED_PAD src0_sel:WORD_1 src1_sel:DWORD
	v_add3_u32 v6, v6, v12, s89
	v_and_b32_sdwa v12, v7, v124 dst_sel:DWORD dst_unused:UNUSED_PAD src0_sel:WORD_1 src1_sel:DWORD
	v_add3_u32 v4, v4, v13, s89
	v_and_b32_sdwa v13, v5, v124 dst_sel:DWORD dst_unused:UNUSED_PAD src0_sel:WORD_1 src1_sel:DWORD
	v_add3_u32 v7, v7, v12, s89
	v_add3_u32 v5, v5, v13, s89
	v_and_b32_e32 v7, 0xffff0000, v7
	v_and_b32_e32 v12, 0xffff0000, v5
	v_or_b32_sdwa v5, v7, v6 dst_sel:DWORD dst_unused:UNUSED_PAD src0_sel:DWORD src1_sel:WORD_1
	s_waitcnt lgkmcnt(0)
	v_and_b32_sdwa v6, v10, v124 dst_sel:DWORD dst_unused:UNUSED_PAD src0_sel:WORD_1 src1_sel:DWORD
	v_and_b32_sdwa v7, v8, v124 dst_sel:DWORD dst_unused:UNUSED_PAD src0_sel:WORD_1 src1_sel:DWORD
	v_add3_u32 v8, v8, v7, s89
	v_add3_u32 v6, v10, v6, s89
	v_and_b32_sdwa v7, v11, v124 dst_sel:DWORD dst_unused:UNUSED_PAD src0_sel:WORD_1 src1_sel:DWORD
	v_and_b32_sdwa v10, v9, v124 dst_sel:DWORD dst_unused:UNUSED_PAD src0_sel:WORD_1 src1_sel:DWORD
	v_add3_u32 v7, v11, v7, s89
	v_add3_u32 v9, v9, v10, s89
	v_and_b32_e32 v7, 0xffff0000, v7
	v_and_b32_e32 v9, 0xffff0000, v9
	v_or_b32_sdwa v7, v7, v6 dst_sel:DWORD dst_unused:UNUSED_PAD src0_sel:DWORD src1_sel:WORD_1
	v_or_b32_sdwa v6, v9, v8 dst_sel:DWORD dst_unused:UNUSED_PAD src0_sel:DWORD src1_sel:WORD_1
	v_or_b32_e32 v8, s18, v122
	v_lshlrev_b32_e32 v8, 14, v8
	v_mov_b32_e32 v9, v75
	v_or_b32_sdwa v4, v12, v4 dst_sel:DWORD dst_unused:UNUSED_PAD src0_sel:DWORD src1_sel:WORD_1
	v_lshl_add_u64 v[2:3], v[2:3], 0, v[8:9]
	global_store_dwordx4 v[2:3], v[4:7], off
	s_waitcnt lgkmcnt(0)

.LBB0_22:
	s_andn2_b64 vcc, exec, s[2:3]
	s_cbranch_vccnz .LBB0_24
	s_add_i32 s14, s92, 0xd000
	s_lshr_b32 s14, s14, 1
	s_and_b32 s19, s14, 0x7fc0
	s_and_b32 s18, s21, 0x1fc0
	v_or_b32_e32 v52, s19, v72
	s_lshl_b32 s14, s18, 2
	v_lshl_add_u64 v[2:3], v[82:83], 0, s[14:15]
	v_lshlrev_b32_e32 v4, 15, v52
	v_mov_b32_e32 v5, v75
	v_lshl_add_u64 v[58:59], v[2:3], 0, v[4:5]
	v_add_co_u32_e32 v6, vcc, 0x20000, v58
	s_mov_b64 s[2:3], s[28:29]
	s_nop 0
	v_addc_co_u32_e32 v7, vcc, 0, v59, vcc
	v_add_co_u32_e32 v10, vcc, 0x40000, v58
	v_lshlrev_b32_e32 v52, 2, v52
	s_nop 0
	v_addc_co_u32_e32 v11, vcc, 0, v59, vcc
	v_add_co_u32_e32 v14, vcc, 0x60000, v58
	global_load_dwordx4 v[2:5], v[58:59], off nt
	s_nop 0
	global_load_dwordx4 v[6:9], v[6:7], off nt
	v_addc_co_u32_e32 v15, vcc, 0, v59, vcc
	v_add_co_u32_e32 v18, vcc, 0x80000, v58
	global_load_dwordx4 v[10:13], v[10:11], off nt
	s_nop 0
	global_load_dwordx4 v[14:17], v[14:15], off nt
	v_addc_co_u32_e32 v19, vcc, 0, v59, vcc
	v_add_co_u32_e32 v22, vcc, 0xa0000, v58
	v_or_b32_e32 v60, s19, v101
	s_nop 0
	v_addc_co_u32_e32 v23, vcc, 0, v59, vcc
	v_add_co_u32_e32 v26, vcc, 0xc0000, v58
	global_load_dwordx4 v[18:21], v[18:19], off nt
	s_nop 0
	global_load_dwordx4 v[22:25], v[22:23], off nt
	v_addc_co_u32_e32 v27, vcc, 0, v59, vcc
	v_add_co_u32_e32 v30, vcc, 0xe0000, v58
	v_or_b32_e32 v61, s19, v103
	s_nop 0
	v_addc_co_u32_e32 v31, vcc, 0, v59, vcc
	v_add_co_u32_e32 v34, vcc, 0x100000, v58
	global_load_dwordx4 v[26:29], v[26:27], off nt
	s_nop 0
	global_load_dwordx4 v[30:33], v[30:31], off nt
	v_addc_co_u32_e32 v35, vcc, 0, v59, vcc
	v_add_co_u32_e32 v38, vcc, 0x120000, v58
	v_lshlrev_b32_e32 v60, 2, v60
	s_nop 0
	v_addc_co_u32_e32 v39, vcc, 0, v59, vcc
	v_add_co_u32_e32 v42, vcc, 0x140000, v58
	global_load_dwordx4 v[34:37], v[34:35], off nt
	s_nop 0
	global_load_dwordx4 v[38:41], v[38:39], off nt
	v_addc_co_u32_e32 v43, vcc, 0, v59, vcc
	v_add_co_u32_e32 v46, vcc, 0x160000, v58
	v_lshlrev_b32_e32 v61, 2, v61
	s_nop 0
	v_addc_co_u32_e32 v47, vcc, 0, v59, vcc
	v_add_co_u32_e32 v50, vcc, 0x180000, v58
	global_load_dwordx4 v[42:45], v[42:43], off nt
	s_nop 0
	global_load_dwordx4 v[46:49], v[46:47], off nt
	v_addc_co_u32_e32 v51, vcc, 0, v59, vcc
	v_add_co_u32_e32 v54, vcc, 0x1a0000, v58
	global_load_dword v66, v52, s[10:11]
	v_or_b32_e32 v52, s19, v100
	v_addc_co_u32_e32 v55, vcc, 0, v59, vcc
	v_lshlrev_b32_e32 v52, 2, v52
	global_load_dword v68, v52, s[10:11]
	s_nop 0
	global_load_dwordx4 v[50:53], v[50:51], off nt
	s_nop 0
	global_load_dwordx4 v[54:57], v[54:55], off nt
	v_or_b32_e32 v62, s19, v106
	global_load_dword v128, v60, s[10:11]
	global_load_dword v132, v61, s[10:11]
	v_or_b32_e32 v60, s19, v102
	v_or_b32_e32 v61, s19, v104
	v_lshlrev_b32_e32 v60, 2, v60
	v_lshlrev_b32_e32 v61, 2, v61
	global_load_dword v130, v60, s[10:11]
	global_load_dword v134, v61, s[10:11]
	v_or_b32_e32 v61, s19, v105
	v_lshlrev_b32_e32 v61, 2, v61
	v_lshlrev_b32_e32 v62, 2, v62
	v_add_co_u32_e32 v60, vcc, 0x1c0000, v58
	global_load_dword v136, v61, s[10:11]
	global_load_dword v138, v62, s[10:11]
	v_or_b32_e32 v62, s19, v107
	v_addc_co_u32_e32 v61, vcc, 0, v59, vcc
	v_lshlrev_b32_e32 v62, 2, v62
	v_or_b32_e32 v63, s19, v108
	v_lshlrev_b32_e32 v63, 2, v63
	global_load_dword v140, v62, s[10:11]
	global_load_dword v142, v63, s[10:11]
	v_add_co_u32_e32 v62, vcc, 0x1e0000, v58
	v_or_b32_e32 v58, s19, v109
	v_lshlrev_b32_e32 v58, 2, v58
	v_or_b32_e32 v63, s19, v110
	v_lshlrev_b32_e32 v63, 2, v63
	global_load_dword v144, v58, s[10:11]
	global_load_dword v146, v63, s[10:11]
	v_or_b32_e32 v58, s19, v111
	v_lshlrev_b32_e32 v58, 2, v58
	global_load_dword v148, v58, s[10:11]
	v_or_b32_e32 v58, s19, v112
	v_or_b32_e32 v67, s19, v113
	v_addc_co_u32_e32 v63, vcc, 0, v59, vcc
	v_lshlrev_b32_e32 v58, 2, v58
	v_lshlrev_b32_e32 v67, 2, v67
	global_load_dword v150, v58, s[10:11]
	s_nop 0
	global_load_dwordx4 v[58:61], v[60:61], off nt
	s_nop 0
	global_load_dwordx4 v[62:65], v[62:63], off nt
	s_lshl_b32 s14, s19, 1
	global_load_dword v152, v67, s[10:11]
	v_or_b32_e32 v67, s19, v114
	v_lshlrev_b32_e32 v67, 2, v67
	global_load_dword v154, v67, s[10:11]
	s_add_u32 s2, s2, s14
	s_addc_u32 s3, s3, 0
	s_waitcnt vmcnt(19)
	v_pk_mul_f32 v[4:5], v[4:5], v[66:67] op_sel_hi:[1,0]
	v_pk_mul_f32 v[2:3], v[2:3], v[66:67] op_sel_hi:[1,0]
	s_waitcnt vmcnt(18)
	v_pk_mul_f32 v[8:9], v[8:9], v[68:69] op_sel_hi:[1,0]
	v_pk_mul_f32 v[6:7], v[6:7], v[68:69] op_sel_hi:[1,0]
	ds_write2_b32 v99, v2, v6 offset1:4
	ds_write2_b32 v99, v3, v7 offset0:65 offset1:69
	ds_write2_b32 v99, v4, v8 offset0:130 offset1:134
	ds_write2_b32 v99, v5, v9 offset0:195 offset1:199
	s_waitcnt vmcnt(15)
	v_pk_mul_f32 v[4:5], v[10:11], v[128:129] op_sel_hi:[1,0]
	v_pk_mul_f32 v[2:3], v[12:13], v[128:129] op_sel_hi:[1,0]
	s_waitcnt vmcnt(13)
	v_pk_mul_f32 v[8:9], v[14:15], v[130:131] op_sel_hi:[1,0]
	v_pk_mul_f32 v[6:7], v[16:17], v[130:131] op_sel_hi:[1,0]
	ds_write2_b32 v99, v4, v8 offset0:8 offset1:12
	ds_write2_b32 v99, v5, v9 offset0:73 offset1:77
	ds_write2_b32 v99, v2, v6 offset0:138 offset1:142
	ds_write2_b32 v99, v3, v7 offset0:203 offset1:207
	v_pk_mul_f32 v[4:5], v[18:19], v[132:133] op_sel_hi:[1,0]
	s_waitcnt vmcnt(12)
	v_pk_mul_f32 v[8:9], v[22:23], v[134:135] op_sel_hi:[1,0]
	v_pk_mul_f32 v[2:3], v[20:21], v[132:133] op_sel_hi:[1,0]
	v_pk_mul_f32 v[6:7], v[24:25], v[134:135] op_sel_hi:[1,0]
	ds_write2_b32 v99, v4, v8 offset0:16 offset1:20
	ds_write2_b32 v99, v5, v9 offset0:81 offset1:85
	ds_write2_b32 v99, v2, v6 offset0:146 offset1:150
	ds_write2_b32 v99, v3, v7 offset0:211 offset1:215
	s_waitcnt vmcnt(11)
	v_pk_mul_f32 v[4:5], v[26:27], v[136:137] op_sel_hi:[1,0]
	s_waitcnt vmcnt(10)
	v_pk_mul_f32 v[8:9], v[30:31], v[138:139] op_sel_hi:[1,0]
	v_pk_mul_f32 v[2:3], v[28:29], v[136:137] op_sel_hi:[1,0]
	v_pk_mul_f32 v[6:7], v[32:33], v[138:139] op_sel_hi:[1,0]
	ds_write2_b32 v99, v4, v8 offset0:24 offset1:28
	ds_write2_b32 v99, v5, v9 offset0:89 offset1:93
	ds_write2_b32 v99, v2, v6 offset0:154 offset1:158
	ds_write2_b32 v99, v3, v7 offset0:219 offset1:223
	s_waitcnt vmcnt(9)
	v_pk_mul_f32 v[4:5], v[34:35], v[140:141] op_sel_hi:[1,0]
	s_waitcnt vmcnt(8)
	v_pk_mul_f32 v[8:9], v[38:39], v[142:143] op_sel_hi:[1,0]
	v_pk_mul_f32 v[2:3], v[36:37], v[140:141] op_sel_hi:[1,0]
	v_pk_mul_f32 v[6:7], v[40:41], v[142:143] op_sel_hi:[1,0]
	ds_write2_b32 v99, v4, v8 offset0:32 offset1:36
	ds_write2_b32 v99, v5, v9 offset0:97 offset1:101
	ds_write2_b32 v99, v2, v6 offset0:162 offset1:166
	ds_write2_b32 v99, v3, v7 offset0:227 offset1:231
	s_waitcnt vmcnt(7)
	v_pk_mul_f32 v[4:5], v[42:43], v[144:145] op_sel_hi:[1,0]
	s_waitcnt vmcnt(6)
	v_pk_mul_f32 v[8:9], v[46:47], v[146:147] op_sel_hi:[1,0]
	v_pk_mul_f32 v[2:3], v[44:45], v[144:145] op_sel_hi:[1,0]
	v_pk_mul_f32 v[6:7], v[48:49], v[146:147] op_sel_hi:[1,0]
	ds_write2_b32 v99, v4, v8 offset0:40 offset1:44
	ds_write2_b32 v99, v5, v9 offset0:105 offset1:109
	ds_write2_b32 v99, v2, v6 offset0:170 offset1:174
	ds_write2_b32 v99, v3, v7 offset0:235 offset1:239
	s_waitcnt vmcnt(5)
	v_pk_mul_f32 v[4:5], v[50:51], v[148:149] op_sel_hi:[1,0]
	v_pk_mul_f32 v[2:3], v[52:53], v[148:149] op_sel_hi:[1,0]
	s_waitcnt vmcnt(4)
	v_pk_mul_f32 v[8:9], v[54:55], v[150:151] op_sel_hi:[1,0]
	v_pk_mul_f32 v[6:7], v[56:57], v[150:151] op_sel_hi:[1,0]
	ds_write2_b32 v99, v4, v8 offset0:48 offset1:52
	ds_write2_b32 v99, v5, v9 offset0:113 offset1:117
	ds_write2_b32 v99, v2, v6 offset0:178 offset1:182
	ds_write2_b32 v99, v3, v7 offset0:243 offset1:247
	s_waitcnt vmcnt(1)
	v_pk_mul_f32 v[4:5], v[58:59], v[152:153] op_sel_hi:[1,0]
	v_pk_mul_f32 v[2:3], v[60:61], v[152:153] op_sel_hi:[1,0]
	s_waitcnt vmcnt(0)
	v_pk_mul_f32 v[8:9], v[62:63], v[154:155] op_sel_hi:[1,0]
	v_pk_mul_f32 v[6:7], v[64:65], v[154:155] op_sel_hi:[1,0]
	ds_write2_b32 v99, v4, v8 offset0:56 offset1:60
	ds_write2_b32 v99, v5, v9 offset0:121 offset1:125
	ds_write2_b32 v99, v2, v6 offset0:186 offset1:190
	ds_write2_b32 v99, v3, v7 offset0:251 offset1:255
	s_waitcnt lgkmcnt(0)
	ds_read2_b32 v[4:5], v123 offset1:1
	ds_read2_b32 v[6:7], v123 offset0:2 offset1:3
	ds_read2_b32 v[8:9], v123 offset0:4 offset1:5
	ds_read2_b32 v[10:11], v123 offset0:6 offset1:7
	v_lshl_add_u64 v[2:3], s[2:3], 0, v[74:75]
	v_lshl_add_u64 v[2:3], v[2:3], 0, s[46:47]
	s_waitcnt lgkmcnt(3)
	v_and_b32_sdwa v13, v4, v124 dst_sel:DWORD dst_unused:UNUSED_PAD src0_sel:WORD_1 src1_sel:DWORD
	s_waitcnt lgkmcnt(2)
	v_and_b32_sdwa v12, v6, v124 dst_sel:DWORD dst_unused:UNUSED_PAD src0_sel:WORD_1 src1_sel:DWORD
	v_add3_u32 v6, v6, v12, s89
	v_and_b32_sdwa v12, v7, v124 dst_sel:DWORD dst_unused:UNUSED_PAD src0_sel:WORD_1 src1_sel:DWORD
	v_add3_u32 v4, v4, v13, s89
	v_and_b32_sdwa v13, v5, v124 dst_sel:DWORD dst_unused:UNUSED_PAD src0_sel:WORD_1 src1_sel:DWORD
	v_add3_u32 v7, v7, v12, s89
	v_add3_u32 v5, v5, v13, s89
	v_and_b32_e32 v7, 0xffff0000, v7
	v_and_b32_e32 v12, 0xffff0000, v5
	v_or_b32_sdwa v5, v7, v6 dst_sel:DWORD dst_unused:UNUSED_PAD src0_sel:DWORD src1_sel:WORD_1
	s_waitcnt lgkmcnt(0)
	v_and_b32_sdwa v6, v10, v124 dst_sel:DWORD dst_unused:UNUSED_PAD src0_sel:WORD_1 src1_sel:DWORD
	v_and_b32_sdwa v7, v8, v124 dst_sel:DWORD dst_unused:UNUSED_PAD src0_sel:WORD_1 src1_sel:DWORD
	v_add3_u32 v8, v8, v7, s89
	v_add3_u32 v6, v10, v6, s89
	v_and_b32_sdwa v7, v11, v124 dst_sel:DWORD dst_unused:UNUSED_PAD src0_sel:WORD_1 src1_sel:DWORD
	v_and_b32_sdwa v10, v9, v124 dst_sel:DWORD dst_unused:UNUSED_PAD src0_sel:WORD_1 src1_sel:DWORD
	v_add3_u32 v7, v11, v7, s89
	v_add3_u32 v9, v9, v10, s89
	v_and_b32_e32 v7, 0xffff0000, v7
	v_and_b32_e32 v9, 0xffff0000, v9
	v_or_b32_sdwa v7, v7, v6 dst_sel:DWORD dst_unused:UNUSED_PAD src0_sel:DWORD src1_sel:WORD_1
	v_or_b32_sdwa v6, v9, v8 dst_sel:DWORD dst_unused:UNUSED_PAD src0_sel:DWORD src1_sel:WORD_1
	v_or_b32_e32 v8, s18, v115
	v_lshlrev_b32_e32 v8, 12, v8
	v_mov_b32_e32 v9, v75
	v_or_b32_sdwa v4, v12, v4 dst_sel:DWORD dst_unused:UNUSED_PAD src0_sel:DWORD src1_sel:WORD_1
	v_lshl_add_u64 v[8:9], v[2:3], 0, v[8:9]
	global_store_dwordx4 v[8:9], v[4:7], off
	ds_read2_b32 v[4:5], v125 offset1:1
	ds_read2_b32 v[6:7], v126 offset1:1
	v_add_u32_e32 v8, 0x830, v123
	v_add_u32_e32 v10, 0x838, v123
	ds_read2_b32 v[8:9], v8 offset1:1
	ds_read2_b32 v[10:11], v10 offset1:1
	s_waitcnt lgkmcnt(3)
	v_and_b32_sdwa v13, v4, v124 dst_sel:DWORD dst_unused:UNUSED_PAD src0_sel:WORD_1 src1_sel:DWORD
	s_waitcnt lgkmcnt(2)
	v_and_b32_sdwa v12, v6, v124 dst_sel:DWORD dst_unused:UNUSED_PAD src0_sel:WORD_1 src1_sel:DWORD
	v_add3_u32 v6, v6, v12, s89
	v_and_b32_sdwa v12, v7, v124 dst_sel:DWORD dst_unused:UNUSED_PAD src0_sel:WORD_1 src1_sel:DWORD
	v_add3_u32 v4, v4, v13, s89
	v_and_b32_sdwa v13, v5, v124 dst_sel:DWORD dst_unused:UNUSED_PAD src0_sel:WORD_1 src1_sel:DWORD
	v_add3_u32 v7, v7, v12, s89
	v_add3_u32 v5, v5, v13, s89
	v_and_b32_e32 v7, 0xffff0000, v7
	v_and_b32_e32 v12, 0xffff0000, v5
	v_or_b32_sdwa v5, v7, v6 dst_sel:DWORD dst_unused:UNUSED_PAD src0_sel:DWORD src1_sel:WORD_1
	s_waitcnt lgkmcnt(0)
	v_and_b32_sdwa v6, v10, v124 dst_sel:DWORD dst_unused:UNUSED_PAD src0_sel:WORD_1 src1_sel:DWORD
	v_and_b32_sdwa v7, v8, v124 dst_sel:DWORD dst_unused:UNUSED_PAD src0_sel:WORD_1 src1_sel:DWORD
	v_add3_u32 v8, v8, v7, s89
	v_add3_u32 v6, v10, v6, s89
	v_and_b32_sdwa v7, v11, v124 dst_sel:DWORD dst_unused:UNUSED_PAD src0_sel:WORD_1 src1_sel:DWORD
	v_and_b32_sdwa v10, v9, v124 dst_sel:DWORD dst_unused:UNUSED_PAD src0_sel:WORD_1 src1_sel:DWORD
	v_add3_u32 v7, v11, v7, s89
	v_add3_u32 v9, v9, v10, s89
	v_and_b32_e32 v7, 0xffff0000, v7
	v_and_b32_e32 v9, 0xffff0000, v9
	v_or_b32_sdwa v7, v7, v6 dst_sel:DWORD dst_unused:UNUSED_PAD src0_sel:DWORD src1_sel:WORD_1
	v_or_b32_sdwa v6, v9, v8 dst_sel:DWORD dst_unused:UNUSED_PAD src0_sel:DWORD src1_sel:WORD_1
	v_or_b32_e32 v8, s18, v116
	v_lshlrev_b32_e32 v8, 12, v8
	v_mov_b32_e32 v9, v75
	v_or_b32_sdwa v4, v12, v4 dst_sel:DWORD dst_unused:UNUSED_PAD src0_sel:DWORD src1_sel:WORD_1
	v_lshl_add_u64 v[8:9], v[2:3], 0, v[8:9]
	global_store_dwordx4 v[8:9], v[4:7], off
	v_add_u32_e32 v8, 0x1050, v123
	v_add_u32_e32 v10, 0x1058, v123
	v_add_u32_e32 v4, 0x1040, v123
	v_add_u32_e32 v6, 0x1048, v123
	ds_read2_b32 v[4:5], v4 offset1:1
	ds_read2_b32 v[6:7], v6 offset1:1
	ds_read2_b32 v[8:9], v8 offset1:1
	ds_read2_b32 v[10:11], v10 offset1:1
	s_waitcnt lgkmcnt(3)
	v_and_b32_sdwa v13, v4, v124 dst_sel:DWORD dst_unused:UNUSED_PAD src0_sel:WORD_1 src1_sel:DWORD
	s_waitcnt lgkmcnt(2)
	v_and_b32_sdwa v12, v6, v124 dst_sel:DWORD dst_unused:UNUSED_PAD src0_sel:WORD_1 src1_sel:DWORD
	v_add3_u32 v6, v6, v12, s89
	v_and_b32_sdwa v12, v7, v124 dst_sel:DWORD dst_unused:UNUSED_PAD src0_sel:WORD_1 src1_sel:DWORD
	v_add3_u32 v4, v4, v13, s89
	v_and_b32_sdwa v13, v5, v124 dst_sel:DWORD dst_unused:UNUSED_PAD src0_sel:WORD_1 src1_sel:DWORD
	v_add3_u32 v7, v7, v12, s89
	v_add3_u32 v5, v5, v13, s89
	v_and_b32_e32 v7, 0xffff0000, v7
	v_and_b32_e32 v12, 0xffff0000, v5
	v_or_b32_sdwa v5, v7, v6 dst_sel:DWORD dst_unused:UNUSED_PAD src0_sel:DWORD src1_sel:WORD_1
	s_waitcnt lgkmcnt(0)
	v_and_b32_sdwa v6, v10, v124 dst_sel:DWORD dst_unused:UNUSED_PAD src0_sel:WORD_1 src1_sel:DWORD
	v_and_b32_sdwa v7, v8, v124 dst_sel:DWORD dst_unused:UNUSED_PAD src0_sel:WORD_1 src1_sel:DWORD
	v_add3_u32 v8, v8, v7, s89
	v_add3_u32 v6, v10, v6, s89
	v_and_b32_sdwa v7, v11, v124 dst_sel:DWORD dst_unused:UNUSED_PAD src0_sel:WORD_1 src1_sel:DWORD
	v_and_b32_sdwa v10, v9, v124 dst_sel:DWORD dst_unused:UNUSED_PAD src0_sel:WORD_1 src1_sel:DWORD
	v_add3_u32 v7, v11, v7, s89
	v_add3_u32 v9, v9, v10, s89
	v_and_b32_e32 v7, 0xffff0000, v7
	v_and_b32_e32 v9, 0xffff0000, v9
	v_or_b32_sdwa v7, v7, v6 dst_sel:DWORD dst_unused:UNUSED_PAD src0_sel:DWORD src1_sel:WORD_1
	v_or_b32_sdwa v6, v9, v8 dst_sel:DWORD dst_unused:UNUSED_PAD src0_sel:DWORD src1_sel:WORD_1
	v_or_b32_e32 v8, s18, v117
	v_lshlrev_b32_e32 v8, 12, v8
	v_mov_b32_e32 v9, v75
	v_or_b32_sdwa v4, v12, v4 dst_sel:DWORD dst_unused:UNUSED_PAD src0_sel:DWORD src1_sel:WORD_1
	v_lshl_add_u64 v[8:9], v[2:3], 0, v[8:9]
	global_store_dwordx4 v[8:9], v[4:7], off
	v_add_u32_e32 v8, 0x1870, v123
	v_add_u32_e32 v10, 0x1878, v123
	v_add_u32_e32 v4, 0x1860, v123
	v_add_u32_e32 v6, 0x1868, v123
	ds_read2_b32 v[4:5], v4 offset1:1
	ds_read2_b32 v[6:7], v6 offset1:1
	ds_read2_b32 v[8:9], v8 offset1:1
	ds_read2_b32 v[10:11], v10 offset1:1
	s_waitcnt lgkmcnt(3)
	v_and_b32_sdwa v13, v4, v124 dst_sel:DWORD dst_unused:UNUSED_PAD src0_sel:WORD_1 src1_sel:DWORD
	s_waitcnt lgkmcnt(2)
	v_and_b32_sdwa v12, v6, v124 dst_sel:DWORD dst_unused:UNUSED_PAD src0_sel:WORD_1 src1_sel:DWORD
	v_add3_u32 v6, v6, v12, s89
	v_and_b32_sdwa v12, v7, v124 dst_sel:DWORD dst_unused:UNUSED_PAD src0_sel:WORD_1 src1_sel:DWORD
	v_add3_u32 v4, v4, v13, s89
	v_and_b32_sdwa v13, v5, v124 dst_sel:DWORD dst_unused:UNUSED_PAD src0_sel:WORD_1 src1_sel:DWORD
	v_add3_u32 v7, v7, v12, s89
	v_add3_u32 v5, v5, v13, s89
	v_and_b32_e32 v7, 0xffff0000, v7
	v_and_b32_e32 v12, 0xffff0000, v5
	v_or_b32_sdwa v5, v7, v6 dst_sel:DWORD dst_unused:UNUSED_PAD src0_sel:DWORD src1_sel:WORD_1
	s_waitcnt lgkmcnt(0)
	v_and_b32_sdwa v6, v10, v124 dst_sel:DWORD dst_unused:UNUSED_PAD src0_sel:WORD_1 src1_sel:DWORD
	v_and_b32_sdwa v7, v8, v124 dst_sel:DWORD dst_unused:UNUSED_PAD src0_sel:WORD_1 src1_sel:DWORD
	v_add3_u32 v8, v8, v7, s89
	v_add3_u32 v6, v10, v6, s89
	v_and_b32_sdwa v7, v11, v124 dst_sel:DWORD dst_unused:UNUSED_PAD src0_sel:WORD_1 src1_sel:DWORD
	v_and_b32_sdwa v10, v9, v124 dst_sel:DWORD dst_unused:UNUSED_PAD src0_sel:WORD_1 src1_sel:DWORD
	v_add3_u32 v7, v11, v7, s89
	v_add3_u32 v9, v9, v10, s89
	v_and_b32_e32 v7, 0xffff0000, v7
	v_and_b32_e32 v9, 0xffff0000, v9
	v_or_b32_sdwa v7, v7, v6 dst_sel:DWORD dst_unused:UNUSED_PAD src0_sel:DWORD src1_sel:WORD_1
	v_or_b32_sdwa v6, v9, v8 dst_sel:DWORD dst_unused:UNUSED_PAD src0_sel:DWORD src1_sel:WORD_1
	v_or_b32_e32 v8, s18, v118
	v_lshlrev_b32_e32 v8, 12, v8
	v_mov_b32_e32 v9, v75
	v_or_b32_sdwa v4, v12, v4 dst_sel:DWORD dst_unused:UNUSED_PAD src0_sel:DWORD src1_sel:WORD_1
	v_lshl_add_u64 v[8:9], v[2:3], 0, v[8:9]
	global_store_dwordx4 v[8:9], v[4:7], off
	v_add_u32_e32 v8, 0x2090, v123
	v_add_u32_e32 v10, 0x2098, v123
	v_add_u32_e32 v4, 0x2080, v123
	v_add_u32_e32 v6, 0x2088, v123
	ds_read2_b32 v[4:5], v4 offset1:1
	ds_read2_b32 v[6:7], v6 offset1:1
	ds_read2_b32 v[8:9], v8 offset1:1
	ds_read2_b32 v[10:11], v10 offset1:1
	s_waitcnt lgkmcnt(3)
	v_and_b32_sdwa v13, v4, v124 dst_sel:DWORD dst_unused:UNUSED_PAD src0_sel:WORD_1 src1_sel:DWORD
	s_waitcnt lgkmcnt(2)
	v_and_b32_sdwa v12, v6, v124 dst_sel:DWORD dst_unused:UNUSED_PAD src0_sel:WORD_1 src1_sel:DWORD
	v_add3_u32 v6, v6, v12, s89
	v_and_b32_sdwa v12, v7, v124 dst_sel:DWORD dst_unused:UNUSED_PAD src0_sel:WORD_1 src1_sel:DWORD
	v_add3_u32 v4, v4, v13, s89
	v_and_b32_sdwa v13, v5, v124 dst_sel:DWORD dst_unused:UNUSED_PAD src0_sel:WORD_1 src1_sel:DWORD
	v_add3_u32 v7, v7, v12, s89
	v_add3_u32 v5, v5, v13, s89
	v_and_b32_e32 v7, 0xffff0000, v7
	v_and_b32_e32 v12, 0xffff0000, v5
	v_or_b32_sdwa v5, v7, v6 dst_sel:DWORD dst_unused:UNUSED_PAD src0_sel:DWORD src1_sel:WORD_1
	s_waitcnt lgkmcnt(0)
	v_and_b32_sdwa v6, v10, v124 dst_sel:DWORD dst_unused:UNUSED_PAD src0_sel:WORD_1 src1_sel:DWORD
	v_and_b32_sdwa v7, v8, v124 dst_sel:DWORD dst_unused:UNUSED_PAD src0_sel:WORD_1 src1_sel:DWORD
	v_add3_u32 v8, v8, v7, s89
	v_add3_u32 v6, v10, v6, s89
	v_and_b32_sdwa v7, v11, v124 dst_sel:DWORD dst_unused:UNUSED_PAD src0_sel:WORD_1 src1_sel:DWORD
	v_and_b32_sdwa v10, v9, v124 dst_sel:DWORD dst_unused:UNUSED_PAD src0_sel:WORD_1 src1_sel:DWORD
	v_add3_u32 v7, v11, v7, s89
	v_add3_u32 v9, v9, v10, s89
	v_and_b32_e32 v7, 0xffff0000, v7
	v_and_b32_e32 v9, 0xffff0000, v9
	v_or_b32_sdwa v7, v7, v6 dst_sel:DWORD dst_unused:UNUSED_PAD src0_sel:DWORD src1_sel:WORD_1
	v_or_b32_sdwa v6, v9, v8 dst_sel:DWORD dst_unused:UNUSED_PAD src0_sel:DWORD src1_sel:WORD_1
	v_or_b32_e32 v8, s18, v119
	v_lshlrev_b32_e32 v8, 12, v8
	v_mov_b32_e32 v9, v75
	v_or_b32_sdwa v4, v12, v4 dst_sel:DWORD dst_unused:UNUSED_PAD src0_sel:DWORD src1_sel:WORD_1
	v_lshl_add_u64 v[8:9], v[2:3], 0, v[8:9]
	global_store_dwordx4 v[8:9], v[4:7], off
	v_add_u32_e32 v8, 0x28b0, v123
	v_add_u32_e32 v10, 0x28b8, v123
	v_add_u32_e32 v4, 0x28a0, v123
	v_add_u32_e32 v6, 0x28a8, v123
	ds_read2_b32 v[4:5], v4 offset1:1
	ds_read2_b32 v[6:7], v6 offset1:1
	ds_read2_b32 v[8:9], v8 offset1:1
	ds_read2_b32 v[10:11], v10 offset1:1
	s_waitcnt lgkmcnt(3)
	v_and_b32_sdwa v13, v4, v124 dst_sel:DWORD dst_unused:UNUSED_PAD src0_sel:WORD_1 src1_sel:DWORD
	s_waitcnt lgkmcnt(2)
	v_and_b32_sdwa v12, v6, v124 dst_sel:DWORD dst_unused:UNUSED_PAD src0_sel:WORD_1 src1_sel:DWORD
	v_add3_u32 v6, v6, v12, s89
	v_and_b32_sdwa v12, v7, v124 dst_sel:DWORD dst_unused:UNUSED_PAD src0_sel:WORD_1 src1_sel:DWORD
	v_add3_u32 v4, v4, v13, s89
	v_and_b32_sdwa v13, v5, v124 dst_sel:DWORD dst_unused:UNUSED_PAD src0_sel:WORD_1 src1_sel:DWORD
	v_add3_u32 v7, v7, v12, s89
	v_add3_u32 v5, v5, v13, s89
	v_and_b32_e32 v7, 0xffff0000, v7
	v_and_b32_e32 v12, 0xffff0000, v5
	v_or_b32_sdwa v5, v7, v6 dst_sel:DWORD dst_unused:UNUSED_PAD src0_sel:DWORD src1_sel:WORD_1
	s_waitcnt lgkmcnt(0)
	v_and_b32_sdwa v6, v10, v124 dst_sel:DWORD dst_unused:UNUSED_PAD src0_sel:WORD_1 src1_sel:DWORD
	v_and_b32_sdwa v7, v8, v124 dst_sel:DWORD dst_unused:UNUSED_PAD src0_sel:WORD_1 src1_sel:DWORD
	v_add3_u32 v8, v8, v7, s89
	v_add3_u32 v6, v10, v6, s89
	v_and_b32_sdwa v7, v11, v124 dst_sel:DWORD dst_unused:UNUSED_PAD src0_sel:WORD_1 src1_sel:DWORD
	v_and_b32_sdwa v10, v9, v124 dst_sel:DWORD dst_unused:UNUSED_PAD src0_sel:WORD_1 src1_sel:DWORD
	v_add3_u32 v7, v11, v7, s89
	v_add3_u32 v9, v9, v10, s89
	v_and_b32_e32 v7, 0xffff0000, v7
	v_and_b32_e32 v9, 0xffff0000, v9
	v_or_b32_sdwa v7, v7, v6 dst_sel:DWORD dst_unused:UNUSED_PAD src0_sel:DWORD src1_sel:WORD_1
	v_or_b32_sdwa v6, v9, v8 dst_sel:DWORD dst_unused:UNUSED_PAD src0_sel:DWORD src1_sel:WORD_1
	v_or_b32_e32 v8, s18, v120
	v_lshlrev_b32_e32 v8, 12, v8
	v_mov_b32_e32 v9, v75
	v_or_b32_sdwa v4, v12, v4 dst_sel:DWORD dst_unused:UNUSED_PAD src0_sel:DWORD src1_sel:WORD_1
	v_lshl_add_u64 v[8:9], v[2:3], 0, v[8:9]
	global_store_dwordx4 v[8:9], v[4:7], off
	v_add_u32_e32 v8, 0x30d0, v123
	v_add_u32_e32 v10, 0x30d8, v123
	v_add_u32_e32 v4, 0x30c0, v123
	v_add_u32_e32 v6, 0x30c8, v123
	ds_read2_b32 v[4:5], v4 offset1:1
	ds_read2_b32 v[6:7], v6 offset1:1
	ds_read2_b32 v[8:9], v8 offset1:1
	ds_read2_b32 v[10:11], v10 offset1:1
	s_waitcnt lgkmcnt(3)
	v_and_b32_sdwa v13, v4, v124 dst_sel:DWORD dst_unused:UNUSED_PAD src0_sel:WORD_1 src1_sel:DWORD
	s_waitcnt lgkmcnt(2)
	v_and_b32_sdwa v12, v6, v124 dst_sel:DWORD dst_unused:UNUSED_PAD src0_sel:WORD_1 src1_sel:DWORD
	v_add3_u32 v6, v6, v12, s89
	v_and_b32_sdwa v12, v7, v124 dst_sel:DWORD dst_unused:UNUSED_PAD src0_sel:WORD_1 src1_sel:DWORD
	v_add3_u32 v4, v4, v13, s89
	v_and_b32_sdwa v13, v5, v124 dst_sel:DWORD dst_unused:UNUSED_PAD src0_sel:WORD_1 src1_sel:DWORD
	v_add3_u32 v7, v7, v12, s89
	v_add3_u32 v5, v5, v13, s89
	v_and_b32_e32 v7, 0xffff0000, v7
	v_and_b32_e32 v12, 0xffff0000, v5
	v_or_b32_sdwa v5, v7, v6 dst_sel:DWORD dst_unused:UNUSED_PAD src0_sel:DWORD src1_sel:WORD_1
	s_waitcnt lgkmcnt(0)
	v_and_b32_sdwa v6, v10, v124 dst_sel:DWORD dst_unused:UNUSED_PAD src0_sel:WORD_1 src1_sel:DWORD
	v_and_b32_sdwa v7, v8, v124 dst_sel:DWORD dst_unused:UNUSED_PAD src0_sel:WORD_1 src1_sel:DWORD
	v_add3_u32 v8, v8, v7, s89
	v_add3_u32 v6, v10, v6, s89
	v_and_b32_sdwa v7, v11, v124 dst_sel:DWORD dst_unused:UNUSED_PAD src0_sel:WORD_1 src1_sel:DWORD
	v_and_b32_sdwa v10, v9, v124 dst_sel:DWORD dst_unused:UNUSED_PAD src0_sel:WORD_1 src1_sel:DWORD
	v_add3_u32 v7, v11, v7, s89
	v_add3_u32 v9, v9, v10, s89
	v_and_b32_e32 v7, 0xffff0000, v7
	v_and_b32_e32 v9, 0xffff0000, v9
	v_or_b32_sdwa v7, v7, v6 dst_sel:DWORD dst_unused:UNUSED_PAD src0_sel:DWORD src1_sel:WORD_1
	v_or_b32_sdwa v6, v9, v8 dst_sel:DWORD dst_unused:UNUSED_PAD src0_sel:DWORD src1_sel:WORD_1
	v_or_b32_e32 v8, s18, v121
	v_lshlrev_b32_e32 v8, 12, v8
	v_mov_b32_e32 v9, v75
	v_or_b32_sdwa v4, v12, v4 dst_sel:DWORD dst_unused:UNUSED_PAD src0_sel:DWORD src1_sel:WORD_1
	v_lshl_add_u64 v[8:9], v[2:3], 0, v[8:9]
	global_store_dwordx4 v[8:9], v[4:7], off
	v_add_u32_e32 v8, 0x38f0, v123
	v_add_u32_e32 v10, 0x38f8, v123
	v_add_u32_e32 v4, 0x38e0, v123
	v_add_u32_e32 v6, 0x38e8, v123
	ds_read2_b32 v[4:5], v4 offset1:1
	ds_read2_b32 v[6:7], v6 offset1:1
	ds_read2_b32 v[8:9], v8 offset1:1
	ds_read2_b32 v[10:11], v10 offset1:1
	s_waitcnt lgkmcnt(3)
	v_and_b32_sdwa v13, v4, v124 dst_sel:DWORD dst_unused:UNUSED_PAD src0_sel:WORD_1 src1_sel:DWORD
	s_waitcnt lgkmcnt(2)
	v_and_b32_sdwa v12, v6, v124 dst_sel:DWORD dst_unused:UNUSED_PAD src0_sel:WORD_1 src1_sel:DWORD
	v_add3_u32 v6, v6, v12, s89
	v_and_b32_sdwa v12, v7, v124 dst_sel:DWORD dst_unused:UNUSED_PAD src0_sel:WORD_1 src1_sel:DWORD
	v_add3_u32 v4, v4, v13, s89
	v_and_b32_sdwa v13, v5, v124 dst_sel:DWORD dst_unused:UNUSED_PAD src0_sel:WORD_1 src1_sel:DWORD
	v_add3_u32 v7, v7, v12, s89
	v_add3_u32 v5, v5, v13, s89
	v_and_b32_e32 v7, 0xffff0000, v7
	v_and_b32_e32 v12, 0xffff0000, v5
	v_or_b32_sdwa v5, v7, v6 dst_sel:DWORD dst_unused:UNUSED_PAD src0_sel:DWORD src1_sel:WORD_1
	s_waitcnt lgkmcnt(0)
	v_and_b32_sdwa v6, v10, v124 dst_sel:DWORD dst_unused:UNUSED_PAD src0_sel:WORD_1 src1_sel:DWORD
	v_and_b32_sdwa v7, v8, v124 dst_sel:DWORD dst_unused:UNUSED_PAD src0_sel:WORD_1 src1_sel:DWORD
	v_add3_u32 v8, v8, v7, s89
	v_add3_u32 v6, v10, v6, s89
	v_and_b32_sdwa v7, v11, v124 dst_sel:DWORD dst_unused:UNUSED_PAD src0_sel:WORD_1 src1_sel:DWORD
	v_and_b32_sdwa v10, v9, v124 dst_sel:DWORD dst_unused:UNUSED_PAD src0_sel:WORD_1 src1_sel:DWORD
	v_add3_u32 v7, v11, v7, s89
	v_add3_u32 v9, v9, v10, s89
	v_and_b32_e32 v7, 0xffff0000, v7
	v_and_b32_e32 v9, 0xffff0000, v9
	v_or_b32_sdwa v7, v7, v6 dst_sel:DWORD dst_unused:UNUSED_PAD src0_sel:DWORD src1_sel:WORD_1
	v_or_b32_sdwa v6, v9, v8 dst_sel:DWORD dst_unused:UNUSED_PAD src0_sel:DWORD src1_sel:WORD_1
	v_or_b32_e32 v8, s18, v122
	v_lshlrev_b32_e32 v8, 12, v8
	v_mov_b32_e32 v9, v75
	v_or_b32_sdwa v4, v12, v4 dst_sel:DWORD dst_unused:UNUSED_PAD src0_sel:DWORD src1_sel:WORD_1
	v_lshl_add_u64 v[2:3], v[2:3], 0, v[8:9]
	global_store_dwordx4 v[2:3], v[4:7], off
	s_waitcnt lgkmcnt(0)

.LBB0_25:
	s_andn2_b64 vcc, exec, s[2:3]
	s_cbranch_vccnz .LBB0_51
	s_add_i32 s2, s92, 0xe000
	s_lshr_b32 s2, s2, 1
	s_and_b32 s19, s2, 0x7fc0
	s_and_b32 s18, s21, 0x1fc0
	v_or_b32_e32 v66, s19, v72
	s_lshl_b32 s14, s18, 2
	v_lshl_add_u64 v[2:3], v[80:81], 0, s[14:15]
	v_lshlrev_b32_e32 v4, 15, v66
	v_mov_b32_e32 v5, v75
	v_lshl_add_u64 v[2:3], v[2:3], 0, v[4:5]
	v_add_co_u32_e32 v4, vcc, 0x20000, v2
	s_mov_b64 s[76:77], s[28:29]
	s_nop 0
	v_addc_co_u32_e32 v5, vcc, 0, v3, vcc
	global_load_dwordx4 v[58:61], v[2:3], off nt
	global_load_dwordx4 v[62:65], v[4:5], off nt
	v_add_co_u32_e32 v4, vcc, 0x40000, v2
	v_cndmask_b32_e64 v67, 0, 1, s[8:9]
	s_nop 0
	v_addc_co_u32_e32 v5, vcc, 0, v3, vcc
	v_add_co_u32_e32 v6, vcc, 0x60000, v2
	v_cmp_ne_u32_e64 s[2:3], 1, v67
	s_nop 0
	v_addc_co_u32_e32 v7, vcc, 0, v3, vcc
	global_load_dwordx4 v[50:53], v[4:5], off nt
	global_load_dwordx4 v[54:57], v[6:7], off nt
	v_add_co_u32_e32 v4, vcc, 0x80000, v2
	v_add_lshl_u32 v127, s19, v72, 2
	s_nop 0
	v_addc_co_u32_e32 v5, vcc, 0, v3, vcc
	v_add_co_u32_e32 v6, vcc, 0xa0000, v2
	s_nop 1
	v_addc_co_u32_e32 v7, vcc, 0, v3, vcc
	global_load_dwordx4 v[42:45], v[4:5], off nt
	global_load_dwordx4 v[46:49], v[6:7], off nt
	v_add_co_u32_e32 v4, vcc, 0xc0000, v2
	s_nop 1
	v_addc_co_u32_e32 v5, vcc, 0, v3, vcc
	v_add_co_u32_e32 v6, vcc, 0xe0000, v2
	s_nop 1
	v_addc_co_u32_e32 v7, vcc, 0, v3, vcc
	global_load_dwordx4 v[34:37], v[4:5], off nt
	global_load_dwordx4 v[38:41], v[6:7], off nt
	v_add_co_u32_e32 v4, vcc, 0x100000, v2
	s_nop 1
	v_addc_co_u32_e32 v5, vcc, 0, v3, vcc
	v_add_co_u32_e32 v6, vcc, 0x120000, v2
	s_nop 1
	v_addc_co_u32_e32 v7, vcc, 0, v3, vcc
	global_load_dwordx4 v[26:29], v[4:5], off nt
	global_load_dwordx4 v[30:33], v[6:7], off nt
	v_add_co_u32_e32 v4, vcc, 0x140000, v2
	s_nop 1
	v_addc_co_u32_e32 v5, vcc, 0, v3, vcc
	v_add_co_u32_e32 v6, vcc, 0x160000, v2
	s_nop 1
	v_addc_co_u32_e32 v7, vcc, 0, v3, vcc
	global_load_dwordx4 v[18:21], v[4:5], off nt
	global_load_dwordx4 v[22:25], v[6:7], off nt
	v_add_co_u32_e32 v4, vcc, 0x180000, v2
	s_nop 1
	v_addc_co_u32_e32 v5, vcc, 0, v3, vcc
	v_add_co_u32_e32 v6, vcc, 0x1a0000, v2
	s_nop 1
	v_addc_co_u32_e32 v7, vcc, 0, v3, vcc
	global_load_dwordx4 v[10:13], v[4:5], off nt
	global_load_dwordx4 v[14:17], v[6:7], off nt
	v_add_co_u32_e32 v4, vcc, 0x1c0000, v2
	s_nop 1
	v_addc_co_u32_e32 v5, vcc, 0, v3, vcc
	v_add_co_u32_e32 v6, vcc, 0x1e0000, v2
	s_nop 1
	v_addc_co_u32_e32 v7, vcc, 0, v3, vcc
	global_load_dwordx4 v[2:5], v[4:5], off nt
	s_nop 0
	global_load_dwordx4 v[6:9], v[6:7], off nt
	s_andn2_b64 vcc, exec, s[8:9]
	s_cbranch_vccnz .LBB0_164
	v_lshlrev_b32_e32 v66, 2, v66
	global_load_dword v66, v66, s[58:59]
	s_nop 0
	global_load_dword v128, v127, s[58:59] offset:16
	s_waitcnt vmcnt(1)
	v_pk_mul_f32 v[60:61], v[60:61], v[66:67] op_sel_hi:[1,0]
	v_pk_mul_f32 v[58:59], v[58:59], v[66:67] op_sel_hi:[1,0]
	s_waitcnt vmcnt(0)
	v_pk_mul_f32 v[68:69], v[64:65], v[128:129] op_sel_hi:[1,0]
	v_pk_mul_f32 v[66:67], v[62:63], v[128:129] op_sel_hi:[1,0]
	s_cbranch_execnz .LBB0_29

.LBB0_52:
	s_andn2_b64 vcc, exec, s[2:3]
	s_cbranch_vccnz .LBB0_54
	s_add_i32 s14, s85, 0x6800
	s_and_b32 s19, s14, 0x1ffc0
	s_and_b32 s18, s21, 0x7c0
	v_or_b32_e32 v4, s19, v72
	s_lshl_b32 s14, s18, 2
	v_lshl_add_u64 v[2:3], v[84:85], 0, s[14:15]
	v_lshlrev_b32_e32 v4, 13, v4
	v_mov_b32_e32 v5, v75
	v_lshl_add_u64 v[58:59], v[2:3], 0, v[4:5]
	v_add_co_u32_e32 v6, vcc, 0x8000, v58
	s_mov_b64 s[2:3], s[28:29]
	s_nop 0
	v_addc_co_u32_e32 v7, vcc, 0, v59, vcc
	v_add_co_u32_e32 v10, vcc, 0x10000, v58
	global_load_dwordx4 v[2:5], v[58:59], off nt
	s_nop 0
	global_load_dwordx4 v[6:9], v[6:7], off nt
	v_addc_co_u32_e32 v11, vcc, 0, v59, vcc
	v_add_co_u32_e32 v14, vcc, 0x18000, v58
	s_lshl_b32 s14, s19, 1
	s_nop 0
	v_addc_co_u32_e32 v15, vcc, 0, v59, vcc
	v_add_co_u32_e32 v18, vcc, 0x20000, v58
	global_load_dwordx4 v[10:13], v[10:11], off nt
	s_nop 0
	global_load_dwordx4 v[14:17], v[14:15], off nt
	v_addc_co_u32_e32 v19, vcc, 0, v59, vcc
	v_add_co_u32_e32 v22, vcc, 0x28000, v58
	s_add_u32 s2, s2, s14
	s_nop 0
	v_addc_co_u32_e32 v23, vcc, 0, v59, vcc
	v_add_co_u32_e32 v26, vcc, 0x30000, v58
	global_load_dwordx4 v[18:21], v[18:19], off nt
	s_nop 0
	global_load_dwordx4 v[22:25], v[22:23], off nt
	v_addc_co_u32_e32 v27, vcc, 0, v59, vcc
	v_add_co_u32_e32 v30, vcc, 0x38000, v58
	s_addc_u32 s3, s3, 0
	s_nop 0
	v_addc_co_u32_e32 v31, vcc, 0, v59, vcc
	v_add_co_u32_e32 v34, vcc, 0x40000, v58
	global_load_dwordx4 v[26:29], v[26:27], off nt
	s_nop 0
	global_load_dwordx4 v[30:33], v[30:31], off nt
	v_addc_co_u32_e32 v35, vcc, 0, v59, vcc
	v_add_co_u32_e32 v38, vcc, 0x48000, v58
	s_nop 1
	v_addc_co_u32_e32 v39, vcc, 0, v59, vcc
	v_add_co_u32_e32 v42, vcc, 0x50000, v58
	global_load_dwordx4 v[34:37], v[34:35], off nt
	s_nop 0
	global_load_dwordx4 v[38:41], v[38:39], off nt
	v_addc_co_u32_e32 v43, vcc, 0, v59, vcc
	v_add_co_u32_e32 v46, vcc, 0x58000, v58
	s_nop 1
	v_addc_co_u32_e32 v47, vcc, 0, v59, vcc
	v_add_co_u32_e32 v50, vcc, 0x60000, v58
	global_load_dwordx4 v[42:45], v[42:43], off nt
	s_nop 0
	global_load_dwordx4 v[46:49], v[46:47], off nt
	v_addc_co_u32_e32 v51, vcc, 0, v59, vcc
	v_add_co_u32_e32 v54, vcc, 0x68000, v58
	s_nop 1
	v_addc_co_u32_e32 v55, vcc, 0, v59, vcc
	v_add_co_u32_e32 v60, vcc, 0x70000, v58
	global_load_dwordx4 v[50:53], v[50:51], off nt
	s_nop 0
	global_load_dwordx4 v[54:57], v[54:55], off nt
	v_addc_co_u32_e32 v61, vcc, 0, v59, vcc
	v_add_co_u32_e32 v62, vcc, 0x78000, v58
	s_nop 1
	v_addc_co_u32_e32 v63, vcc, 0, v59, vcc
	global_load_dwordx4 v[58:61], v[60:61], off nt
	s_nop 0
	global_load_dwordx4 v[62:65], v[62:63], off nt
	s_waitcnt vmcnt(14)
	ds_write2_b32 v99, v2, v6 offset1:4
	ds_write2_b32 v99, v3, v7 offset0:65 offset1:69
	ds_write2_b32 v99, v4, v8 offset0:130 offset1:134
	ds_write2_b32 v99, v5, v9 offset0:195 offset1:199
	s_waitcnt vmcnt(12)
	ds_write2_b32 v99, v10, v14 offset0:8 offset1:12
	ds_write2_b32 v99, v11, v15 offset0:73 offset1:77
	ds_write2_b32 v99, v12, v16 offset0:138 offset1:142
	ds_write2_b32 v99, v13, v17 offset0:203 offset1:207
	s_waitcnt vmcnt(10)
	ds_write2_b32 v99, v18, v22 offset0:16 offset1:20
	ds_write2_b32 v99, v19, v23 offset0:81 offset1:85
	ds_write2_b32 v99, v20, v24 offset0:146 offset1:150
	ds_write2_b32 v99, v21, v25 offset0:211 offset1:215
	s_waitcnt vmcnt(8)
	ds_write2_b32 v99, v26, v30 offset0:24 offset1:28
	ds_write2_b32 v99, v27, v31 offset0:89 offset1:93
	ds_write2_b32 v99, v28, v32 offset0:154 offset1:158
	ds_write2_b32 v99, v29, v33 offset0:219 offset1:223
	s_waitcnt vmcnt(6)
	ds_write2_b32 v99, v34, v38 offset0:32 offset1:36
	ds_write2_b32 v99, v35, v39 offset0:97 offset1:101
	ds_write2_b32 v99, v36, v40 offset0:162 offset1:166
	ds_write2_b32 v99, v37, v41 offset0:227 offset1:231
	s_waitcnt vmcnt(4)
	ds_write2_b32 v99, v42, v46 offset0:40 offset1:44
	ds_write2_b32 v99, v43, v47 offset0:105 offset1:109
	ds_write2_b32 v99, v44, v48 offset0:170 offset1:174
	ds_write2_b32 v99, v45, v49 offset0:235 offset1:239
	s_waitcnt vmcnt(2)
	ds_write2_b32 v99, v50, v54 offset0:48 offset1:52
	ds_write2_b32 v99, v51, v55 offset0:113 offset1:117
	ds_write2_b32 v99, v52, v56 offset0:178 offset1:182
	ds_write2_b32 v99, v53, v57 offset0:243 offset1:247
	s_waitcnt vmcnt(0)
	ds_write2_b32 v99, v58, v62 offset0:56 offset1:60
	ds_write2_b32 v99, v59, v63 offset0:121 offset1:125
	ds_write2_b32 v99, v60, v64 offset0:186 offset1:190
	ds_write2_b32 v99, v61, v65 offset0:251 offset1:255
	s_waitcnt lgkmcnt(0)
	ds_read2_b32 v[4:5], v123 offset1:1
	ds_read2_b32 v[6:7], v123 offset0:2 offset1:3
	ds_read2_b32 v[8:9], v123 offset0:4 offset1:5
	ds_read2_b32 v[10:11], v123 offset0:6 offset1:7
	v_lshl_add_u64 v[2:3], s[2:3], 0, v[74:75]
	v_lshl_add_u64 v[2:3], v[2:3], 0, s[70:71]
	s_waitcnt lgkmcnt(3)
	v_and_b32_sdwa v13, v4, v124 dst_sel:DWORD dst_unused:UNUSED_PAD src0_sel:WORD_1 src1_sel:DWORD
	s_waitcnt lgkmcnt(2)
	v_and_b32_sdwa v12, v6, v124 dst_sel:DWORD dst_unused:UNUSED_PAD src0_sel:WORD_1 src1_sel:DWORD
	v_add3_u32 v6, v6, v12, s89
	v_and_b32_sdwa v12, v7, v124 dst_sel:DWORD dst_unused:UNUSED_PAD src0_sel:WORD_1 src1_sel:DWORD
	v_add3_u32 v4, v4, v13, s89
	v_and_b32_sdwa v13, v5, v124 dst_sel:DWORD dst_unused:UNUSED_PAD src0_sel:WORD_1 src1_sel:DWORD
	v_add3_u32 v7, v7, v12, s89
	v_add3_u32 v5, v5, v13, s89
	v_and_b32_e32 v7, 0xffff0000, v7
	v_and_b32_e32 v12, 0xffff0000, v5
	v_or_b32_sdwa v5, v7, v6 dst_sel:DWORD dst_unused:UNUSED_PAD src0_sel:DWORD src1_sel:WORD_1
	s_waitcnt lgkmcnt(0)
	v_and_b32_sdwa v6, v10, v124 dst_sel:DWORD dst_unused:UNUSED_PAD src0_sel:WORD_1 src1_sel:DWORD
	v_and_b32_sdwa v7, v8, v124 dst_sel:DWORD dst_unused:UNUSED_PAD src0_sel:WORD_1 src1_sel:DWORD
	v_add3_u32 v8, v8, v7, s89
	v_add3_u32 v6, v10, v6, s89
	v_and_b32_sdwa v7, v11, v124 dst_sel:DWORD dst_unused:UNUSED_PAD src0_sel:WORD_1 src1_sel:DWORD
	v_and_b32_sdwa v10, v9, v124 dst_sel:DWORD dst_unused:UNUSED_PAD src0_sel:WORD_1 src1_sel:DWORD
	v_add3_u32 v7, v11, v7, s89
	v_add3_u32 v9, v9, v10, s89
	v_and_b32_e32 v7, 0xffff0000, v7
	v_and_b32_e32 v9, 0xffff0000, v9
	v_or_b32_sdwa v7, v7, v6 dst_sel:DWORD dst_unused:UNUSED_PAD src0_sel:DWORD src1_sel:WORD_1
	v_or_b32_sdwa v6, v9, v8 dst_sel:DWORD dst_unused:UNUSED_PAD src0_sel:DWORD src1_sel:WORD_1
	v_or_b32_e32 v8, s18, v115
	v_lshlrev_b32_e32 v8, 12, v8
	v_mov_b32_e32 v9, v75
	v_or_b32_sdwa v4, v12, v4 dst_sel:DWORD dst_unused:UNUSED_PAD src0_sel:DWORD src1_sel:WORD_1
	v_lshl_add_u64 v[8:9], v[2:3], 0, v[8:9]
	global_store_dwordx4 v[8:9], v[4:7], off
	ds_read2_b32 v[4:5], v125 offset1:1
	ds_read2_b32 v[6:7], v126 offset1:1
	v_add_u32_e32 v8, 0x830, v123
	v_add_u32_e32 v10, 0x838, v123
	ds_read2_b32 v[8:9], v8 offset1:1
	ds_read2_b32 v[10:11], v10 offset1:1
	s_waitcnt lgkmcnt(3)
	v_and_b32_sdwa v13, v4, v124 dst_sel:DWORD dst_unused:UNUSED_PAD src0_sel:WORD_1 src1_sel:DWORD
	s_waitcnt lgkmcnt(2)
	v_and_b32_sdwa v12, v6, v124 dst_sel:DWORD dst_unused:UNUSED_PAD src0_sel:WORD_1 src1_sel:DWORD
	v_add3_u32 v6, v6, v12, s89
	v_and_b32_sdwa v12, v7, v124 dst_sel:DWORD dst_unused:UNUSED_PAD src0_sel:WORD_1 src1_sel:DWORD
	v_add3_u32 v4, v4, v13, s89
	v_and_b32_sdwa v13, v5, v124 dst_sel:DWORD dst_unused:UNUSED_PAD src0_sel:WORD_1 src1_sel:DWORD
	v_add3_u32 v7, v7, v12, s89
	v_add3_u32 v5, v5, v13, s89
	v_and_b32_e32 v7, 0xffff0000, v7
	v_and_b32_e32 v12, 0xffff0000, v5
	v_or_b32_sdwa v5, v7, v6 dst_sel:DWORD dst_unused:UNUSED_PAD src0_sel:DWORD src1_sel:WORD_1
	s_waitcnt lgkmcnt(0)
	v_and_b32_sdwa v6, v10, v124 dst_sel:DWORD dst_unused:UNUSED_PAD src0_sel:WORD_1 src1_sel:DWORD
	v_and_b32_sdwa v7, v8, v124 dst_sel:DWORD dst_unused:UNUSED_PAD src0_sel:WORD_1 src1_sel:DWORD
	v_add3_u32 v8, v8, v7, s89
	v_add3_u32 v6, v10, v6, s89
	v_and_b32_sdwa v7, v11, v124 dst_sel:DWORD dst_unused:UNUSED_PAD src0_sel:WORD_1 src1_sel:DWORD
	v_and_b32_sdwa v10, v9, v124 dst_sel:DWORD dst_unused:UNUSED_PAD src0_sel:WORD_1 src1_sel:DWORD
	v_add3_u32 v7, v11, v7, s89
	v_add3_u32 v9, v9, v10, s89
	v_and_b32_e32 v7, 0xffff0000, v7
	v_and_b32_e32 v9, 0xffff0000, v9
	v_or_b32_sdwa v7, v7, v6 dst_sel:DWORD dst_unused:UNUSED_PAD src0_sel:DWORD src1_sel:WORD_1
	v_or_b32_sdwa v6, v9, v8 dst_sel:DWORD dst_unused:UNUSED_PAD src0_sel:DWORD src1_sel:WORD_1
	v_or_b32_e32 v8, s18, v116
	v_lshlrev_b32_e32 v8, 12, v8
	v_mov_b32_e32 v9, v75
	v_or_b32_sdwa v4, v12, v4 dst_sel:DWORD dst_unused:UNUSED_PAD src0_sel:DWORD src1_sel:WORD_1
	v_lshl_add_u64 v[8:9], v[2:3], 0, v[8:9]
	global_store_dwordx4 v[8:9], v[4:7], off
	v_add_u32_e32 v8, 0x1050, v123
	v_add_u32_e32 v10, 0x1058, v123
	v_add_u32_e32 v4, 0x1040, v123
	v_add_u32_e32 v6, 0x1048, v123
	ds_read2_b32 v[4:5], v4 offset1:1
	ds_read2_b32 v[6:7], v6 offset1:1
	ds_read2_b32 v[8:9], v8 offset1:1
	ds_read2_b32 v[10:11], v10 offset1:1
	s_waitcnt lgkmcnt(3)
	v_and_b32_sdwa v13, v4, v124 dst_sel:DWORD dst_unused:UNUSED_PAD src0_sel:WORD_1 src1_sel:DWORD
	s_waitcnt lgkmcnt(2)
	v_and_b32_sdwa v12, v6, v124 dst_sel:DWORD dst_unused:UNUSED_PAD src0_sel:WORD_1 src1_sel:DWORD
	v_add3_u32 v6, v6, v12, s89
	v_and_b32_sdwa v12, v7, v124 dst_sel:DWORD dst_unused:UNUSED_PAD src0_sel:WORD_1 src1_sel:DWORD
	v_add3_u32 v4, v4, v13, s89
	v_and_b32_sdwa v13, v5, v124 dst_sel:DWORD dst_unused:UNUSED_PAD src0_sel:WORD_1 src1_sel:DWORD
	v_add3_u32 v7, v7, v12, s89
	v_add3_u32 v5, v5, v13, s89
	v_and_b32_e32 v7, 0xffff0000, v7
	v_and_b32_e32 v12, 0xffff0000, v5
	v_or_b32_sdwa v5, v7, v6 dst_sel:DWORD dst_unused:UNUSED_PAD src0_sel:DWORD src1_sel:WORD_1
	s_waitcnt lgkmcnt(0)
	v_and_b32_sdwa v6, v10, v124 dst_sel:DWORD dst_unused:UNUSED_PAD src0_sel:WORD_1 src1_sel:DWORD
	v_and_b32_sdwa v7, v8, v124 dst_sel:DWORD dst_unused:UNUSED_PAD src0_sel:WORD_1 src1_sel:DWORD
	v_add3_u32 v8, v8, v7, s89
	v_add3_u32 v6, v10, v6, s89
	v_and_b32_sdwa v7, v11, v124 dst_sel:DWORD dst_unused:UNUSED_PAD src0_sel:WORD_1 src1_sel:DWORD
	v_and_b32_sdwa v10, v9, v124 dst_sel:DWORD dst_unused:UNUSED_PAD src0_sel:WORD_1 src1_sel:DWORD
	v_add3_u32 v7, v11, v7, s89
	v_add3_u32 v9, v9, v10, s89
	v_and_b32_e32 v7, 0xffff0000, v7
	v_and_b32_e32 v9, 0xffff0000, v9
	v_or_b32_sdwa v7, v7, v6 dst_sel:DWORD dst_unused:UNUSED_PAD src0_sel:DWORD src1_sel:WORD_1
	v_or_b32_sdwa v6, v9, v8 dst_sel:DWORD dst_unused:UNUSED_PAD src0_sel:DWORD src1_sel:WORD_1
	v_or_b32_e32 v8, s18, v117
	v_lshlrev_b32_e32 v8, 12, v8
	v_mov_b32_e32 v9, v75
	v_or_b32_sdwa v4, v12, v4 dst_sel:DWORD dst_unused:UNUSED_PAD src0_sel:DWORD src1_sel:WORD_1
	v_lshl_add_u64 v[8:9], v[2:3], 0, v[8:9]
	global_store_dwordx4 v[8:9], v[4:7], off
	v_add_u32_e32 v8, 0x1870, v123
	v_add_u32_e32 v10, 0x1878, v123
	v_add_u32_e32 v4, 0x1860, v123
	v_add_u32_e32 v6, 0x1868, v123
	ds_read2_b32 v[4:5], v4 offset1:1
	ds_read2_b32 v[6:7], v6 offset1:1
	ds_read2_b32 v[8:9], v8 offset1:1
	ds_read2_b32 v[10:11], v10 offset1:1
	s_waitcnt lgkmcnt(3)
	v_and_b32_sdwa v13, v4, v124 dst_sel:DWORD dst_unused:UNUSED_PAD src0_sel:WORD_1 src1_sel:DWORD
	s_waitcnt lgkmcnt(2)
	v_and_b32_sdwa v12, v6, v124 dst_sel:DWORD dst_unused:UNUSED_PAD src0_sel:WORD_1 src1_sel:DWORD
	v_add3_u32 v6, v6, v12, s89
	v_and_b32_sdwa v12, v7, v124 dst_sel:DWORD dst_unused:UNUSED_PAD src0_sel:WORD_1 src1_sel:DWORD
	v_add3_u32 v4, v4, v13, s89
	v_and_b32_sdwa v13, v5, v124 dst_sel:DWORD dst_unused:UNUSED_PAD src0_sel:WORD_1 src1_sel:DWORD
	v_add3_u32 v7, v7, v12, s89
	v_add3_u32 v5, v5, v13, s89
	v_and_b32_e32 v7, 0xffff0000, v7
	v_and_b32_e32 v12, 0xffff0000, v5
	v_or_b32_sdwa v5, v7, v6 dst_sel:DWORD dst_unused:UNUSED_PAD src0_sel:DWORD src1_sel:WORD_1
	s_waitcnt lgkmcnt(0)
	v_and_b32_sdwa v6, v10, v124 dst_sel:DWORD dst_unused:UNUSED_PAD src0_sel:WORD_1 src1_sel:DWORD
	v_and_b32_sdwa v7, v8, v124 dst_sel:DWORD dst_unused:UNUSED_PAD src0_sel:WORD_1 src1_sel:DWORD
	v_add3_u32 v8, v8, v7, s89
	v_add3_u32 v6, v10, v6, s89
	v_and_b32_sdwa v7, v11, v124 dst_sel:DWORD dst_unused:UNUSED_PAD src0_sel:WORD_1 src1_sel:DWORD
	v_and_b32_sdwa v10, v9, v124 dst_sel:DWORD dst_unused:UNUSED_PAD src0_sel:WORD_1 src1_sel:DWORD
	v_add3_u32 v7, v11, v7, s89
	v_add3_u32 v9, v9, v10, s89
	v_and_b32_e32 v7, 0xffff0000, v7
	v_and_b32_e32 v9, 0xffff0000, v9
	v_or_b32_sdwa v7, v7, v6 dst_sel:DWORD dst_unused:UNUSED_PAD src0_sel:DWORD src1_sel:WORD_1
	v_or_b32_sdwa v6, v9, v8 dst_sel:DWORD dst_unused:UNUSED_PAD src0_sel:DWORD src1_sel:WORD_1
	v_or_b32_e32 v8, s18, v118
	v_lshlrev_b32_e32 v8, 12, v8
	v_mov_b32_e32 v9, v75
	v_or_b32_sdwa v4, v12, v4 dst_sel:DWORD dst_unused:UNUSED_PAD src0_sel:DWORD src1_sel:WORD_1
	v_lshl_add_u64 v[8:9], v[2:3], 0, v[8:9]
	global_store_dwordx4 v[8:9], v[4:7], off
	v_add_u32_e32 v8, 0x2090, v123
	v_add_u32_e32 v10, 0x2098, v123
	v_add_u32_e32 v4, 0x2080, v123
	v_add_u32_e32 v6, 0x2088, v123
	ds_read2_b32 v[4:5], v4 offset1:1
	ds_read2_b32 v[6:7], v6 offset1:1
	ds_read2_b32 v[8:9], v8 offset1:1
	ds_read2_b32 v[10:11], v10 offset1:1
	s_waitcnt lgkmcnt(3)
	v_and_b32_sdwa v13, v4, v124 dst_sel:DWORD dst_unused:UNUSED_PAD src0_sel:WORD_1 src1_sel:DWORD
	s_waitcnt lgkmcnt(2)
	v_and_b32_sdwa v12, v6, v124 dst_sel:DWORD dst_unused:UNUSED_PAD src0_sel:WORD_1 src1_sel:DWORD
	v_add3_u32 v6, v6, v12, s89
	v_and_b32_sdwa v12, v7, v124 dst_sel:DWORD dst_unused:UNUSED_PAD src0_sel:WORD_1 src1_sel:DWORD
	v_add3_u32 v4, v4, v13, s89
	v_and_b32_sdwa v13, v5, v124 dst_sel:DWORD dst_unused:UNUSED_PAD src0_sel:WORD_1 src1_sel:DWORD
	v_add3_u32 v7, v7, v12, s89
	v_add3_u32 v5, v5, v13, s89
	v_and_b32_e32 v7, 0xffff0000, v7
	v_and_b32_e32 v12, 0xffff0000, v5
	v_or_b32_sdwa v5, v7, v6 dst_sel:DWORD dst_unused:UNUSED_PAD src0_sel:DWORD src1_sel:WORD_1
	s_waitcnt lgkmcnt(0)
	v_and_b32_sdwa v6, v10, v124 dst_sel:DWORD dst_unused:UNUSED_PAD src0_sel:WORD_1 src1_sel:DWORD
	v_and_b32_sdwa v7, v8, v124 dst_sel:DWORD dst_unused:UNUSED_PAD src0_sel:WORD_1 src1_sel:DWORD
	v_add3_u32 v8, v8, v7, s89
	v_add3_u32 v6, v10, v6, s89
	v_and_b32_sdwa v7, v11, v124 dst_sel:DWORD dst_unused:UNUSED_PAD src0_sel:WORD_1 src1_sel:DWORD
	v_and_b32_sdwa v10, v9, v124 dst_sel:DWORD dst_unused:UNUSED_PAD src0_sel:WORD_1 src1_sel:DWORD
	v_add3_u32 v7, v11, v7, s89
	v_add3_u32 v9, v9, v10, s89
	v_and_b32_e32 v7, 0xffff0000, v7
	v_and_b32_e32 v9, 0xffff0000, v9
	v_or_b32_sdwa v7, v7, v6 dst_sel:DWORD dst_unused:UNUSED_PAD src0_sel:DWORD src1_sel:WORD_1
	v_or_b32_sdwa v6, v9, v8 dst_sel:DWORD dst_unused:UNUSED_PAD src0_sel:DWORD src1_sel:WORD_1
	v_or_b32_e32 v8, s18, v119
	v_lshlrev_b32_e32 v8, 12, v8
	v_mov_b32_e32 v9, v75
	v_or_b32_sdwa v4, v12, v4 dst_sel:DWORD dst_unused:UNUSED_PAD src0_sel:DWORD src1_sel:WORD_1
	v_lshl_add_u64 v[8:9], v[2:3], 0, v[8:9]
	global_store_dwordx4 v[8:9], v[4:7], off
	v_add_u32_e32 v8, 0x28b0, v123
	v_add_u32_e32 v10, 0x28b8, v123
	v_add_u32_e32 v4, 0x28a0, v123
	v_add_u32_e32 v6, 0x28a8, v123
	ds_read2_b32 v[4:5], v4 offset1:1
	ds_read2_b32 v[6:7], v6 offset1:1
	ds_read2_b32 v[8:9], v8 offset1:1
	ds_read2_b32 v[10:11], v10 offset1:1
	s_waitcnt lgkmcnt(3)
	v_and_b32_sdwa v13, v4, v124 dst_sel:DWORD dst_unused:UNUSED_PAD src0_sel:WORD_1 src1_sel:DWORD
	s_waitcnt lgkmcnt(2)
	v_and_b32_sdwa v12, v6, v124 dst_sel:DWORD dst_unused:UNUSED_PAD src0_sel:WORD_1 src1_sel:DWORD
	v_add3_u32 v6, v6, v12, s89
	v_and_b32_sdwa v12, v7, v124 dst_sel:DWORD dst_unused:UNUSED_PAD src0_sel:WORD_1 src1_sel:DWORD
	v_add3_u32 v4, v4, v13, s89
	v_and_b32_sdwa v13, v5, v124 dst_sel:DWORD dst_unused:UNUSED_PAD src0_sel:WORD_1 src1_sel:DWORD
	v_add3_u32 v7, v7, v12, s89
	v_add3_u32 v5, v5, v13, s89
	v_and_b32_e32 v7, 0xffff0000, v7
	v_and_b32_e32 v12, 0xffff0000, v5
	v_or_b32_sdwa v5, v7, v6 dst_sel:DWORD dst_unused:UNUSED_PAD src0_sel:DWORD src1_sel:WORD_1
	s_waitcnt lgkmcnt(0)
	v_and_b32_sdwa v6, v10, v124 dst_sel:DWORD dst_unused:UNUSED_PAD src0_sel:WORD_1 src1_sel:DWORD
	v_and_b32_sdwa v7, v8, v124 dst_sel:DWORD dst_unused:UNUSED_PAD src0_sel:WORD_1 src1_sel:DWORD
	v_add3_u32 v8, v8, v7, s89
	v_add3_u32 v6, v10, v6, s89
	v_and_b32_sdwa v7, v11, v124 dst_sel:DWORD dst_unused:UNUSED_PAD src0_sel:WORD_1 src1_sel:DWORD
	v_and_b32_sdwa v10, v9, v124 dst_sel:DWORD dst_unused:UNUSED_PAD src0_sel:WORD_1 src1_sel:DWORD
	v_add3_u32 v7, v11, v7, s89
	v_add3_u32 v9, v9, v10, s89
	v_and_b32_e32 v7, 0xffff0000, v7
	v_and_b32_e32 v9, 0xffff0000, v9
	v_or_b32_sdwa v7, v7, v6 dst_sel:DWORD dst_unused:UNUSED_PAD src0_sel:DWORD src1_sel:WORD_1
	v_or_b32_sdwa v6, v9, v8 dst_sel:DWORD dst_unused:UNUSED_PAD src0_sel:DWORD src1_sel:WORD_1
	v_or_b32_e32 v8, s18, v120
	v_lshlrev_b32_e32 v8, 12, v8
	v_mov_b32_e32 v9, v75
	v_or_b32_sdwa v4, v12, v4 dst_sel:DWORD dst_unused:UNUSED_PAD src0_sel:DWORD src1_sel:WORD_1
	v_lshl_add_u64 v[8:9], v[2:3], 0, v[8:9]
	global_store_dwordx4 v[8:9], v[4:7], off
	v_add_u32_e32 v8, 0x30d0, v123
	v_add_u32_e32 v10, 0x30d8, v123
	v_add_u32_e32 v4, 0x30c0, v123
	v_add_u32_e32 v6, 0x30c8, v123
	ds_read2_b32 v[4:5], v4 offset1:1
	ds_read2_b32 v[6:7], v6 offset1:1
	ds_read2_b32 v[8:9], v8 offset1:1
	ds_read2_b32 v[10:11], v10 offset1:1
	s_waitcnt lgkmcnt(3)
	v_and_b32_sdwa v13, v4, v124 dst_sel:DWORD dst_unused:UNUSED_PAD src0_sel:WORD_1 src1_sel:DWORD
	s_waitcnt lgkmcnt(2)
	v_and_b32_sdwa v12, v6, v124 dst_sel:DWORD dst_unused:UNUSED_PAD src0_sel:WORD_1 src1_sel:DWORD
	v_add3_u32 v6, v6, v12, s89
	v_and_b32_sdwa v12, v7, v124 dst_sel:DWORD dst_unused:UNUSED_PAD src0_sel:WORD_1 src1_sel:DWORD
	v_add3_u32 v4, v4, v13, s89
	v_and_b32_sdwa v13, v5, v124 dst_sel:DWORD dst_unused:UNUSED_PAD src0_sel:WORD_1 src1_sel:DWORD
	v_add3_u32 v7, v7, v12, s89
	v_add3_u32 v5, v5, v13, s89
	v_and_b32_e32 v7, 0xffff0000, v7
	v_and_b32_e32 v12, 0xffff0000, v5
	v_or_b32_sdwa v5, v7, v6 dst_sel:DWORD dst_unused:UNUSED_PAD src0_sel:DWORD src1_sel:WORD_1
	s_waitcnt lgkmcnt(0)
	v_and_b32_sdwa v6, v10, v124 dst_sel:DWORD dst_unused:UNUSED_PAD src0_sel:WORD_1 src1_sel:DWORD
	v_and_b32_sdwa v7, v8, v124 dst_sel:DWORD dst_unused:UNUSED_PAD src0_sel:WORD_1 src1_sel:DWORD
	v_add3_u32 v8, v8, v7, s89
	v_add3_u32 v6, v10, v6, s89
	v_and_b32_sdwa v7, v11, v124 dst_sel:DWORD dst_unused:UNUSED_PAD src0_sel:WORD_1 src1_sel:DWORD
	v_and_b32_sdwa v10, v9, v124 dst_sel:DWORD dst_unused:UNUSED_PAD src0_sel:WORD_1 src1_sel:DWORD
	v_add3_u32 v7, v11, v7, s89
	v_add3_u32 v9, v9, v10, s89
	v_and_b32_e32 v7, 0xffff0000, v7
	v_and_b32_e32 v9, 0xffff0000, v9
	v_or_b32_sdwa v7, v7, v6 dst_sel:DWORD dst_unused:UNUSED_PAD src0_sel:DWORD src1_sel:WORD_1
	v_or_b32_sdwa v6, v9, v8 dst_sel:DWORD dst_unused:UNUSED_PAD src0_sel:DWORD src1_sel:WORD_1
	v_or_b32_e32 v8, s18, v121
	v_lshlrev_b32_e32 v8, 12, v8
	v_mov_b32_e32 v9, v75
	v_or_b32_sdwa v4, v12, v4 dst_sel:DWORD dst_unused:UNUSED_PAD src0_sel:DWORD src1_sel:WORD_1
	v_lshl_add_u64 v[8:9], v[2:3], 0, v[8:9]
	global_store_dwordx4 v[8:9], v[4:7], off
	v_add_u32_e32 v8, 0x38f0, v123
	v_add_u32_e32 v10, 0x38f8, v123
	v_add_u32_e32 v4, 0x38e0, v123
	v_add_u32_e32 v6, 0x38e8, v123
	ds_read2_b32 v[4:5], v4 offset1:1
	ds_read2_b32 v[6:7], v6 offset1:1
	ds_read2_b32 v[8:9], v8 offset1:1
	ds_read2_b32 v[10:11], v10 offset1:1
	s_waitcnt lgkmcnt(3)
	v_and_b32_sdwa v13, v4, v124 dst_sel:DWORD dst_unused:UNUSED_PAD src0_sel:WORD_1 src1_sel:DWORD
	s_waitcnt lgkmcnt(2)
	v_and_b32_sdwa v12, v6, v124 dst_sel:DWORD dst_unused:UNUSED_PAD src0_sel:WORD_1 src1_sel:DWORD
	v_add3_u32 v6, v6, v12, s89
	v_and_b32_sdwa v12, v7, v124 dst_sel:DWORD dst_unused:UNUSED_PAD src0_sel:WORD_1 src1_sel:DWORD
	v_add3_u32 v4, v4, v13, s89
	v_and_b32_sdwa v13, v5, v124 dst_sel:DWORD dst_unused:UNUSED_PAD src0_sel:WORD_1 src1_sel:DWORD
	v_add3_u32 v7, v7, v12, s89
	v_add3_u32 v5, v5, v13, s89
	v_and_b32_e32 v7, 0xffff0000, v7
	v_and_b32_e32 v12, 0xffff0000, v5
	v_or_b32_sdwa v5, v7, v6 dst_sel:DWORD dst_unused:UNUSED_PAD src0_sel:DWORD src1_sel:WORD_1
	s_waitcnt lgkmcnt(0)
	v_and_b32_sdwa v6, v10, v124 dst_sel:DWORD dst_unused:UNUSED_PAD src0_sel:WORD_1 src1_sel:DWORD
	v_and_b32_sdwa v7, v8, v124 dst_sel:DWORD dst_unused:UNUSED_PAD src0_sel:WORD_1 src1_sel:DWORD
	v_add3_u32 v8, v8, v7, s89
	v_add3_u32 v6, v10, v6, s89
	v_and_b32_sdwa v7, v11, v124 dst_sel:DWORD dst_unused:UNUSED_PAD src0_sel:WORD_1 src1_sel:DWORD
	v_and_b32_sdwa v10, v9, v124 dst_sel:DWORD dst_unused:UNUSED_PAD src0_sel:WORD_1 src1_sel:DWORD
	v_add3_u32 v7, v11, v7, s89
	v_add3_u32 v9, v9, v10, s89
	v_and_b32_e32 v7, 0xffff0000, v7
	v_and_b32_e32 v9, 0xffff0000, v9
	v_or_b32_sdwa v7, v7, v6 dst_sel:DWORD dst_unused:UNUSED_PAD src0_sel:DWORD src1_sel:WORD_1
	v_or_b32_sdwa v6, v9, v8 dst_sel:DWORD dst_unused:UNUSED_PAD src0_sel:DWORD src1_sel:WORD_1
	v_or_b32_e32 v8, s18, v122
	v_lshlrev_b32_e32 v8, 12, v8
	v_mov_b32_e32 v9, v75
	v_or_b32_sdwa v4, v12, v4 dst_sel:DWORD dst_unused:UNUSED_PAD src0_sel:DWORD src1_sel:WORD_1
	v_lshl_add_u64 v[2:3], v[2:3], 0, v[8:9]
	global_store_dwordx4 v[2:3], v[4:7], off
	s_waitcnt lgkmcnt(0)

.LBB0_55:
	s_andn2_b64 vcc, exec, s[2:3]
	s_cbranch_vccnz .LBB0_81
	s_add_i32 s2, s85, 0x7000
	s_and_b32 s18, s2, 0x1ffc0
	s_and_b32 s19, s21, 0x7c0
	v_or_b32_e32 v66, s18, v72
	s_lshl_b32 s14, s19, 2
	v_lshl_add_u64 v[2:3], v[86:87], 0, s[14:15]
	v_lshlrev_b32_e32 v4, 13, v66
	v_mov_b32_e32 v5, v75
	v_lshl_add_u64 v[2:3], v[2:3], 0, v[4:5]
	v_add_co_u32_e32 v4, vcc, 0x8000, v2
	v_cndmask_b32_e64 v67, 0, 1, s[6:7]
	s_nop 0
	v_addc_co_u32_e32 v5, vcc, 0, v3, vcc
	global_load_dwordx4 v[58:61], v[2:3], off nt
	global_load_dwordx4 v[62:65], v[4:5], off nt
	v_add_co_u32_e32 v4, vcc, 0x10000, v2
	v_cmp_ne_u32_e64 s[2:3], 1, v67
	s_nop 0
	v_addc_co_u32_e32 v5, vcc, 0, v3, vcc
	v_add_co_u32_e32 v6, vcc, 0x18000, v2
	v_add_lshl_u32 v127, s18, v72, 2
	s_nop 0
	v_addc_co_u32_e32 v7, vcc, 0, v3, vcc
	global_load_dwordx4 v[50:53], v[4:5], off nt
	global_load_dwordx4 v[54:57], v[6:7], off nt
	v_add_co_u32_e32 v4, vcc, 0x20000, v2
	s_nop 1
	v_addc_co_u32_e32 v5, vcc, 0, v3, vcc
	v_add_co_u32_e32 v6, vcc, 0x28000, v2
	s_nop 1
	v_addc_co_u32_e32 v7, vcc, 0, v3, vcc
	global_load_dwordx4 v[42:45], v[4:5], off nt
	global_load_dwordx4 v[46:49], v[6:7], off nt
	v_add_co_u32_e32 v4, vcc, 0x30000, v2
	s_nop 1
	v_addc_co_u32_e32 v5, vcc, 0, v3, vcc
	v_add_co_u32_e32 v6, vcc, 0x38000, v2
	s_nop 1
	v_addc_co_u32_e32 v7, vcc, 0, v3, vcc
	global_load_dwordx4 v[34:37], v[4:5], off nt
	global_load_dwordx4 v[38:41], v[6:7], off nt
	v_add_co_u32_e32 v4, vcc, 0x40000, v2
	s_nop 1
	v_addc_co_u32_e32 v5, vcc, 0, v3, vcc
	v_add_co_u32_e32 v6, vcc, 0x48000, v2
	s_nop 1
	v_addc_co_u32_e32 v7, vcc, 0, v3, vcc
	global_load_dwordx4 v[26:29], v[4:5], off nt
	global_load_dwordx4 v[30:33], v[6:7], off nt
	v_add_co_u32_e32 v4, vcc, 0x50000, v2
	s_nop 1
	v_addc_co_u32_e32 v5, vcc, 0, v3, vcc
	v_add_co_u32_e32 v6, vcc, 0x58000, v2
	s_nop 1
	v_addc_co_u32_e32 v7, vcc, 0, v3, vcc
	global_load_dwordx4 v[18:21], v[4:5], off nt
	global_load_dwordx4 v[22:25], v[6:7], off nt
	v_add_co_u32_e32 v4, vcc, 0x60000, v2
	s_nop 1
	v_addc_co_u32_e32 v5, vcc, 0, v3, vcc
	v_add_co_u32_e32 v6, vcc, 0x68000, v2
	s_nop 1
	v_addc_co_u32_e32 v7, vcc, 0, v3, vcc
	global_load_dwordx4 v[10:13], v[4:5], off nt
	global_load_dwordx4 v[14:17], v[6:7], off nt
	v_add_co_u32_e32 v4, vcc, 0x70000, v2
	s_nop 1
	v_addc_co_u32_e32 v5, vcc, 0, v3, vcc
	v_add_co_u32_e32 v6, vcc, 0x78000, v2
	s_nop 1
	v_addc_co_u32_e32 v7, vcc, 0, v3, vcc
	global_load_dwordx4 v[2:5], v[4:5], off nt
	s_nop 0
	global_load_dwordx4 v[6:9], v[6:7], off nt
	s_andn2_b64 vcc, exec, s[6:7]
	s_cbranch_vccnz .LBB0_156
	v_lshlrev_b32_e32 v66, 2, v66
	global_load_dword v66, v66, s[42:43]
	s_nop 0
	global_load_dword v128, v127, s[42:43] offset:16
	s_waitcnt vmcnt(1)
	v_pk_mul_f32 v[60:61], v[60:61], v[66:67] op_sel_hi:[1,0]
	v_pk_mul_f32 v[58:59], v[58:59], v[66:67] op_sel_hi:[1,0]
	s_waitcnt vmcnt(0)
	v_pk_mul_f32 v[68:69], v[64:65], v[128:129] op_sel_hi:[1,0]
	v_pk_mul_f32 v[66:67], v[62:63], v[128:129] op_sel_hi:[1,0]
	s_cbranch_execnz .LBB0_59

.LBB0_82:
	s_andn2_b64 vcc, exec, s[2:3]
	s_cbranch_vccnz .LBB0_108
	s_add_i32 s2, s85, 0x7800
	s_and_b32 s18, s2, 0x1ffc0
	s_and_b32 s19, s21, 0x7c0
	v_or_b32_e32 v66, s18, v72
	s_lshl_b32 s14, s19, 2
	v_lshl_add_u64 v[2:3], v[90:91], 0, s[14:15]
	v_lshlrev_b32_e32 v4, 13, v66
	v_mov_b32_e32 v5, v75
	v_lshl_add_u64 v[2:3], v[2:3], 0, v[4:5]
	v_add_co_u32_e32 v4, vcc, 0x8000, v2
	v_cndmask_b32_e64 v67, 0, 1, s[6:7]
	s_nop 0
	v_addc_co_u32_e32 v5, vcc, 0, v3, vcc
	global_load_dwordx4 v[58:61], v[2:3], off nt
	global_load_dwordx4 v[62:65], v[4:5], off nt
	v_add_co_u32_e32 v4, vcc, 0x10000, v2
	v_cmp_ne_u32_e64 s[2:3], 1, v67
	s_nop 0
	v_addc_co_u32_e32 v5, vcc, 0, v3, vcc
	v_add_co_u32_e32 v6, vcc, 0x18000, v2
	v_add_lshl_u32 v127, s18, v72, 2
	s_nop 0
	v_addc_co_u32_e32 v7, vcc, 0, v3, vcc
	global_load_dwordx4 v[50:53], v[4:5], off nt
	global_load_dwordx4 v[54:57], v[6:7], off nt
	v_add_co_u32_e32 v4, vcc, 0x20000, v2
	s_nop 1
	v_addc_co_u32_e32 v5, vcc, 0, v3, vcc
	v_add_co_u32_e32 v6, vcc, 0x28000, v2
	s_nop 1
	v_addc_co_u32_e32 v7, vcc, 0, v3, vcc
	global_load_dwordx4 v[42:45], v[4:5], off nt
	global_load_dwordx4 v[46:49], v[6:7], off nt
	v_add_co_u32_e32 v4, vcc, 0x30000, v2
	s_nop 1
	v_addc_co_u32_e32 v5, vcc, 0, v3, vcc
	v_add_co_u32_e32 v6, vcc, 0x38000, v2
	s_nop 1
	v_addc_co_u32_e32 v7, vcc, 0, v3, vcc
	global_load_dwordx4 v[34:37], v[4:5], off nt
	global_load_dwordx4 v[38:41], v[6:7], off nt
	v_add_co_u32_e32 v4, vcc, 0x40000, v2
	s_nop 1
	v_addc_co_u32_e32 v5, vcc, 0, v3, vcc
	v_add_co_u32_e32 v6, vcc, 0x48000, v2
	s_nop 1
	v_addc_co_u32_e32 v7, vcc, 0, v3, vcc
	global_load_dwordx4 v[26:29], v[4:5], off nt
	global_load_dwordx4 v[30:33], v[6:7], off nt
	v_add_co_u32_e32 v4, vcc, 0x50000, v2
	s_nop 1
	v_addc_co_u32_e32 v5, vcc, 0, v3, vcc
	v_add_co_u32_e32 v6, vcc, 0x58000, v2
	s_nop 1
	v_addc_co_u32_e32 v7, vcc, 0, v3, vcc
	global_load_dwordx4 v[18:21], v[4:5], off nt
	global_load_dwordx4 v[22:25], v[6:7], off nt
	v_add_co_u32_e32 v4, vcc, 0x60000, v2
	s_nop 1
	v_addc_co_u32_e32 v5, vcc, 0, v3, vcc
	v_add_co_u32_e32 v6, vcc, 0x68000, v2
	s_nop 1
	v_addc_co_u32_e32 v7, vcc, 0, v3, vcc
	global_load_dwordx4 v[10:13], v[4:5], off nt
	global_load_dwordx4 v[14:17], v[6:7], off nt
	v_add_co_u32_e32 v4, vcc, 0x70000, v2
	s_nop 1
	v_addc_co_u32_e32 v5, vcc, 0, v3, vcc
	v_add_co_u32_e32 v6, vcc, 0x78000, v2
	s_nop 1
	v_addc_co_u32_e32 v7, vcc, 0, v3, vcc
	global_load_dwordx4 v[2:5], v[4:5], off nt
	s_nop 0
	global_load_dwordx4 v[6:9], v[6:7], off nt
	s_andn2_b64 vcc, exec, s[6:7]
	s_cbranch_vccnz .LBB0_148
	v_lshlrev_b32_e32 v66, 2, v66
	global_load_dword v66, v66, s[42:43]
	s_nop 0
	global_load_dword v128, v127, s[42:43] offset:16
	s_waitcnt vmcnt(1)
	v_pk_mul_f32 v[60:61], v[60:61], v[66:67] op_sel_hi:[1,0]
	v_pk_mul_f32 v[58:59], v[58:59], v[66:67] op_sel_hi:[1,0]
	s_waitcnt vmcnt(0)
	v_pk_mul_f32 v[68:69], v[64:65], v[128:129] op_sel_hi:[1,0]
	v_pk_mul_f32 v[66:67], v[62:63], v[128:129] op_sel_hi:[1,0]
	s_cbranch_execnz .LBB0_86

.LBB0_109:
	s_andn2_b64 vcc, exec, s[2:3]
	s_cbranch_vccnz .LBB0_111
	s_add_i32 s2, s85, 0x8000
	s_and_b32 s3, s2, 0x1ffc0
	s_and_b32 s2, s21, 0x7c0
	v_or_b32_e32 v54, s3, v72
	s_lshl_b32 s14, s2, 2
	v_lshl_add_u64 v[2:3], v[92:93], 0, s[14:15]
	v_lshlrev_b32_e32 v4, 13, v54
	v_mov_b32_e32 v5, v75
	v_lshl_add_u64 v[58:59], v[2:3], 0, v[4:5]
	v_add_co_u32_e32 v6, vcc, 0x8000, v58
	v_lshlrev_b32_e32 v54, 2, v54
	s_nop 0
	v_addc_co_u32_e32 v7, vcc, 0, v59, vcc
	v_add_co_u32_e32 v10, vcc, 0x10000, v58
	global_load_dwordx4 v[2:5], v[58:59], off nt
	s_nop 0
	global_load_dwordx4 v[6:9], v[6:7], off nt
	v_addc_co_u32_e32 v11, vcc, 0, v59, vcc
	v_add_co_u32_e32 v14, vcc, 0x18000, v58
	v_or_b32_e32 v61, s3, v101
	s_nop 0
	v_addc_co_u32_e32 v15, vcc, 0, v59, vcc
	v_add_co_u32_e32 v18, vcc, 0x20000, v58
	global_load_dwordx4 v[10:13], v[10:11], off nt
	s_nop 0
	global_load_dwordx4 v[14:17], v[14:15], off nt
	v_addc_co_u32_e32 v19, vcc, 0, v59, vcc
	v_add_co_u32_e32 v22, vcc, 0x28000, v58
	v_lshlrev_b32_e32 v61, 2, v61
	s_nop 0
	v_addc_co_u32_e32 v23, vcc, 0, v59, vcc
	v_add_co_u32_e32 v26, vcc, 0x30000, v58
	global_load_dwordx4 v[18:21], v[18:19], off nt
	s_nop 0
	global_load_dwordx4 v[22:25], v[22:23], off nt
	v_addc_co_u32_e32 v27, vcc, 0, v59, vcc
	v_add_co_u32_e32 v28, vcc, 0x38000, v58
	v_or_b32_e32 v63, s3, v106
	s_nop 0
	v_addc_co_u32_e32 v29, vcc, 0, v59, vcc
	v_add_co_u32_e32 v34, vcc, 0x40000, v58
	global_load_dwordx4 v[30:33], v[26:27], off nt
	s_nop 0
	global_load_dwordx4 v[26:29], v[28:29], off nt
	v_addc_co_u32_e32 v35, vcc, 0, v59, vcc
	v_add_co_u32_e32 v36, vcc, 0x48000, v58
	v_lshlrev_b32_e32 v63, 2, v63
	s_nop 0
	v_addc_co_u32_e32 v37, vcc, 0, v59, vcc
	v_add_co_u32_e32 v42, vcc, 0x50000, v58
	global_load_dwordx4 v[38:41], v[34:35], off nt
	s_nop 0
	global_load_dwordx4 v[34:37], v[36:37], off nt
	v_addc_co_u32_e32 v43, vcc, 0, v59, vcc
	v_add_co_u32_e32 v44, vcc, 0x58000, v58
	s_lshl_b32 s14, s3, 1
	s_nop 0
	v_addc_co_u32_e32 v45, vcc, 0, v59, vcc
	v_add_co_u32_e32 v50, vcc, 0x60000, v58
	global_load_dwordx4 v[46:49], v[42:43], off nt
	s_nop 0
	global_load_dwordx4 v[42:45], v[44:45], off nt
	v_addc_co_u32_e32 v51, vcc, 0, v59, vcc
	v_add_co_u32_e32 v52, vcc, 0x68000, v58
	global_load_dword v60, v54, s[16:17]
	v_or_b32_e32 v54, s3, v100
	v_addc_co_u32_e32 v53, vcc, 0, v59, vcc
	v_lshlrev_b32_e32 v54, 2, v54
	global_load_dword v62, v54, s[16:17]
	s_nop 0
	global_load_dwordx4 v[54:57], v[50:51], off nt
	s_nop 0
	global_load_dwordx4 v[50:53], v[52:53], off nt
	v_add_co_u32_e32 v64, vcc, 0x70000, v58
	global_load_dword v68, v61, s[16:17]
	v_or_b32_e32 v61, s3, v102
	v_lshlrev_b32_e32 v61, 2, v61
	global_load_dword v132, v61, s[16:17]
	v_or_b32_e32 v61, s3, v103
	v_lshlrev_b32_e32 v61, 2, v61
	global_load_dword v134, v61, s[16:17]
	v_or_b32_e32 v61, s3, v104
	v_lshlrev_b32_e32 v61, 2, v61
	global_load_dword v136, v61, s[16:17]
	v_or_b32_e32 v61, s3, v105
	v_lshlrev_b32_e32 v61, 2, v61
	global_load_dword v138, v61, s[16:17]
	global_load_dword v140, v63, s[16:17]
	v_or_b32_e32 v61, s3, v107
	v_lshlrev_b32_e32 v61, 2, v61
	v_or_b32_e32 v63, s3, v108
	v_lshlrev_b32_e32 v63, 2, v63
	global_load_dword v142, v61, s[16:17]
	global_load_dword v144, v63, s[16:17]
	v_or_b32_e32 v61, s3, v109
	v_lshlrev_b32_e32 v61, 2, v61
	v_or_b32_e32 v63, s3, v110
	v_lshlrev_b32_e32 v63, 2, v63
	global_load_dword v146, v61, s[16:17]
	global_load_dword v148, v63, s[16:17]
	v_or_b32_e32 v61, s3, v111
	v_addc_co_u32_e32 v65, vcc, 0, v59, vcc
	v_lshlrev_b32_e32 v61, 2, v61
	v_add_co_u32_e32 v58, vcc, 0x78000, v58
	global_load_dword v150, v61, s[16:17]
	v_or_b32_e32 v61, s3, v112
	v_addc_co_u32_e32 v59, vcc, 0, v59, vcc
	v_lshlrev_b32_e32 v61, 2, v61
	global_load_dword v152, v61, s[16:17]
	s_nop 0
	global_load_dwordx4 v[64:67], v[64:65], off nt
	s_nop 0
	global_load_dwordx4 v[128:131], v[58:59], off nt
	v_or_b32_e32 v58, s3, v113
	v_or_b32_e32 v59, s3, v114
	v_lshlrev_b32_e32 v58, 2, v58
	v_lshlrev_b32_e32 v59, 2, v59
	global_load_dword v58, v58, s[16:17]
	s_waitcnt vmcnt(18)
	v_pk_mul_f32 v[4:5], v[4:5], v[60:61] op_sel_hi:[1,0]
	global_load_dword v154, v59, s[16:17]
	v_pk_mul_f32 v[2:3], v[2:3], v[60:61] op_sel_hi:[1,0]
	s_waitcnt vmcnt(18)
	v_pk_mul_f32 v[8:9], v[8:9], v[62:63] op_sel_hi:[1,0]
	v_pk_mul_f32 v[6:7], v[6:7], v[62:63] op_sel_hi:[1,0]
	ds_write2_b32 v99, v2, v6 offset1:4
	ds_write2_b32 v99, v3, v7 offset0:65 offset1:69
	ds_write2_b32 v99, v4, v8 offset0:130 offset1:134
	ds_write2_b32 v99, v5, v9 offset0:195 offset1:199
	s_waitcnt vmcnt(15)
	v_pk_mul_f32 v[4:5], v[10:11], v[68:69] op_sel_hi:[1,0]
	v_pk_mul_f32 v[2:3], v[12:13], v[68:69] op_sel_hi:[1,0]
	s_waitcnt vmcnt(14)
	v_pk_mul_f32 v[8:9], v[14:15], v[132:133] op_sel_hi:[1,0]
	v_pk_mul_f32 v[6:7], v[16:17], v[132:133] op_sel_hi:[1,0]
	ds_write2_b32 v99, v4, v8 offset0:8 offset1:12
	ds_write2_b32 v99, v5, v9 offset0:73 offset1:77
	ds_write2_b32 v99, v2, v6 offset0:138 offset1:142
	ds_write2_b32 v99, v3, v7 offset0:203 offset1:207
	s_waitcnt vmcnt(13)
	v_pk_mul_f32 v[4:5], v[18:19], v[134:135] op_sel_hi:[1,0]
	v_pk_mul_f32 v[2:3], v[20:21], v[134:135] op_sel_hi:[1,0]
	s_waitcnt vmcnt(12)
	v_pk_mul_f32 v[8:9], v[22:23], v[136:137] op_sel_hi:[1,0]
	v_pk_mul_f32 v[6:7], v[24:25], v[136:137] op_sel_hi:[1,0]
	ds_write2_b32 v99, v4, v8 offset0:16 offset1:20
	ds_write2_b32 v99, v5, v9 offset0:81 offset1:85
	ds_write2_b32 v99, v2, v6 offset0:146 offset1:150
	ds_write2_b32 v99, v3, v7 offset0:211 offset1:215
	s_waitcnt vmcnt(11)
	v_pk_mul_f32 v[4:5], v[30:31], v[138:139] op_sel_hi:[1,0]
	s_waitcnt vmcnt(10)
	v_pk_mul_f32 v[8:9], v[26:27], v[140:141] op_sel_hi:[1,0]
	v_pk_mul_f32 v[2:3], v[32:33], v[138:139] op_sel_hi:[1,0]
	v_pk_mul_f32 v[6:7], v[28:29], v[140:141] op_sel_hi:[1,0]
	ds_write2_b32 v99, v4, v8 offset0:24 offset1:28
	ds_write2_b32 v99, v5, v9 offset0:89 offset1:93
	ds_write2_b32 v99, v2, v6 offset0:154 offset1:158
	ds_write2_b32 v99, v3, v7 offset0:219 offset1:223
	s_waitcnt vmcnt(9)
	v_pk_mul_f32 v[4:5], v[38:39], v[142:143] op_sel_hi:[1,0]
	s_waitcnt vmcnt(8)
	v_pk_mul_f32 v[8:9], v[34:35], v[144:145] op_sel_hi:[1,0]
	v_pk_mul_f32 v[2:3], v[40:41], v[142:143] op_sel_hi:[1,0]
	v_pk_mul_f32 v[6:7], v[36:37], v[144:145] op_sel_hi:[1,0]
	ds_write2_b32 v99, v4, v8 offset0:32 offset1:36
	ds_write2_b32 v99, v5, v9 offset0:97 offset1:101
	ds_write2_b32 v99, v2, v6 offset0:162 offset1:166
	ds_write2_b32 v99, v3, v7 offset0:227 offset1:231
	s_waitcnt vmcnt(7)
	v_pk_mul_f32 v[4:5], v[46:47], v[146:147] op_sel_hi:[1,0]
	s_waitcnt vmcnt(6)
	v_pk_mul_f32 v[8:9], v[42:43], v[148:149] op_sel_hi:[1,0]
	v_pk_mul_f32 v[2:3], v[48:49], v[146:147] op_sel_hi:[1,0]
	v_pk_mul_f32 v[6:7], v[44:45], v[148:149] op_sel_hi:[1,0]
	ds_write2_b32 v99, v4, v8 offset0:40 offset1:44
	ds_write2_b32 v99, v5, v9 offset0:105 offset1:109
	ds_write2_b32 v99, v2, v6 offset0:170 offset1:174
	ds_write2_b32 v99, v3, v7 offset0:235 offset1:239
	s_waitcnt vmcnt(5)
	v_pk_mul_f32 v[4:5], v[54:55], v[150:151] op_sel_hi:[1,0]
	v_pk_mul_f32 v[2:3], v[56:57], v[150:151] op_sel_hi:[1,0]
	s_waitcnt vmcnt(4)
	v_pk_mul_f32 v[8:9], v[50:51], v[152:153] op_sel_hi:[1,0]
	v_pk_mul_f32 v[6:7], v[52:53], v[152:153] op_sel_hi:[1,0]
	ds_write2_b32 v99, v4, v8 offset0:48 offset1:52
	ds_write2_b32 v99, v5, v9 offset0:113 offset1:117
	ds_write2_b32 v99, v2, v6 offset0:178 offset1:182
	ds_write2_b32 v99, v3, v7 offset0:243 offset1:247
	s_waitcnt vmcnt(1)
	v_pk_mul_f32 v[4:5], v[64:65], v[58:59] op_sel_hi:[1,0]
	v_pk_mul_f32 v[2:3], v[66:67], v[58:59] op_sel_hi:[1,0]
	s_waitcnt vmcnt(0)
	v_pk_mul_f32 v[8:9], v[128:129], v[154:155] op_sel_hi:[1,0]
	v_pk_mul_f32 v[6:7], v[130:131], v[154:155] op_sel_hi:[1,0]
	ds_write2_b32 v99, v4, v8 offset0:56 offset1:60
	ds_write2_b32 v99, v5, v9 offset0:121 offset1:125
	ds_write2_b32 v99, v2, v6 offset0:186 offset1:190
	ds_write2_b32 v99, v3, v7 offset0:251 offset1:255
	s_waitcnt lgkmcnt(0)
	ds_read2_b32 v[4:5], v123 offset1:1
	ds_read2_b32 v[6:7], v123 offset0:2 offset1:3
	ds_read2_b32 v[8:9], v123 offset0:4 offset1:5
	ds_read2_b32 v[10:11], v123 offset0:6 offset1:7
	v_lshl_add_u64 v[2:3], v[88:89], 0, s[14:15]
	s_waitcnt lgkmcnt(3)
	v_and_b32_sdwa v13, v4, v124 dst_sel:DWORD dst_unused:UNUSED_PAD src0_sel:WORD_1 src1_sel:DWORD
	s_waitcnt lgkmcnt(2)
	v_and_b32_sdwa v12, v6, v124 dst_sel:DWORD dst_unused:UNUSED_PAD src0_sel:WORD_1 src1_sel:DWORD
	v_add3_u32 v6, v6, v12, s89
	v_and_b32_sdwa v12, v7, v124 dst_sel:DWORD dst_unused:UNUSED_PAD src0_sel:WORD_1 src1_sel:DWORD
	v_add3_u32 v4, v4, v13, s89
	v_and_b32_sdwa v13, v5, v124 dst_sel:DWORD dst_unused:UNUSED_PAD src0_sel:WORD_1 src1_sel:DWORD
	v_add3_u32 v7, v7, v12, s89
	v_add3_u32 v5, v5, v13, s89
	v_and_b32_e32 v7, 0xffff0000, v7
	v_and_b32_e32 v12, 0xffff0000, v5
	v_or_b32_sdwa v5, v7, v6 dst_sel:DWORD dst_unused:UNUSED_PAD src0_sel:DWORD src1_sel:WORD_1
	s_waitcnt lgkmcnt(0)
	v_and_b32_sdwa v6, v10, v124 dst_sel:DWORD dst_unused:UNUSED_PAD src0_sel:WORD_1 src1_sel:DWORD
	v_and_b32_sdwa v7, v8, v124 dst_sel:DWORD dst_unused:UNUSED_PAD src0_sel:WORD_1 src1_sel:DWORD
	v_add3_u32 v8, v8, v7, s89
	v_add3_u32 v6, v10, v6, s89
	v_and_b32_sdwa v7, v11, v124 dst_sel:DWORD dst_unused:UNUSED_PAD src0_sel:WORD_1 src1_sel:DWORD
	v_and_b32_sdwa v10, v9, v124 dst_sel:DWORD dst_unused:UNUSED_PAD src0_sel:WORD_1 src1_sel:DWORD
	v_add3_u32 v7, v11, v7, s89
	v_add3_u32 v9, v9, v10, s89
	v_and_b32_e32 v7, 0xffff0000, v7
	v_and_b32_e32 v9, 0xffff0000, v9
	v_or_b32_sdwa v7, v7, v6 dst_sel:DWORD dst_unused:UNUSED_PAD src0_sel:DWORD src1_sel:WORD_1
	v_or_b32_sdwa v6, v9, v8 dst_sel:DWORD dst_unused:UNUSED_PAD src0_sel:DWORD src1_sel:WORD_1
	v_or_b32_e32 v8, s2, v115
	v_lshlrev_b32_e32 v8, 12, v8
	v_mov_b32_e32 v9, v75
	v_or_b32_sdwa v4, v12, v4 dst_sel:DWORD dst_unused:UNUSED_PAD src0_sel:DWORD src1_sel:WORD_1
	v_lshl_add_u64 v[8:9], v[2:3], 0, v[8:9]
	global_store_dwordx4 v[8:9], v[4:7], off
	ds_read2_b32 v[4:5], v125 offset1:1
	ds_read2_b32 v[6:7], v126 offset1:1
	v_add_u32_e32 v8, 0x830, v123
	v_add_u32_e32 v10, 0x838, v123
	ds_read2_b32 v[8:9], v8 offset1:1
	ds_read2_b32 v[10:11], v10 offset1:1
	s_waitcnt lgkmcnt(3)
	v_and_b32_sdwa v13, v4, v124 dst_sel:DWORD dst_unused:UNUSED_PAD src0_sel:WORD_1 src1_sel:DWORD
	s_waitcnt lgkmcnt(2)
	v_and_b32_sdwa v12, v6, v124 dst_sel:DWORD dst_unused:UNUSED_PAD src0_sel:WORD_1 src1_sel:DWORD
	v_add3_u32 v6, v6, v12, s89
	v_and_b32_sdwa v12, v7, v124 dst_sel:DWORD dst_unused:UNUSED_PAD src0_sel:WORD_1 src1_sel:DWORD
	v_add3_u32 v4, v4, v13, s89
	v_and_b32_sdwa v13, v5, v124 dst_sel:DWORD dst_unused:UNUSED_PAD src0_sel:WORD_1 src1_sel:DWORD
	v_add3_u32 v7, v7, v12, s89
	v_add3_u32 v5, v5, v13, s89
	v_and_b32_e32 v7, 0xffff0000, v7
	v_and_b32_e32 v12, 0xffff0000, v5
	v_or_b32_sdwa v5, v7, v6 dst_sel:DWORD dst_unused:UNUSED_PAD src0_sel:DWORD src1_sel:WORD_1
	s_waitcnt lgkmcnt(0)
	v_and_b32_sdwa v6, v10, v124 dst_sel:DWORD dst_unused:UNUSED_PAD src0_sel:WORD_1 src1_sel:DWORD
	v_and_b32_sdwa v7, v8, v124 dst_sel:DWORD dst_unused:UNUSED_PAD src0_sel:WORD_1 src1_sel:DWORD
	v_add3_u32 v8, v8, v7, s89
	v_add3_u32 v6, v10, v6, s89
	v_and_b32_sdwa v7, v11, v124 dst_sel:DWORD dst_unused:UNUSED_PAD src0_sel:WORD_1 src1_sel:DWORD
	v_and_b32_sdwa v10, v9, v124 dst_sel:DWORD dst_unused:UNUSED_PAD src0_sel:WORD_1 src1_sel:DWORD
	v_add3_u32 v7, v11, v7, s89
	v_add3_u32 v9, v9, v10, s89
	v_and_b32_e32 v7, 0xffff0000, v7
	v_and_b32_e32 v9, 0xffff0000, v9
	v_or_b32_sdwa v7, v7, v6 dst_sel:DWORD dst_unused:UNUSED_PAD src0_sel:DWORD src1_sel:WORD_1
	v_or_b32_sdwa v6, v9, v8 dst_sel:DWORD dst_unused:UNUSED_PAD src0_sel:DWORD src1_sel:WORD_1
	v_or_b32_e32 v8, s2, v116
	v_lshlrev_b32_e32 v8, 12, v8
	v_mov_b32_e32 v9, v75
	v_or_b32_sdwa v4, v12, v4 dst_sel:DWORD dst_unused:UNUSED_PAD src0_sel:DWORD src1_sel:WORD_1
	v_lshl_add_u64 v[8:9], v[2:3], 0, v[8:9]
	global_store_dwordx4 v[8:9], v[4:7], off
	v_add_u32_e32 v8, 0x1050, v123
	v_add_u32_e32 v10, 0x1058, v123
	v_add_u32_e32 v4, 0x1040, v123
	v_add_u32_e32 v6, 0x1048, v123
	ds_read2_b32 v[4:5], v4 offset1:1
	ds_read2_b32 v[6:7], v6 offset1:1
	ds_read2_b32 v[8:9], v8 offset1:1
	ds_read2_b32 v[10:11], v10 offset1:1
	s_waitcnt lgkmcnt(3)
	v_and_b32_sdwa v13, v4, v124 dst_sel:DWORD dst_unused:UNUSED_PAD src0_sel:WORD_1 src1_sel:DWORD
	s_waitcnt lgkmcnt(2)
	v_and_b32_sdwa v12, v6, v124 dst_sel:DWORD dst_unused:UNUSED_PAD src0_sel:WORD_1 src1_sel:DWORD
	v_add3_u32 v6, v6, v12, s89
	v_and_b32_sdwa v12, v7, v124 dst_sel:DWORD dst_unused:UNUSED_PAD src0_sel:WORD_1 src1_sel:DWORD
	v_add3_u32 v4, v4, v13, s89
	v_and_b32_sdwa v13, v5, v124 dst_sel:DWORD dst_unused:UNUSED_PAD src0_sel:WORD_1 src1_sel:DWORD
	v_add3_u32 v7, v7, v12, s89
	v_add3_u32 v5, v5, v13, s89
	v_and_b32_e32 v7, 0xffff0000, v7
	v_and_b32_e32 v12, 0xffff0000, v5
	v_or_b32_sdwa v5, v7, v6 dst_sel:DWORD dst_unused:UNUSED_PAD src0_sel:DWORD src1_sel:WORD_1
	s_waitcnt lgkmcnt(0)
	v_and_b32_sdwa v6, v10, v124 dst_sel:DWORD dst_unused:UNUSED_PAD src0_sel:WORD_1 src1_sel:DWORD
	v_and_b32_sdwa v7, v8, v124 dst_sel:DWORD dst_unused:UNUSED_PAD src0_sel:WORD_1 src1_sel:DWORD
	v_add3_u32 v8, v8, v7, s89
	v_add3_u32 v6, v10, v6, s89
	v_and_b32_sdwa v7, v11, v124 dst_sel:DWORD dst_unused:UNUSED_PAD src0_sel:WORD_1 src1_sel:DWORD
	v_and_b32_sdwa v10, v9, v124 dst_sel:DWORD dst_unused:UNUSED_PAD src0_sel:WORD_1 src1_sel:DWORD
	v_add3_u32 v7, v11, v7, s89
	v_add3_u32 v9, v9, v10, s89
	v_and_b32_e32 v7, 0xffff0000, v7
	v_and_b32_e32 v9, 0xffff0000, v9
	v_or_b32_sdwa v7, v7, v6 dst_sel:DWORD dst_unused:UNUSED_PAD src0_sel:DWORD src1_sel:WORD_1
	v_or_b32_sdwa v6, v9, v8 dst_sel:DWORD dst_unused:UNUSED_PAD src0_sel:DWORD src1_sel:WORD_1
	v_or_b32_e32 v8, s2, v117
	v_lshlrev_b32_e32 v8, 12, v8
	v_mov_b32_e32 v9, v75
	v_or_b32_sdwa v4, v12, v4 dst_sel:DWORD dst_unused:UNUSED_PAD src0_sel:DWORD src1_sel:WORD_1
	v_lshl_add_u64 v[8:9], v[2:3], 0, v[8:9]
	global_store_dwordx4 v[8:9], v[4:7], off
	v_add_u32_e32 v8, 0x1870, v123
	v_add_u32_e32 v10, 0x1878, v123
	v_add_u32_e32 v4, 0x1860, v123
	v_add_u32_e32 v6, 0x1868, v123
	ds_read2_b32 v[4:5], v4 offset1:1
	ds_read2_b32 v[6:7], v6 offset1:1
	ds_read2_b32 v[8:9], v8 offset1:1
	ds_read2_b32 v[10:11], v10 offset1:1
	s_waitcnt lgkmcnt(3)
	v_and_b32_sdwa v13, v4, v124 dst_sel:DWORD dst_unused:UNUSED_PAD src0_sel:WORD_1 src1_sel:DWORD
	s_waitcnt lgkmcnt(2)
	v_and_b32_sdwa v12, v6, v124 dst_sel:DWORD dst_unused:UNUSED_PAD src0_sel:WORD_1 src1_sel:DWORD
	v_add3_u32 v6, v6, v12, s89
	v_and_b32_sdwa v12, v7, v124 dst_sel:DWORD dst_unused:UNUSED_PAD src0_sel:WORD_1 src1_sel:DWORD
	v_add3_u32 v4, v4, v13, s89
	v_and_b32_sdwa v13, v5, v124 dst_sel:DWORD dst_unused:UNUSED_PAD src0_sel:WORD_1 src1_sel:DWORD
	v_add3_u32 v7, v7, v12, s89
	v_add3_u32 v5, v5, v13, s89
	v_and_b32_e32 v7, 0xffff0000, v7
	v_and_b32_e32 v12, 0xffff0000, v5
	v_or_b32_sdwa v5, v7, v6 dst_sel:DWORD dst_unused:UNUSED_PAD src0_sel:DWORD src1_sel:WORD_1
	s_waitcnt lgkmcnt(0)
	v_and_b32_sdwa v6, v10, v124 dst_sel:DWORD dst_unused:UNUSED_PAD src0_sel:WORD_1 src1_sel:DWORD
	v_and_b32_sdwa v7, v8, v124 dst_sel:DWORD dst_unused:UNUSED_PAD src0_sel:WORD_1 src1_sel:DWORD
	v_add3_u32 v8, v8, v7, s89
	v_add3_u32 v6, v10, v6, s89
	v_and_b32_sdwa v7, v11, v124 dst_sel:DWORD dst_unused:UNUSED_PAD src0_sel:WORD_1 src1_sel:DWORD
	v_and_b32_sdwa v10, v9, v124 dst_sel:DWORD dst_unused:UNUSED_PAD src0_sel:WORD_1 src1_sel:DWORD
	v_add3_u32 v7, v11, v7, s89
	v_add3_u32 v9, v9, v10, s89
	v_and_b32_e32 v7, 0xffff0000, v7
	v_and_b32_e32 v9, 0xffff0000, v9
	v_or_b32_sdwa v7, v7, v6 dst_sel:DWORD dst_unused:UNUSED_PAD src0_sel:DWORD src1_sel:WORD_1
	v_or_b32_sdwa v6, v9, v8 dst_sel:DWORD dst_unused:UNUSED_PAD src0_sel:DWORD src1_sel:WORD_1
	v_or_b32_e32 v8, s2, v118
	v_lshlrev_b32_e32 v8, 12, v8
	v_mov_b32_e32 v9, v75
	v_or_b32_sdwa v4, v12, v4 dst_sel:DWORD dst_unused:UNUSED_PAD src0_sel:DWORD src1_sel:WORD_1
	v_lshl_add_u64 v[8:9], v[2:3], 0, v[8:9]
	global_store_dwordx4 v[8:9], v[4:7], off
	v_add_u32_e32 v8, 0x2090, v123
	v_add_u32_e32 v10, 0x2098, v123
	v_add_u32_e32 v4, 0x2080, v123
	v_add_u32_e32 v6, 0x2088, v123
	ds_read2_b32 v[4:5], v4 offset1:1
	ds_read2_b32 v[6:7], v6 offset1:1
	ds_read2_b32 v[8:9], v8 offset1:1
	ds_read2_b32 v[10:11], v10 offset1:1
	s_waitcnt lgkmcnt(3)
	v_and_b32_sdwa v13, v4, v124 dst_sel:DWORD dst_unused:UNUSED_PAD src0_sel:WORD_1 src1_sel:DWORD
	s_waitcnt lgkmcnt(2)
	v_and_b32_sdwa v12, v6, v124 dst_sel:DWORD dst_unused:UNUSED_PAD src0_sel:WORD_1 src1_sel:DWORD
	v_add3_u32 v6, v6, v12, s89
	v_and_b32_sdwa v12, v7, v124 dst_sel:DWORD dst_unused:UNUSED_PAD src0_sel:WORD_1 src1_sel:DWORD
	v_add3_u32 v4, v4, v13, s89
	v_and_b32_sdwa v13, v5, v124 dst_sel:DWORD dst_unused:UNUSED_PAD src0_sel:WORD_1 src1_sel:DWORD
	v_add3_u32 v7, v7, v12, s89
	v_add3_u32 v5, v5, v13, s89
	v_and_b32_e32 v7, 0xffff0000, v7
	v_and_b32_e32 v12, 0xffff0000, v5
	v_or_b32_sdwa v5, v7, v6 dst_sel:DWORD dst_unused:UNUSED_PAD src0_sel:DWORD src1_sel:WORD_1
	s_waitcnt lgkmcnt(0)
	v_and_b32_sdwa v6, v10, v124 dst_sel:DWORD dst_unused:UNUSED_PAD src0_sel:WORD_1 src1_sel:DWORD
	v_and_b32_sdwa v7, v8, v124 dst_sel:DWORD dst_unused:UNUSED_PAD src0_sel:WORD_1 src1_sel:DWORD
	v_add3_u32 v8, v8, v7, s89
	v_add3_u32 v6, v10, v6, s89
	v_and_b32_sdwa v7, v11, v124 dst_sel:DWORD dst_unused:UNUSED_PAD src0_sel:WORD_1 src1_sel:DWORD
	v_and_b32_sdwa v10, v9, v124 dst_sel:DWORD dst_unused:UNUSED_PAD src0_sel:WORD_1 src1_sel:DWORD
	v_add3_u32 v7, v11, v7, s89
	v_add3_u32 v9, v9, v10, s89
	v_and_b32_e32 v7, 0xffff0000, v7
	v_and_b32_e32 v9, 0xffff0000, v9
	v_or_b32_sdwa v7, v7, v6 dst_sel:DWORD dst_unused:UNUSED_PAD src0_sel:DWORD src1_sel:WORD_1
	v_or_b32_sdwa v6, v9, v8 dst_sel:DWORD dst_unused:UNUSED_PAD src0_sel:DWORD src1_sel:WORD_1
	v_or_b32_e32 v8, s2, v119
	v_lshlrev_b32_e32 v8, 12, v8
	v_mov_b32_e32 v9, v75
	v_or_b32_sdwa v4, v12, v4 dst_sel:DWORD dst_unused:UNUSED_PAD src0_sel:DWORD src1_sel:WORD_1
	v_lshl_add_u64 v[8:9], v[2:3], 0, v[8:9]
	global_store_dwordx4 v[8:9], v[4:7], off
	v_add_u32_e32 v8, 0x28b0, v123
	v_add_u32_e32 v10, 0x28b8, v123
	v_add_u32_e32 v4, 0x28a0, v123
	v_add_u32_e32 v6, 0x28a8, v123
	ds_read2_b32 v[4:5], v4 offset1:1
	ds_read2_b32 v[6:7], v6 offset1:1
	ds_read2_b32 v[8:9], v8 offset1:1
	ds_read2_b32 v[10:11], v10 offset1:1
	s_waitcnt lgkmcnt(3)
	v_and_b32_sdwa v13, v4, v124 dst_sel:DWORD dst_unused:UNUSED_PAD src0_sel:WORD_1 src1_sel:DWORD
	s_waitcnt lgkmcnt(2)
	v_and_b32_sdwa v12, v6, v124 dst_sel:DWORD dst_unused:UNUSED_PAD src0_sel:WORD_1 src1_sel:DWORD
	v_add3_u32 v6, v6, v12, s89
	v_and_b32_sdwa v12, v7, v124 dst_sel:DWORD dst_unused:UNUSED_PAD src0_sel:WORD_1 src1_sel:DWORD
	v_add3_u32 v4, v4, v13, s89
	v_and_b32_sdwa v13, v5, v124 dst_sel:DWORD dst_unused:UNUSED_PAD src0_sel:WORD_1 src1_sel:DWORD
	v_add3_u32 v7, v7, v12, s89
	v_add3_u32 v5, v5, v13, s89
	v_and_b32_e32 v7, 0xffff0000, v7
	v_and_b32_e32 v12, 0xffff0000, v5
	v_or_b32_sdwa v5, v7, v6 dst_sel:DWORD dst_unused:UNUSED_PAD src0_sel:DWORD src1_sel:WORD_1
	s_waitcnt lgkmcnt(0)
	v_and_b32_sdwa v6, v10, v124 dst_sel:DWORD dst_unused:UNUSED_PAD src0_sel:WORD_1 src1_sel:DWORD
	v_and_b32_sdwa v7, v8, v124 dst_sel:DWORD dst_unused:UNUSED_PAD src0_sel:WORD_1 src1_sel:DWORD
	v_add3_u32 v8, v8, v7, s89
	v_add3_u32 v6, v10, v6, s89
	v_and_b32_sdwa v7, v11, v124 dst_sel:DWORD dst_unused:UNUSED_PAD src0_sel:WORD_1 src1_sel:DWORD
	v_and_b32_sdwa v10, v9, v124 dst_sel:DWORD dst_unused:UNUSED_PAD src0_sel:WORD_1 src1_sel:DWORD
	v_add3_u32 v7, v11, v7, s89
	v_add3_u32 v9, v9, v10, s89
	v_and_b32_e32 v7, 0xffff0000, v7
	v_and_b32_e32 v9, 0xffff0000, v9
	v_or_b32_sdwa v7, v7, v6 dst_sel:DWORD dst_unused:UNUSED_PAD src0_sel:DWORD src1_sel:WORD_1
	v_or_b32_sdwa v6, v9, v8 dst_sel:DWORD dst_unused:UNUSED_PAD src0_sel:DWORD src1_sel:WORD_1
	v_or_b32_e32 v8, s2, v120
	v_lshlrev_b32_e32 v8, 12, v8
	v_mov_b32_e32 v9, v75
	v_or_b32_sdwa v4, v12, v4 dst_sel:DWORD dst_unused:UNUSED_PAD src0_sel:DWORD src1_sel:WORD_1
	v_lshl_add_u64 v[8:9], v[2:3], 0, v[8:9]
	global_store_dwordx4 v[8:9], v[4:7], off
	v_add_u32_e32 v8, 0x30d0, v123
	v_add_u32_e32 v10, 0x30d8, v123
	v_add_u32_e32 v4, 0x30c0, v123
	v_add_u32_e32 v6, 0x30c8, v123
	ds_read2_b32 v[4:5], v4 offset1:1
	ds_read2_b32 v[6:7], v6 offset1:1
	ds_read2_b32 v[8:9], v8 offset1:1
	ds_read2_b32 v[10:11], v10 offset1:1
	s_waitcnt lgkmcnt(3)
	v_and_b32_sdwa v13, v4, v124 dst_sel:DWORD dst_unused:UNUSED_PAD src0_sel:WORD_1 src1_sel:DWORD
	s_waitcnt lgkmcnt(2)
	v_and_b32_sdwa v12, v6, v124 dst_sel:DWORD dst_unused:UNUSED_PAD src0_sel:WORD_1 src1_sel:DWORD
	v_add3_u32 v6, v6, v12, s89
	v_and_b32_sdwa v12, v7, v124 dst_sel:DWORD dst_unused:UNUSED_PAD src0_sel:WORD_1 src1_sel:DWORD
	v_add3_u32 v4, v4, v13, s89
	v_and_b32_sdwa v13, v5, v124 dst_sel:DWORD dst_unused:UNUSED_PAD src0_sel:WORD_1 src1_sel:DWORD
	v_add3_u32 v7, v7, v12, s89
	v_add3_u32 v5, v5, v13, s89
	v_and_b32_e32 v7, 0xffff0000, v7
	v_and_b32_e32 v12, 0xffff0000, v5
	v_or_b32_sdwa v5, v7, v6 dst_sel:DWORD dst_unused:UNUSED_PAD src0_sel:DWORD src1_sel:WORD_1
	s_waitcnt lgkmcnt(0)
	v_and_b32_sdwa v6, v10, v124 dst_sel:DWORD dst_unused:UNUSED_PAD src0_sel:WORD_1 src1_sel:DWORD
	v_and_b32_sdwa v7, v8, v124 dst_sel:DWORD dst_unused:UNUSED_PAD src0_sel:WORD_1 src1_sel:DWORD
	v_add3_u32 v8, v8, v7, s89
	v_add3_u32 v6, v10, v6, s89
	v_and_b32_sdwa v7, v11, v124 dst_sel:DWORD dst_unused:UNUSED_PAD src0_sel:WORD_1 src1_sel:DWORD
	v_and_b32_sdwa v10, v9, v124 dst_sel:DWORD dst_unused:UNUSED_PAD src0_sel:WORD_1 src1_sel:DWORD
	v_add3_u32 v7, v11, v7, s89
	v_add3_u32 v9, v9, v10, s89
	v_and_b32_e32 v7, 0xffff0000, v7
	v_and_b32_e32 v9, 0xffff0000, v9
	v_or_b32_sdwa v7, v7, v6 dst_sel:DWORD dst_unused:UNUSED_PAD src0_sel:DWORD src1_sel:WORD_1
	v_or_b32_sdwa v6, v9, v8 dst_sel:DWORD dst_unused:UNUSED_PAD src0_sel:DWORD src1_sel:WORD_1
	v_or_b32_e32 v8, s2, v121
	v_lshlrev_b32_e32 v8, 12, v8
	v_mov_b32_e32 v9, v75
	v_or_b32_sdwa v4, v12, v4 dst_sel:DWORD dst_unused:UNUSED_PAD src0_sel:DWORD src1_sel:WORD_1
	v_lshl_add_u64 v[8:9], v[2:3], 0, v[8:9]
	global_store_dwordx4 v[8:9], v[4:7], off
	v_add_u32_e32 v8, 0x38f0, v123
	v_add_u32_e32 v10, 0x38f8, v123
	v_add_u32_e32 v4, 0x38e0, v123
	v_add_u32_e32 v6, 0x38e8, v123
	ds_read2_b32 v[4:5], v4 offset1:1
	ds_read2_b32 v[6:7], v6 offset1:1
	ds_read2_b32 v[8:9], v8 offset1:1
	ds_read2_b32 v[10:11], v10 offset1:1
	s_waitcnt lgkmcnt(3)
	v_and_b32_sdwa v13, v4, v124 dst_sel:DWORD dst_unused:UNUSED_PAD src0_sel:WORD_1 src1_sel:DWORD
	s_waitcnt lgkmcnt(2)
	v_and_b32_sdwa v12, v6, v124 dst_sel:DWORD dst_unused:UNUSED_PAD src0_sel:WORD_1 src1_sel:DWORD
	v_add3_u32 v6, v6, v12, s89
	v_and_b32_sdwa v12, v7, v124 dst_sel:DWORD dst_unused:UNUSED_PAD src0_sel:WORD_1 src1_sel:DWORD
	v_add3_u32 v4, v4, v13, s89
	v_and_b32_sdwa v13, v5, v124 dst_sel:DWORD dst_unused:UNUSED_PAD src0_sel:WORD_1 src1_sel:DWORD
	v_add3_u32 v7, v7, v12, s89
	v_add3_u32 v5, v5, v13, s89
	v_and_b32_e32 v7, 0xffff0000, v7
	v_and_b32_e32 v12, 0xffff0000, v5
	v_or_b32_sdwa v5, v7, v6 dst_sel:DWORD dst_unused:UNUSED_PAD src0_sel:DWORD src1_sel:WORD_1
	s_waitcnt lgkmcnt(0)
	v_and_b32_sdwa v6, v10, v124 dst_sel:DWORD dst_unused:UNUSED_PAD src0_sel:WORD_1 src1_sel:DWORD
	v_and_b32_sdwa v7, v8, v124 dst_sel:DWORD dst_unused:UNUSED_PAD src0_sel:WORD_1 src1_sel:DWORD
	v_add3_u32 v8, v8, v7, s89
	v_add3_u32 v6, v10, v6, s89
	v_and_b32_sdwa v7, v11, v124 dst_sel:DWORD dst_unused:UNUSED_PAD src0_sel:WORD_1 src1_sel:DWORD
	v_and_b32_sdwa v10, v9, v124 dst_sel:DWORD dst_unused:UNUSED_PAD src0_sel:WORD_1 src1_sel:DWORD
	v_add3_u32 v7, v11, v7, s89
	v_add3_u32 v9, v9, v10, s89
	v_and_b32_e32 v7, 0xffff0000, v7
	v_and_b32_e32 v9, 0xffff0000, v9
	v_or_b32_sdwa v7, v7, v6 dst_sel:DWORD dst_unused:UNUSED_PAD src0_sel:DWORD src1_sel:WORD_1
	v_or_b32_sdwa v6, v9, v8 dst_sel:DWORD dst_unused:UNUSED_PAD src0_sel:DWORD src1_sel:WORD_1
	v_or_b32_e32 v8, s2, v122
	v_lshlrev_b32_e32 v8, 12, v8
	v_mov_b32_e32 v9, v75
	v_or_b32_sdwa v4, v12, v4 dst_sel:DWORD dst_unused:UNUSED_PAD src0_sel:DWORD src1_sel:WORD_1
	v_lshl_add_u64 v[2:3], v[2:3], 0, v[8:9]
	global_store_dwordx4 v[2:3], v[4:7], off
	s_waitcnt lgkmcnt(0)

.LBB0_112:
	s_andn2_b64 vcc, exec, s[2:3]
	s_cbranch_vccnz .LBB0_114
	s_add_i32 s14, s85, 0x8800
	s_and_b32 s19, s14, 0x1ffc0
	s_and_b32 s18, s21, 0x7c0
	v_or_b32_e32 v4, s19, v72
	s_lshl_b32 s14, s18, 2
	v_lshl_add_u64 v[2:3], v[94:95], 0, s[14:15]
	v_lshlrev_b32_e32 v4, 13, v4
	v_mov_b32_e32 v5, v75
	v_lshl_add_u64 v[58:59], v[2:3], 0, v[4:5]
	v_add_co_u32_e32 v6, vcc, 0x8000, v58
	s_mov_b64 s[2:3], s[28:29]
	s_nop 0
	v_addc_co_u32_e32 v7, vcc, 0, v59, vcc
	v_add_co_u32_e32 v10, vcc, 0x10000, v58
	global_load_dwordx4 v[2:5], v[58:59], off nt
	s_nop 0
	global_load_dwordx4 v[6:9], v[6:7], off nt
	v_addc_co_u32_e32 v11, vcc, 0, v59, vcc
	v_add_co_u32_e32 v14, vcc, 0x18000, v58
	s_lshl_b32 s14, s19, 1
	s_nop 0
	v_addc_co_u32_e32 v15, vcc, 0, v59, vcc
	v_add_co_u32_e32 v18, vcc, 0x20000, v58
	global_load_dwordx4 v[10:13], v[10:11], off nt
	s_nop 0
	global_load_dwordx4 v[14:17], v[14:15], off nt
	v_addc_co_u32_e32 v19, vcc, 0, v59, vcc
	v_add_co_u32_e32 v22, vcc, 0x28000, v58
	s_add_u32 s2, s2, s14
	s_nop 0
	v_addc_co_u32_e32 v23, vcc, 0, v59, vcc
	v_add_co_u32_e32 v26, vcc, 0x30000, v58
	global_load_dwordx4 v[18:21], v[18:19], off nt
	s_nop 0
	global_load_dwordx4 v[22:25], v[22:23], off nt
	v_addc_co_u32_e32 v27, vcc, 0, v59, vcc
	v_add_co_u32_e32 v30, vcc, 0x38000, v58
	s_addc_u32 s3, s3, 0
	s_nop 0
	v_addc_co_u32_e32 v31, vcc, 0, v59, vcc
	v_add_co_u32_e32 v34, vcc, 0x40000, v58
	global_load_dwordx4 v[26:29], v[26:27], off nt
	s_nop 0
	global_load_dwordx4 v[30:33], v[30:31], off nt
	v_addc_co_u32_e32 v35, vcc, 0, v59, vcc
	v_add_co_u32_e32 v38, vcc, 0x48000, v58
	s_nop 1
	v_addc_co_u32_e32 v39, vcc, 0, v59, vcc
	v_add_co_u32_e32 v42, vcc, 0x50000, v58
	global_load_dwordx4 v[34:37], v[34:35], off nt
	s_nop 0
	global_load_dwordx4 v[38:41], v[38:39], off nt
	v_addc_co_u32_e32 v43, vcc, 0, v59, vcc
	v_add_co_u32_e32 v46, vcc, 0x58000, v58
	s_nop 1
	v_addc_co_u32_e32 v47, vcc, 0, v59, vcc
	v_add_co_u32_e32 v50, vcc, 0x60000, v58
	global_load_dwordx4 v[42:45], v[42:43], off nt
	s_nop 0
	global_load_dwordx4 v[46:49], v[46:47], off nt
	v_addc_co_u32_e32 v51, vcc, 0, v59, vcc
	v_add_co_u32_e32 v54, vcc, 0x68000, v58
	s_nop 1
	v_addc_co_u32_e32 v55, vcc, 0, v59, vcc
	v_add_co_u32_e32 v60, vcc, 0x70000, v58
	global_load_dwordx4 v[50:53], v[50:51], off nt
	s_nop 0
	global_load_dwordx4 v[54:57], v[54:55], off nt
	v_addc_co_u32_e32 v61, vcc, 0, v59, vcc
	v_add_co_u32_e32 v62, vcc, 0x78000, v58
	s_nop 1
	v_addc_co_u32_e32 v63, vcc, 0, v59, vcc
	global_load_dwordx4 v[58:61], v[60:61], off nt
	s_nop 0
	global_load_dwordx4 v[62:65], v[62:63], off nt
	s_waitcnt vmcnt(14)
	ds_write2_b32 v99, v2, v6 offset1:4
	ds_write2_b32 v99, v3, v7 offset0:65 offset1:69
	ds_write2_b32 v99, v4, v8 offset0:130 offset1:134
	ds_write2_b32 v99, v5, v9 offset0:195 offset1:199
	s_waitcnt vmcnt(12)
	ds_write2_b32 v99, v10, v14 offset0:8 offset1:12
	ds_write2_b32 v99, v11, v15 offset0:73 offset1:77
	ds_write2_b32 v99, v12, v16 offset0:138 offset1:142
	ds_write2_b32 v99, v13, v17 offset0:203 offset1:207
	s_waitcnt vmcnt(10)
	ds_write2_b32 v99, v18, v22 offset0:16 offset1:20
	ds_write2_b32 v99, v19, v23 offset0:81 offset1:85
	ds_write2_b32 v99, v20, v24 offset0:146 offset1:150
	ds_write2_b32 v99, v21, v25 offset0:211 offset1:215
	s_waitcnt vmcnt(8)
	ds_write2_b32 v99, v26, v30 offset0:24 offset1:28
	ds_write2_b32 v99, v27, v31 offset0:89 offset1:93
	ds_write2_b32 v99, v28, v32 offset0:154 offset1:158
	ds_write2_b32 v99, v29, v33 offset0:219 offset1:223
	s_waitcnt vmcnt(6)
	ds_write2_b32 v99, v34, v38 offset0:32 offset1:36
	ds_write2_b32 v99, v35, v39 offset0:97 offset1:101
	ds_write2_b32 v99, v36, v40 offset0:162 offset1:166
	ds_write2_b32 v99, v37, v41 offset0:227 offset1:231
	s_waitcnt vmcnt(4)
	ds_write2_b32 v99, v42, v46 offset0:40 offset1:44
	ds_write2_b32 v99, v43, v47 offset0:105 offset1:109
	ds_write2_b32 v99, v44, v48 offset0:170 offset1:174
	ds_write2_b32 v99, v45, v49 offset0:235 offset1:239
	s_waitcnt vmcnt(2)
	ds_write2_b32 v99, v50, v54 offset0:48 offset1:52
	ds_write2_b32 v99, v51, v55 offset0:113 offset1:117
	ds_write2_b32 v99, v52, v56 offset0:178 offset1:182
	ds_write2_b32 v99, v53, v57 offset0:243 offset1:247
	s_waitcnt vmcnt(0)
	ds_write2_b32 v99, v58, v62 offset0:56 offset1:60
	ds_write2_b32 v99, v59, v63 offset0:121 offset1:125
	ds_write2_b32 v99, v60, v64 offset0:186 offset1:190
	ds_write2_b32 v99, v61, v65 offset0:251 offset1:255
	s_waitcnt lgkmcnt(0)
	ds_read2_b32 v[4:5], v123 offset1:1
	ds_read2_b32 v[6:7], v123 offset0:2 offset1:3
	ds_read2_b32 v[8:9], v123 offset0:4 offset1:5
	ds_read2_b32 v[10:11], v123 offset0:6 offset1:7
	v_lshl_add_u64 v[2:3], s[2:3], 0, v[74:75]
	v_lshl_add_u64 v[2:3], v[2:3], 0, s[72:73]
	s_waitcnt lgkmcnt(3)
	v_and_b32_sdwa v13, v4, v124 dst_sel:DWORD dst_unused:UNUSED_PAD src0_sel:WORD_1 src1_sel:DWORD
	s_waitcnt lgkmcnt(2)
	v_and_b32_sdwa v12, v6, v124 dst_sel:DWORD dst_unused:UNUSED_PAD src0_sel:WORD_1 src1_sel:DWORD
	v_add3_u32 v6, v6, v12, s89
	v_and_b32_sdwa v12, v7, v124 dst_sel:DWORD dst_unused:UNUSED_PAD src0_sel:WORD_1 src1_sel:DWORD
	v_add3_u32 v4, v4, v13, s89
	v_and_b32_sdwa v13, v5, v124 dst_sel:DWORD dst_unused:UNUSED_PAD src0_sel:WORD_1 src1_sel:DWORD
	v_add3_u32 v7, v7, v12, s89
	v_add3_u32 v5, v5, v13, s89
	v_and_b32_e32 v7, 0xffff0000, v7
	v_and_b32_e32 v12, 0xffff0000, v5
	v_or_b32_sdwa v5, v7, v6 dst_sel:DWORD dst_unused:UNUSED_PAD src0_sel:DWORD src1_sel:WORD_1
	s_waitcnt lgkmcnt(0)
	v_and_b32_sdwa v6, v10, v124 dst_sel:DWORD dst_unused:UNUSED_PAD src0_sel:WORD_1 src1_sel:DWORD
	v_and_b32_sdwa v7, v8, v124 dst_sel:DWORD dst_unused:UNUSED_PAD src0_sel:WORD_1 src1_sel:DWORD
	v_add3_u32 v8, v8, v7, s89
	v_add3_u32 v6, v10, v6, s89
	v_and_b32_sdwa v7, v11, v124 dst_sel:DWORD dst_unused:UNUSED_PAD src0_sel:WORD_1 src1_sel:DWORD
	v_and_b32_sdwa v10, v9, v124 dst_sel:DWORD dst_unused:UNUSED_PAD src0_sel:WORD_1 src1_sel:DWORD
	v_add3_u32 v7, v11, v7, s89
	v_add3_u32 v9, v9, v10, s89
	v_and_b32_e32 v7, 0xffff0000, v7
	v_and_b32_e32 v9, 0xffff0000, v9
	v_or_b32_sdwa v7, v7, v6 dst_sel:DWORD dst_unused:UNUSED_PAD src0_sel:DWORD src1_sel:WORD_1
	v_or_b32_sdwa v6, v9, v8 dst_sel:DWORD dst_unused:UNUSED_PAD src0_sel:DWORD src1_sel:WORD_1
	v_or_b32_e32 v8, s18, v115
	v_lshlrev_b32_e32 v8, 12, v8
	v_mov_b32_e32 v9, v75
	v_or_b32_sdwa v4, v12, v4 dst_sel:DWORD dst_unused:UNUSED_PAD src0_sel:DWORD src1_sel:WORD_1
	v_lshl_add_u64 v[8:9], v[2:3], 0, v[8:9]
	global_store_dwordx4 v[8:9], v[4:7], off
	ds_read2_b32 v[4:5], v125 offset1:1
	ds_read2_b32 v[6:7], v126 offset1:1
	v_add_u32_e32 v8, 0x830, v123
	v_add_u32_e32 v10, 0x838, v123
	ds_read2_b32 v[8:9], v8 offset1:1
	ds_read2_b32 v[10:11], v10 offset1:1
	s_waitcnt lgkmcnt(3)
	v_and_b32_sdwa v13, v4, v124 dst_sel:DWORD dst_unused:UNUSED_PAD src0_sel:WORD_1 src1_sel:DWORD
	s_waitcnt lgkmcnt(2)
	v_and_b32_sdwa v12, v6, v124 dst_sel:DWORD dst_unused:UNUSED_PAD src0_sel:WORD_1 src1_sel:DWORD
	v_add3_u32 v6, v6, v12, s89
	v_and_b32_sdwa v12, v7, v124 dst_sel:DWORD dst_unused:UNUSED_PAD src0_sel:WORD_1 src1_sel:DWORD
	v_add3_u32 v4, v4, v13, s89
	v_and_b32_sdwa v13, v5, v124 dst_sel:DWORD dst_unused:UNUSED_PAD src0_sel:WORD_1 src1_sel:DWORD
	v_add3_u32 v7, v7, v12, s89
	v_add3_u32 v5, v5, v13, s89
	v_and_b32_e32 v7, 0xffff0000, v7
	v_and_b32_e32 v12, 0xffff0000, v5
	v_or_b32_sdwa v5, v7, v6 dst_sel:DWORD dst_unused:UNUSED_PAD src0_sel:DWORD src1_sel:WORD_1
	s_waitcnt lgkmcnt(0)
	v_and_b32_sdwa v6, v10, v124 dst_sel:DWORD dst_unused:UNUSED_PAD src0_sel:WORD_1 src1_sel:DWORD
	v_and_b32_sdwa v7, v8, v124 dst_sel:DWORD dst_unused:UNUSED_PAD src0_sel:WORD_1 src1_sel:DWORD
	v_add3_u32 v8, v8, v7, s89
	v_add3_u32 v6, v10, v6, s89
	v_and_b32_sdwa v7, v11, v124 dst_sel:DWORD dst_unused:UNUSED_PAD src0_sel:WORD_1 src1_sel:DWORD
	v_and_b32_sdwa v10, v9, v124 dst_sel:DWORD dst_unused:UNUSED_PAD src0_sel:WORD_1 src1_sel:DWORD
	v_add3_u32 v7, v11, v7, s89
	v_add3_u32 v9, v9, v10, s89
	v_and_b32_e32 v7, 0xffff0000, v7
	v_and_b32_e32 v9, 0xffff0000, v9
	v_or_b32_sdwa v7, v7, v6 dst_sel:DWORD dst_unused:UNUSED_PAD src0_sel:DWORD src1_sel:WORD_1
	v_or_b32_sdwa v6, v9, v8 dst_sel:DWORD dst_unused:UNUSED_PAD src0_sel:DWORD src1_sel:WORD_1
	v_or_b32_e32 v8, s18, v116
	v_lshlrev_b32_e32 v8, 12, v8
	v_mov_b32_e32 v9, v75
	v_or_b32_sdwa v4, v12, v4 dst_sel:DWORD dst_unused:UNUSED_PAD src0_sel:DWORD src1_sel:WORD_1
	v_lshl_add_u64 v[8:9], v[2:3], 0, v[8:9]
	global_store_dwordx4 v[8:9], v[4:7], off
	v_add_u32_e32 v8, 0x1050, v123
	v_add_u32_e32 v10, 0x1058, v123
	v_add_u32_e32 v4, 0x1040, v123
	v_add_u32_e32 v6, 0x1048, v123
	ds_read2_b32 v[4:5], v4 offset1:1
	ds_read2_b32 v[6:7], v6 offset1:1
	ds_read2_b32 v[8:9], v8 offset1:1
	ds_read2_b32 v[10:11], v10 offset1:1
	s_waitcnt lgkmcnt(3)
	v_and_b32_sdwa v13, v4, v124 dst_sel:DWORD dst_unused:UNUSED_PAD src0_sel:WORD_1 src1_sel:DWORD
	s_waitcnt lgkmcnt(2)
	v_and_b32_sdwa v12, v6, v124 dst_sel:DWORD dst_unused:UNUSED_PAD src0_sel:WORD_1 src1_sel:DWORD
	v_add3_u32 v6, v6, v12, s89
	v_and_b32_sdwa v12, v7, v124 dst_sel:DWORD dst_unused:UNUSED_PAD src0_sel:WORD_1 src1_sel:DWORD
	v_add3_u32 v4, v4, v13, s89
	v_and_b32_sdwa v13, v5, v124 dst_sel:DWORD dst_unused:UNUSED_PAD src0_sel:WORD_1 src1_sel:DWORD
	v_add3_u32 v7, v7, v12, s89
	v_add3_u32 v5, v5, v13, s89
	v_and_b32_e32 v7, 0xffff0000, v7
	v_and_b32_e32 v12, 0xffff0000, v5
	v_or_b32_sdwa v5, v7, v6 dst_sel:DWORD dst_unused:UNUSED_PAD src0_sel:DWORD src1_sel:WORD_1
	s_waitcnt lgkmcnt(0)
	v_and_b32_sdwa v6, v10, v124 dst_sel:DWORD dst_unused:UNUSED_PAD src0_sel:WORD_1 src1_sel:DWORD
	v_and_b32_sdwa v7, v8, v124 dst_sel:DWORD dst_unused:UNUSED_PAD src0_sel:WORD_1 src1_sel:DWORD
	v_add3_u32 v8, v8, v7, s89
	v_add3_u32 v6, v10, v6, s89
	v_and_b32_sdwa v7, v11, v124 dst_sel:DWORD dst_unused:UNUSED_PAD src0_sel:WORD_1 src1_sel:DWORD
	v_and_b32_sdwa v10, v9, v124 dst_sel:DWORD dst_unused:UNUSED_PAD src0_sel:WORD_1 src1_sel:DWORD
	v_add3_u32 v7, v11, v7, s89
	v_add3_u32 v9, v9, v10, s89
	v_and_b32_e32 v7, 0xffff0000, v7
	v_and_b32_e32 v9, 0xffff0000, v9
	v_or_b32_sdwa v7, v7, v6 dst_sel:DWORD dst_unused:UNUSED_PAD src0_sel:DWORD src1_sel:WORD_1
	v_or_b32_sdwa v6, v9, v8 dst_sel:DWORD dst_unused:UNUSED_PAD src0_sel:DWORD src1_sel:WORD_1
	v_or_b32_e32 v8, s18, v117
	v_lshlrev_b32_e32 v8, 12, v8
	v_mov_b32_e32 v9, v75
	v_or_b32_sdwa v4, v12, v4 dst_sel:DWORD dst_unused:UNUSED_PAD src0_sel:DWORD src1_sel:WORD_1
	v_lshl_add_u64 v[8:9], v[2:3], 0, v[8:9]
	global_store_dwordx4 v[8:9], v[4:7], off
	v_add_u32_e32 v8, 0x1870, v123
	v_add_u32_e32 v10, 0x1878, v123
	v_add_u32_e32 v4, 0x1860, v123
	v_add_u32_e32 v6, 0x1868, v123
	ds_read2_b32 v[4:5], v4 offset1:1
	ds_read2_b32 v[6:7], v6 offset1:1
	ds_read2_b32 v[8:9], v8 offset1:1
	ds_read2_b32 v[10:11], v10 offset1:1
	s_waitcnt lgkmcnt(3)
	v_and_b32_sdwa v13, v4, v124 dst_sel:DWORD dst_unused:UNUSED_PAD src0_sel:WORD_1 src1_sel:DWORD
	s_waitcnt lgkmcnt(2)
	v_and_b32_sdwa v12, v6, v124 dst_sel:DWORD dst_unused:UNUSED_PAD src0_sel:WORD_1 src1_sel:DWORD
	v_add3_u32 v6, v6, v12, s89
	v_and_b32_sdwa v12, v7, v124 dst_sel:DWORD dst_unused:UNUSED_PAD src0_sel:WORD_1 src1_sel:DWORD
	v_add3_u32 v4, v4, v13, s89
	v_and_b32_sdwa v13, v5, v124 dst_sel:DWORD dst_unused:UNUSED_PAD src0_sel:WORD_1 src1_sel:DWORD
	v_add3_u32 v7, v7, v12, s89
	v_add3_u32 v5, v5, v13, s89
	v_and_b32_e32 v7, 0xffff0000, v7
	v_and_b32_e32 v12, 0xffff0000, v5
	v_or_b32_sdwa v5, v7, v6 dst_sel:DWORD dst_unused:UNUSED_PAD src0_sel:DWORD src1_sel:WORD_1
	s_waitcnt lgkmcnt(0)
	v_and_b32_sdwa v6, v10, v124 dst_sel:DWORD dst_unused:UNUSED_PAD src0_sel:WORD_1 src1_sel:DWORD
	v_and_b32_sdwa v7, v8, v124 dst_sel:DWORD dst_unused:UNUSED_PAD src0_sel:WORD_1 src1_sel:DWORD
	v_add3_u32 v8, v8, v7, s89
	v_add3_u32 v6, v10, v6, s89
	v_and_b32_sdwa v7, v11, v124 dst_sel:DWORD dst_unused:UNUSED_PAD src0_sel:WORD_1 src1_sel:DWORD
	v_and_b32_sdwa v10, v9, v124 dst_sel:DWORD dst_unused:UNUSED_PAD src0_sel:WORD_1 src1_sel:DWORD
	v_add3_u32 v7, v11, v7, s89
	v_add3_u32 v9, v9, v10, s89
	v_and_b32_e32 v7, 0xffff0000, v7
	v_and_b32_e32 v9, 0xffff0000, v9
	v_or_b32_sdwa v7, v7, v6 dst_sel:DWORD dst_unused:UNUSED_PAD src0_sel:DWORD src1_sel:WORD_1
	v_or_b32_sdwa v6, v9, v8 dst_sel:DWORD dst_unused:UNUSED_PAD src0_sel:DWORD src1_sel:WORD_1
	v_or_b32_e32 v8, s18, v118
	v_lshlrev_b32_e32 v8, 12, v8
	v_mov_b32_e32 v9, v75
	v_or_b32_sdwa v4, v12, v4 dst_sel:DWORD dst_unused:UNUSED_PAD src0_sel:DWORD src1_sel:WORD_1
	v_lshl_add_u64 v[8:9], v[2:3], 0, v[8:9]
	global_store_dwordx4 v[8:9], v[4:7], off
	v_add_u32_e32 v8, 0x2090, v123
	v_add_u32_e32 v10, 0x2098, v123
	v_add_u32_e32 v4, 0x2080, v123
	v_add_u32_e32 v6, 0x2088, v123
	ds_read2_b32 v[4:5], v4 offset1:1
	ds_read2_b32 v[6:7], v6 offset1:1
	ds_read2_b32 v[8:9], v8 offset1:1
	ds_read2_b32 v[10:11], v10 offset1:1
	s_waitcnt lgkmcnt(3)
	v_and_b32_sdwa v13, v4, v124 dst_sel:DWORD dst_unused:UNUSED_PAD src0_sel:WORD_1 src1_sel:DWORD
	s_waitcnt lgkmcnt(2)
	v_and_b32_sdwa v12, v6, v124 dst_sel:DWORD dst_unused:UNUSED_PAD src0_sel:WORD_1 src1_sel:DWORD
	v_add3_u32 v6, v6, v12, s89
	v_and_b32_sdwa v12, v7, v124 dst_sel:DWORD dst_unused:UNUSED_PAD src0_sel:WORD_1 src1_sel:DWORD
	v_add3_u32 v4, v4, v13, s89
	v_and_b32_sdwa v13, v5, v124 dst_sel:DWORD dst_unused:UNUSED_PAD src0_sel:WORD_1 src1_sel:DWORD
	v_add3_u32 v7, v7, v12, s89
	v_add3_u32 v5, v5, v13, s89
	v_and_b32_e32 v7, 0xffff0000, v7
	v_and_b32_e32 v12, 0xffff0000, v5
	v_or_b32_sdwa v5, v7, v6 dst_sel:DWORD dst_unused:UNUSED_PAD src0_sel:DWORD src1_sel:WORD_1
	s_waitcnt lgkmcnt(0)
	v_and_b32_sdwa v6, v10, v124 dst_sel:DWORD dst_unused:UNUSED_PAD src0_sel:WORD_1 src1_sel:DWORD
	v_and_b32_sdwa v7, v8, v124 dst_sel:DWORD dst_unused:UNUSED_PAD src0_sel:WORD_1 src1_sel:DWORD
	v_add3_u32 v8, v8, v7, s89
	v_add3_u32 v6, v10, v6, s89
	v_and_b32_sdwa v7, v11, v124 dst_sel:DWORD dst_unused:UNUSED_PAD src0_sel:WORD_1 src1_sel:DWORD
	v_and_b32_sdwa v10, v9, v124 dst_sel:DWORD dst_unused:UNUSED_PAD src0_sel:WORD_1 src1_sel:DWORD
	v_add3_u32 v7, v11, v7, s89
	v_add3_u32 v9, v9, v10, s89
	v_and_b32_e32 v7, 0xffff0000, v7
	v_and_b32_e32 v9, 0xffff0000, v9
	v_or_b32_sdwa v7, v7, v6 dst_sel:DWORD dst_unused:UNUSED_PAD src0_sel:DWORD src1_sel:WORD_1
	v_or_b32_sdwa v6, v9, v8 dst_sel:DWORD dst_unused:UNUSED_PAD src0_sel:DWORD src1_sel:WORD_1
	v_or_b32_e32 v8, s18, v119
	v_lshlrev_b32_e32 v8, 12, v8
	v_mov_b32_e32 v9, v75
	v_or_b32_sdwa v4, v12, v4 dst_sel:DWORD dst_unused:UNUSED_PAD src0_sel:DWORD src1_sel:WORD_1
	v_lshl_add_u64 v[8:9], v[2:3], 0, v[8:9]
	global_store_dwordx4 v[8:9], v[4:7], off
	v_add_u32_e32 v8, 0x28b0, v123
	v_add_u32_e32 v10, 0x28b8, v123
	v_add_u32_e32 v4, 0x28a0, v123
	v_add_u32_e32 v6, 0x28a8, v123
	ds_read2_b32 v[4:5], v4 offset1:1
	ds_read2_b32 v[6:7], v6 offset1:1
	ds_read2_b32 v[8:9], v8 offset1:1
	ds_read2_b32 v[10:11], v10 offset1:1
	s_waitcnt lgkmcnt(3)
	v_and_b32_sdwa v13, v4, v124 dst_sel:DWORD dst_unused:UNUSED_PAD src0_sel:WORD_1 src1_sel:DWORD
	s_waitcnt lgkmcnt(2)
	v_and_b32_sdwa v12, v6, v124 dst_sel:DWORD dst_unused:UNUSED_PAD src0_sel:WORD_1 src1_sel:DWORD
	v_add3_u32 v6, v6, v12, s89
	v_and_b32_sdwa v12, v7, v124 dst_sel:DWORD dst_unused:UNUSED_PAD src0_sel:WORD_1 src1_sel:DWORD
	v_add3_u32 v4, v4, v13, s89
	v_and_b32_sdwa v13, v5, v124 dst_sel:DWORD dst_unused:UNUSED_PAD src0_sel:WORD_1 src1_sel:DWORD
	v_add3_u32 v7, v7, v12, s89
	v_add3_u32 v5, v5, v13, s89
	v_and_b32_e32 v7, 0xffff0000, v7
	v_and_b32_e32 v12, 0xffff0000, v5
	v_or_b32_sdwa v5, v7, v6 dst_sel:DWORD dst_unused:UNUSED_PAD src0_sel:DWORD src1_sel:WORD_1
	s_waitcnt lgkmcnt(0)
	v_and_b32_sdwa v6, v10, v124 dst_sel:DWORD dst_unused:UNUSED_PAD src0_sel:WORD_1 src1_sel:DWORD
	v_and_b32_sdwa v7, v8, v124 dst_sel:DWORD dst_unused:UNUSED_PAD src0_sel:WORD_1 src1_sel:DWORD
	v_add3_u32 v8, v8, v7, s89
	v_add3_u32 v6, v10, v6, s89
	v_and_b32_sdwa v7, v11, v124 dst_sel:DWORD dst_unused:UNUSED_PAD src0_sel:WORD_1 src1_sel:DWORD
	v_and_b32_sdwa v10, v9, v124 dst_sel:DWORD dst_unused:UNUSED_PAD src0_sel:WORD_1 src1_sel:DWORD
	v_add3_u32 v7, v11, v7, s89
	v_add3_u32 v9, v9, v10, s89
	v_and_b32_e32 v7, 0xffff0000, v7
	v_and_b32_e32 v9, 0xffff0000, v9
	v_or_b32_sdwa v7, v7, v6 dst_sel:DWORD dst_unused:UNUSED_PAD src0_sel:DWORD src1_sel:WORD_1
	v_or_b32_sdwa v6, v9, v8 dst_sel:DWORD dst_unused:UNUSED_PAD src0_sel:DWORD src1_sel:WORD_1
	v_or_b32_e32 v8, s18, v120
	v_lshlrev_b32_e32 v8, 12, v8
	v_mov_b32_e32 v9, v75
	v_or_b32_sdwa v4, v12, v4 dst_sel:DWORD dst_unused:UNUSED_PAD src0_sel:DWORD src1_sel:WORD_1
	v_lshl_add_u64 v[8:9], v[2:3], 0, v[8:9]
	global_store_dwordx4 v[8:9], v[4:7], off
	v_add_u32_e32 v8, 0x30d0, v123
	v_add_u32_e32 v10, 0x30d8, v123
	v_add_u32_e32 v4, 0x30c0, v123
	v_add_u32_e32 v6, 0x30c8, v123
	ds_read2_b32 v[4:5], v4 offset1:1
	ds_read2_b32 v[6:7], v6 offset1:1
	ds_read2_b32 v[8:9], v8 offset1:1
	ds_read2_b32 v[10:11], v10 offset1:1
	s_waitcnt lgkmcnt(3)
	v_and_b32_sdwa v13, v4, v124 dst_sel:DWORD dst_unused:UNUSED_PAD src0_sel:WORD_1 src1_sel:DWORD
	s_waitcnt lgkmcnt(2)
	v_and_b32_sdwa v12, v6, v124 dst_sel:DWORD dst_unused:UNUSED_PAD src0_sel:WORD_1 src1_sel:DWORD
	v_add3_u32 v6, v6, v12, s89
	v_and_b32_sdwa v12, v7, v124 dst_sel:DWORD dst_unused:UNUSED_PAD src0_sel:WORD_1 src1_sel:DWORD
	v_add3_u32 v4, v4, v13, s89
	v_and_b32_sdwa v13, v5, v124 dst_sel:DWORD dst_unused:UNUSED_PAD src0_sel:WORD_1 src1_sel:DWORD
	v_add3_u32 v7, v7, v12, s89
	v_add3_u32 v5, v5, v13, s89
	v_and_b32_e32 v7, 0xffff0000, v7
	v_and_b32_e32 v12, 0xffff0000, v5
	v_or_b32_sdwa v5, v7, v6 dst_sel:DWORD dst_unused:UNUSED_PAD src0_sel:DWORD src1_sel:WORD_1
	s_waitcnt lgkmcnt(0)
	v_and_b32_sdwa v6, v10, v124 dst_sel:DWORD dst_unused:UNUSED_PAD src0_sel:WORD_1 src1_sel:DWORD
	v_and_b32_sdwa v7, v8, v124 dst_sel:DWORD dst_unused:UNUSED_PAD src0_sel:WORD_1 src1_sel:DWORD
	v_add3_u32 v8, v8, v7, s89
	v_add3_u32 v6, v10, v6, s89
	v_and_b32_sdwa v7, v11, v124 dst_sel:DWORD dst_unused:UNUSED_PAD src0_sel:WORD_1 src1_sel:DWORD
	v_and_b32_sdwa v10, v9, v124 dst_sel:DWORD dst_unused:UNUSED_PAD src0_sel:WORD_1 src1_sel:DWORD
	v_add3_u32 v7, v11, v7, s89
	v_add3_u32 v9, v9, v10, s89
	v_and_b32_e32 v7, 0xffff0000, v7
	v_and_b32_e32 v9, 0xffff0000, v9
	v_or_b32_sdwa v7, v7, v6 dst_sel:DWORD dst_unused:UNUSED_PAD src0_sel:DWORD src1_sel:WORD_1
	v_or_b32_sdwa v6, v9, v8 dst_sel:DWORD dst_unused:UNUSED_PAD src0_sel:DWORD src1_sel:WORD_1
	v_or_b32_e32 v8, s18, v121
	v_lshlrev_b32_e32 v8, 12, v8
	v_mov_b32_e32 v9, v75
	v_or_b32_sdwa v4, v12, v4 dst_sel:DWORD dst_unused:UNUSED_PAD src0_sel:DWORD src1_sel:WORD_1
	v_lshl_add_u64 v[8:9], v[2:3], 0, v[8:9]
	global_store_dwordx4 v[8:9], v[4:7], off
	v_add_u32_e32 v8, 0x38f0, v123
	v_add_u32_e32 v10, 0x38f8, v123
	v_add_u32_e32 v4, 0x38e0, v123
	v_add_u32_e32 v6, 0x38e8, v123
	ds_read2_b32 v[4:5], v4 offset1:1
	ds_read2_b32 v[6:7], v6 offset1:1
	ds_read2_b32 v[8:9], v8 offset1:1
	ds_read2_b32 v[10:11], v10 offset1:1
	s_waitcnt lgkmcnt(3)
	v_and_b32_sdwa v13, v4, v124 dst_sel:DWORD dst_unused:UNUSED_PAD src0_sel:WORD_1 src1_sel:DWORD
	s_waitcnt lgkmcnt(2)
	v_and_b32_sdwa v12, v6, v124 dst_sel:DWORD dst_unused:UNUSED_PAD src0_sel:WORD_1 src1_sel:DWORD
	v_add3_u32 v6, v6, v12, s89
	v_and_b32_sdwa v12, v7, v124 dst_sel:DWORD dst_unused:UNUSED_PAD src0_sel:WORD_1 src1_sel:DWORD
	v_add3_u32 v4, v4, v13, s89
	v_and_b32_sdwa v13, v5, v124 dst_sel:DWORD dst_unused:UNUSED_PAD src0_sel:WORD_1 src1_sel:DWORD
	v_add3_u32 v7, v7, v12, s89
	v_add3_u32 v5, v5, v13, s89
	v_and_b32_e32 v7, 0xffff0000, v7
	v_and_b32_e32 v12, 0xffff0000, v5
	v_or_b32_sdwa v5, v7, v6 dst_sel:DWORD dst_unused:UNUSED_PAD src0_sel:DWORD src1_sel:WORD_1
	s_waitcnt lgkmcnt(0)
	v_and_b32_sdwa v6, v10, v124 dst_sel:DWORD dst_unused:UNUSED_PAD src0_sel:WORD_1 src1_sel:DWORD
	v_and_b32_sdwa v7, v8, v124 dst_sel:DWORD dst_unused:UNUSED_PAD src0_sel:WORD_1 src1_sel:DWORD
	v_add3_u32 v8, v8, v7, s89
	v_add3_u32 v6, v10, v6, s89
	v_and_b32_sdwa v7, v11, v124 dst_sel:DWORD dst_unused:UNUSED_PAD src0_sel:WORD_1 src1_sel:DWORD
	v_and_b32_sdwa v10, v9, v124 dst_sel:DWORD dst_unused:UNUSED_PAD src0_sel:WORD_1 src1_sel:DWORD
	v_add3_u32 v7, v11, v7, s89
	v_add3_u32 v9, v9, v10, s89
	v_and_b32_e32 v7, 0xffff0000, v7
	v_and_b32_e32 v9, 0xffff0000, v9
	v_or_b32_sdwa v7, v7, v6 dst_sel:DWORD dst_unused:UNUSED_PAD src0_sel:DWORD src1_sel:WORD_1
	v_or_b32_sdwa v6, v9, v8 dst_sel:DWORD dst_unused:UNUSED_PAD src0_sel:DWORD src1_sel:WORD_1
	v_or_b32_e32 v8, s18, v122
	v_lshlrev_b32_e32 v8, 12, v8
	v_mov_b32_e32 v9, v75
	v_or_b32_sdwa v4, v12, v4 dst_sel:DWORD dst_unused:UNUSED_PAD src0_sel:DWORD src1_sel:WORD_1
	v_lshl_add_u64 v[2:3], v[2:3], 0, v[8:9]
	global_store_dwordx4 v[2:3], v[4:7], off
	s_waitcnt lgkmcnt(0)

.LBB0_115:
	s_andn2_b64 vcc, exec, s[2:3]
	s_cbranch_vccnz .LBB0_8
	s_mul_hi_i32 s2, s92, 0x2aaaaaab
	s_lshr_b32 s3, s2, 31
	s_ashr_i32 s2, s2, 4
	s_add_i32 s2, s2, s3
	s_lshl_b32 s80, s2, 6
	s_mulk_i32 s2, 0xe800
	s_add_i32 s76, s21, s2
	v_or_b32_e32 v66, s80, v72
	s_ashr_i32 s77, s76, 31
	v_lshl_add_u64 v[2:3], s[76:77], 2, v[96:97]
	v_or_b32_e32 v6, 4, v66
	s_mov_b64 s[78:79], s[28:29]
	v_mad_i64_i32 v[4:5], s[2:3], v66, s91, v[2:3]
	v_mad_i64_i32 v[6:7], s[2:3], v6, s91, v[2:3]
	global_load_dwordx4 v[58:61], v[4:5], off nt
	global_load_dwordx4 v[62:65], v[6:7], off nt
	v_or_b32_e32 v4, 8, v66
	v_or_b32_e32 v6, 12, v66
	v_mad_i64_i32 v[4:5], s[2:3], v4, s91, v[2:3]
	v_mad_i64_i32 v[6:7], s[2:3], v6, s91, v[2:3]
	global_load_dwordx4 v[50:53], v[4:5], off nt
	global_load_dwordx4 v[54:57], v[6:7], off nt
	v_or_b32_e32 v4, 16, v66
	v_or_b32_e32 v6, 20, v66
	v_mad_i64_i32 v[4:5], s[2:3], v4, s91, v[2:3]
	v_mad_i64_i32 v[6:7], s[2:3], v6, s91, v[2:3]
	global_load_dwordx4 v[42:45], v[4:5], off nt
	global_load_dwordx4 v[46:49], v[6:7], off nt
	v_or_b32_e32 v4, 24, v66
	v_or_b32_e32 v6, 28, v66
	v_mad_i64_i32 v[4:5], s[2:3], v4, s91, v[2:3]
	v_mad_i64_i32 v[6:7], s[2:3], v6, s91, v[2:3]
	global_load_dwordx4 v[34:37], v[4:5], off nt
	global_load_dwordx4 v[38:41], v[6:7], off nt
	v_or_b32_e32 v4, 32, v66
	v_or_b32_e32 v6, 36, v66
	v_mad_i64_i32 v[4:5], s[2:3], v4, s91, v[2:3]
	v_mad_i64_i32 v[6:7], s[2:3], v6, s91, v[2:3]
	v_or_b32_e32 v10, 52, v66
	global_load_dwordx4 v[26:29], v[4:5], off nt
	global_load_dwordx4 v[30:33], v[6:7], off nt
	v_or_b32_e32 v4, 40, v66
	v_or_b32_e32 v6, 44, v66
	v_or_b32_e32 v8, 48, v66
	v_mad_i64_i32 v[14:15], s[2:3], v10, s91, v[2:3]
	v_or_b32_e32 v10, 56, v66
	v_mad_i64_i32 v[4:5], s[2:3], v4, s91, v[2:3]
	v_mad_i64_i32 v[6:7], s[2:3], v6, s91, v[2:3]
	v_mad_i64_i32 v[8:9], s[2:3], v8, s91, v[2:3]
	v_mad_i64_i32 v[68:69], s[2:3], v10, s91, v[2:3]
	v_or_b32_e32 v10, 60, v66
	v_mad_i64_i32 v[128:129], s[2:3], v10, s91, v[2:3]
	global_load_dwordx4 v[18:21], v[4:5], off nt
	global_load_dwordx4 v[22:25], v[6:7], off nt
	global_load_dwordx4 v[10:13], v[8:9], off nt
	s_nop 0
	global_load_dwordx4 v[14:17], v[14:15], off nt
	s_nop 0
	global_load_dwordx4 v[2:5], v[68:69], off nt
	global_load_dwordx4 v[6:9], v[128:129], off nt
	v_cndmask_b32_e64 v67, 0, 1, s[4:5]
	v_cmp_ne_u32_e64 s[2:3], 1, v67
	s_andn2_b64 vcc, exec, s[4:5]
	s_cbranch_vccnz .LBB0_139
	s_ashr_i32 s81, s80, 31
	v_ashrrev_i32_e32 v67, 31, v66
	v_lshl_add_u64 v[68:69], s[80:81], 0, v[72:73]
	v_lshl_add_u64 v[66:67], v[66:67], 2, s[56:57]
	v_lshl_add_u64 v[68:69], v[68:69], 2, s[56:57]
	global_load_dword v66, v[66:67], off
	s_nop 0
	global_load_dword v128, v[68:69], off offset:16
	s_waitcnt vmcnt(1)
	v_pk_mul_f32 v[60:61], v[60:61], v[66:67] op_sel_hi:[1,0]
	v_pk_mul_f32 v[58:59], v[58:59], v[66:67] op_sel_hi:[1,0]
	s_waitcnt vmcnt(0)
	v_pk_mul_f32 v[68:69], v[64:65], v[128:129] op_sel_hi:[1,0]
	v_pk_mul_f32 v[66:67], v[62:63], v[128:129] op_sel_hi:[1,0]
	s_cbranch_execnz .LBB0_119

.LBB0_191:
	global_load_dwordx4 v[6:9], v[34:35], off offset:-4096 nt
	global_load_dwordx4 v[2:5], v[34:35], off offset:-3072 nt
	global_load_dwordx4 v[10:13], v[34:35], off offset:-2048 nt
	global_load_dwordx4 v[14:17], v[34:35], off nt
	global_load_dwordx4 v[18:21], v[34:35], off offset:-1024 nt
	global_load_dwordx4 v[22:25], v[34:35], off offset:1024 nt
	global_load_dwordx4 v[26:29], v[34:35], off offset:3072 nt
	global_load_dwordx4 v[30:33], v[34:35], off offset:2048 nt
	s_add_i32 s8, s8, s22
	v_lshl_add_u64 v[34:35], v[34:35], 0, s[2:3]
	s_cmp_lt_i32 s8, 0x8000
	s_waitcnt vmcnt(7)
	v_mov_b32_e32 v50, v7
	s_waitcnt vmcnt(6)
	v_mov_b32_e32 v51, v3
	v_mov_b32_e32 v54, v9
	v_mov_b32_e32 v55, v5
	v_mov_b32_e32 v48, v6
	v_mov_b32_e32 v49, v2
	v_mov_b32_e32 v52, v8
	v_mov_b32_e32 v53, v4
	s_waitcnt vmcnt(5)
	v_pk_mul_f32 v[56:57], v[12:13], v[12:13]
	v_pk_mul_f32 v[58:59], v[10:11], v[10:11]
	s_waitcnt vmcnt(3)
	v_mul_f32_e32 v60, v19, v19
	v_mul_f32_e32 v62, v21, v21
	s_waitcnt vmcnt(1)
	v_mul_f32_e32 v80, v26, v26
	v_mul_f32_e32 v81, v27, v27
	v_mul_f32_e32 v82, v28, v28
	v_mov_b32_e32 v76, v26
	v_mov_b32_e32 v77, v28
	v_mov_b32_e32 v28, v27
	v_pk_mul_f32 v[26:27], v[50:51], v[50:51]
	v_pk_mul_f32 v[50:51], v[54:55], v[54:55]
	v_mul_f32_e32 v71, v15, v15
	v_pk_mul_f32 v[64:65], v[24:25], v[24:25]
	v_pk_mul_f32 v[66:67], v[22:23], v[22:23]
	s_waitcnt vmcnt(0)
	v_mul_f32_e32 v68, v31, v31
	v_mul_f32_e32 v70, v33, v33
	v_mov_b32_e32 v72, v6
	v_mov_b32_e32 v73, v8
	v_mov_b32_e32 v8, v7
	v_mov_b32_e32 v6, v2
	v_mov_b32_e32 v7, v4
	v_mov_b32_e32 v4, v3
	v_mov_b32_e32 v2, v10
	v_mov_b32_e32 v3, v12
	v_mov_b32_e32 v12, v11
	v_mov_b32_e32 v10, v18
	v_mov_b32_e32 v11, v20
	v_pk_mov_b32 v[54:55], v[58:59], v[56:57] op_sel:[1,0]
	v_mov_b32_e32 v59, v57
	v_pk_fma_f32 v[56:57], v[18:19], v[18:19], v[60:61] op_sel_hi:[1,1,0]
	v_pk_fma_f32 v[60:61], v[20:21], v[20:21], v[62:63] op_sel_hi:[1,1,0]
	v_mov_b32_e32 v20, v19
	v_pk_fma_f32 v[18:19], v[48:49], v[48:49], v[26:27]
	v_pk_fma_f32 v[26:27], v[52:53], v[52:53], v[50:51]
	v_mul_f32_e32 v47, v14, v14
	v_mul_f32_e32 v78, v16, v16
	v_mov_b32_e32 v74, v14
	v_mov_b32_e32 v75, v16
	v_mov_b32_e32 v16, v15
	v_mov_b32_e32 v14, v22
	v_mov_b32_e32 v15, v24
	v_mov_b32_e32 v24, v23
	v_mov_b32_e32 v22, v30
	v_mov_b32_e32 v23, v32
	v_pk_mov_b32 v[62:63], v[66:67], v[64:65] op_sel:[1,0]
	v_mov_b32_e32 v67, v65
	v_pk_fma_f32 v[64:65], v[30:31], v[30:31], v[68:69] op_sel_hi:[1,1,0]
	v_pk_fma_f32 v[68:69], v[32:33], v[32:33], v[70:71] op_sel_hi:[1,1,0]
	v_mov_b32_e32 v32, v31
	v_pk_add_f32 v[30:31], v[54:55], v[58:59]
	v_pk_add_f32 v[18:19], v[18:19], v[26:27]
	v_mul_f32_e32 v79, v17, v17
	v_pk_add_f32 v[26:27], v[30:31], v[30:31] op_sel:[0,1] op_sel_hi:[1,0]
	v_pk_add_f32 v[18:19], v[18:19], v[18:19] op_sel:[0,1] op_sel_hi:[1,0]
	v_mov_b32_e32 v57, v78
	v_mov_b32_e32 v61, v79
	v_mov_b32_e32 v27, v71
	v_mov_b32_e32 v19, v47
	v_pk_add_f32 v[30:31], v[56:57], v[60:61]
	v_pk_add_f32 v[18:19], v[18:19], v[26:27]
	v_pk_add_f32 v[48:49], v[62:63], v[66:67]
	v_pk_add_f32 v[18:19], v[18:19], v[30:31]
	v_mul_f32_e32 v83, v29, v29
	v_pk_add_f32 v[48:49], v[48:49], v[48:49] op_sel:[0,1] op_sel_hi:[1,0]
	v_pk_add_f32 v[18:19], v[18:19], v[18:19] op_sel:[0,1] op_sel_hi:[1,0]
	v_mov_b32_e32 v65, v82
	v_mov_b32_e32 v69, v83
	v_mov_b32_e32 v49, v81
	v_mov_b32_e32 v19, v80
	v_pk_add_f32 v[50:51], v[64:65], v[68:69]
	v_pk_add_f32 v[18:19], v[18:19], v[48:49]
	s_nop 0
	v_pk_add_f32 v[18:19], v[18:19], v[50:51]
	s_nop 0
	v_add_f32_e32 v18, v18, v19
	ds_bpermute_b32 v19, v38, v18
	s_waitcnt lgkmcnt(0)
	v_add_f32_e32 v18, v18, v19
	ds_bpermute_b32 v19, v39, v18
	s_waitcnt lgkmcnt(0)
	v_add_f32_e32 v18, v18, v19
	ds_bpermute_b32 v19, v40, v18
	s_waitcnt lgkmcnt(0)
	v_add_f32_e32 v18, v18, v19
	ds_bpermute_b32 v19, v41, v18
	s_waitcnt lgkmcnt(0)
	v_add_f32_e32 v18, v18, v19
	ds_bpermute_b32 v19, v42, v18
	s_waitcnt lgkmcnt(0)
	v_add_f32_e32 v18, v18, v19
	ds_bpermute_b32 v19, v43, v18
	s_waitcnt lgkmcnt(0)
	v_add_f32_e32 v18, v18, v19
	v_fmamk_f32 v18, v18, 0x3a000000, v44
	v_mul_f32_e32 v19, 0x4f800000, v18
	v_cmp_gt_f32_e32 vcc, s7, v18
	s_nop 1
	v_cndmask_b32_e32 v18, v18, v19, vcc
	v_sqrt_f32_e32 v19, v18
	s_nop 0
	v_add_u32_e32 v26, -1, v19
	v_add_u32_e32 v27, 1, v19
	v_fma_f32 v30, -v26, v19, v18
	v_fma_f32 v31, -v27, v19, v18
	v_cmp_ge_f32_e64 s[0:1], 0, v30
	s_nop 1
	v_cndmask_b32_e64 v19, v19, v26, s[0:1]
	v_cmp_lt_f32_e64 s[0:1], 0, v31
	s_nop 1
	v_cndmask_b32_e64 v19, v19, v27, s[0:1]
	v_mul_f32_e32 v26, 0x37800000, v19
	v_cndmask_b32_e32 v19, v19, v26, vcc
	v_cmp_class_f32_e32 vcc, v18, v45
	s_nop 1
	v_cndmask_b32_e32 v18, v19, v18, vcc
	v_div_scale_f32 v19, s[0:1], v18, v18, 1.0
	v_rcp_f32_e32 v27, v19
	v_div_scale_f32 v26, vcc, 1.0, v18, 1.0
	v_fma_f32 v30, -v19, v27, 1.0
	v_fmac_f32_e32 v27, v30, v27
	v_mul_f32_e32 v30, v26, v27
	v_fma_f32 v31, -v19, v30, v26
	v_fmac_f32_e32 v30, v31, v27
	v_fma_f32 v19, -v19, v30, v26
	v_div_fmas_f32 v19, v19, v27, v30
	v_div_fixup_f32 v18, v19, v18, 1.0
	v_pk_mul_f32 v[8:9], v[8:9], v[18:19] op_sel_hi:[1,0]
	v_pk_mul_f32 v[26:27], v[72:73], v[18:19] op_sel_hi:[1,0]
	v_pk_mul_f32 v[6:7], v[6:7], v[18:19] op_sel_hi:[1,0]
	v_pk_mul_f32 v[4:5], v[4:5], v[18:19] op_sel_hi:[1,0]
	v_pk_mul_f32 v[2:3], v[2:3], v[18:19] op_sel_hi:[1,0]
	v_pk_mul_f32 v[12:13], v[12:13], v[18:19] op_sel_hi:[1,0]
	v_pk_mul_f32 v[10:11], v[10:11], v[18:19] op_sel_hi:[1,0]
	v_pk_mul_f32 v[20:21], v[20:21], v[18:19] op_sel_hi:[1,0]
	v_pk_mul_f32 v[30:31], v[74:75], v[18:19] op_sel_hi:[1,0]
	v_pk_mul_f32 v[16:17], v[16:17], v[18:19] op_sel_hi:[1,0]
	v_pk_mul_f32 v[14:15], v[14:15], v[18:19] op_sel_hi:[1,0]
	v_pk_mul_f32 v[24:25], v[24:25], v[18:19] op_sel_hi:[1,0]
	v_pk_mul_f32 v[22:23], v[22:23], v[18:19] op_sel_hi:[1,0]
	v_pk_mul_f32 v[32:33], v[32:33], v[18:19] op_sel_hi:[1,0]
	v_pk_mul_f32 v[48:49], v[76:77], v[18:19] op_sel_hi:[1,0]
	v_pk_mul_f32 v[18:19], v[28:29], v[18:19] op_sel_hi:[1,0]
	v_and_b32_sdwa v47, v9, v46 dst_sel:DWORD dst_unused:UNUSED_PAD src0_sel:WORD_1 src1_sel:DWORD
	v_and_b32_sdwa v50, v8, v46 dst_sel:DWORD dst_unused:UNUSED_PAD src0_sel:WORD_1 src1_sel:DWORD
	v_and_b32_sdwa v28, v27, v46 dst_sel:DWORD dst_unused:UNUSED_PAD src0_sel:WORD_1 src1_sel:DWORD
	v_and_b32_sdwa v29, v26, v46 dst_sel:DWORD dst_unused:UNUSED_PAD src0_sel:WORD_1 src1_sel:DWORD
	v_and_b32_sdwa v53, v5, v46 dst_sel:DWORD dst_unused:UNUSED_PAD src0_sel:WORD_1 src1_sel:DWORD
	v_and_b32_sdwa v54, v4, v46 dst_sel:DWORD dst_unused:UNUSED_PAD src0_sel:WORD_1 src1_sel:DWORD
	v_and_b32_sdwa v55, v3, v46 dst_sel:DWORD dst_unused:UNUSED_PAD src0_sel:WORD_1 src1_sel:DWORD
	v_and_b32_sdwa v56, v2, v46 dst_sel:DWORD dst_unused:UNUSED_PAD src0_sel:WORD_1 src1_sel:DWORD
	v_and_b32_sdwa v57, v13, v46 dst_sel:DWORD dst_unused:UNUSED_PAD src0_sel:WORD_1 src1_sel:DWORD
	v_and_b32_sdwa v58, v12, v46 dst_sel:DWORD dst_unused:UNUSED_PAD src0_sel:WORD_1 src1_sel:DWORD
	v_and_b32_sdwa v61, v21, v46 dst_sel:DWORD dst_unused:UNUSED_PAD src0_sel:WORD_1 src1_sel:DWORD
	v_and_b32_sdwa v62, v20, v46 dst_sel:DWORD dst_unused:UNUSED_PAD src0_sel:WORD_1 src1_sel:DWORD
	v_and_b32_sdwa v63, v31, v46 dst_sel:DWORD dst_unused:UNUSED_PAD src0_sel:WORD_1 src1_sel:DWORD
	v_and_b32_sdwa v64, v30, v46 dst_sel:DWORD dst_unused:UNUSED_PAD src0_sel:WORD_1 src1_sel:DWORD
	v_and_b32_sdwa v65, v17, v46 dst_sel:DWORD dst_unused:UNUSED_PAD src0_sel:WORD_1 src1_sel:DWORD
	v_and_b32_sdwa v66, v16, v46 dst_sel:DWORD dst_unused:UNUSED_PAD src0_sel:WORD_1 src1_sel:DWORD
	v_and_b32_sdwa v69, v25, v46 dst_sel:DWORD dst_unused:UNUSED_PAD src0_sel:WORD_1 src1_sel:DWORD
	v_and_b32_sdwa v70, v24, v46 dst_sel:DWORD dst_unused:UNUSED_PAD src0_sel:WORD_1 src1_sel:DWORD
	v_and_b32_sdwa v73, v33, v46 dst_sel:DWORD dst_unused:UNUSED_PAD src0_sel:WORD_1 src1_sel:DWORD
	v_and_b32_sdwa v74, v32, v46 dst_sel:DWORD dst_unused:UNUSED_PAD src0_sel:WORD_1 src1_sel:DWORD
	v_and_b32_sdwa v77, v19, v46 dst_sel:DWORD dst_unused:UNUSED_PAD src0_sel:WORD_1 src1_sel:DWORD
	v_and_b32_sdwa v78, v18, v46 dst_sel:DWORD dst_unused:UNUSED_PAD src0_sel:WORD_1 src1_sel:DWORD
	v_add3_u32 v9, v9, v47, s6
	v_add3_u32 v8, v8, v50, s6
	v_and_b32_sdwa v51, v7, v46 dst_sel:DWORD dst_unused:UNUSED_PAD src0_sel:WORD_1 src1_sel:DWORD
	v_and_b32_sdwa v52, v6, v46 dst_sel:DWORD dst_unused:UNUSED_PAD src0_sel:WORD_1 src1_sel:DWORD
	v_and_b32_sdwa v59, v11, v46 dst_sel:DWORD dst_unused:UNUSED_PAD src0_sel:WORD_1 src1_sel:DWORD
	v_and_b32_sdwa v60, v10, v46 dst_sel:DWORD dst_unused:UNUSED_PAD src0_sel:WORD_1 src1_sel:DWORD
	v_and_b32_sdwa v67, v15, v46 dst_sel:DWORD dst_unused:UNUSED_PAD src0_sel:WORD_1 src1_sel:DWORD
	v_and_b32_sdwa v68, v14, v46 dst_sel:DWORD dst_unused:UNUSED_PAD src0_sel:WORD_1 src1_sel:DWORD
	v_and_b32_sdwa v71, v23, v46 dst_sel:DWORD dst_unused:UNUSED_PAD src0_sel:WORD_1 src1_sel:DWORD
	v_and_b32_sdwa v72, v22, v46 dst_sel:DWORD dst_unused:UNUSED_PAD src0_sel:WORD_1 src1_sel:DWORD
	v_and_b32_sdwa v75, v49, v46 dst_sel:DWORD dst_unused:UNUSED_PAD src0_sel:WORD_1 src1_sel:DWORD
	v_and_b32_sdwa v76, v48, v46 dst_sel:DWORD dst_unused:UNUSED_PAD src0_sel:WORD_1 src1_sel:DWORD
	v_add3_u32 v26, v26, v29, s6
	v_add3_u32 v27, v27, v28, s6
	v_add3_u32 v5, v5, v53, s6
	v_add3_u32 v4, v4, v54, s6
	v_add3_u32 v28, v2, v56, s6
	v_add3_u32 v29, v3, v55, s6
	v_add3_u32 v2, v13, v57, s6
	v_add3_u32 v3, v12, v58, s6
	v_add3_u32 v12, v21, v61, s6
	v_add3_u32 v13, v20, v62, s6
	v_add3_u32 v20, v30, v64, s6
	v_add3_u32 v21, v31, v63, s6
	v_add3_u32 v17, v17, v65, s6
	v_add3_u32 v16, v16, v66, s6
	v_add3_u32 v25, v25, v69, s6
	v_add3_u32 v24, v24, v70, s6
	v_add3_u32 v30, v33, v73, s6
	v_add3_u32 v31, v32, v74, s6
	v_add3_u32 v19, v19, v77, s6
	v_add3_u32 v18, v18, v78, s6
	v_and_b32_e32 v9, 0xffff0000, v9
	v_and_b32_e32 v8, 0xffff0000, v8
	v_add3_u32 v6, v6, v52, s6
	v_add3_u32 v7, v7, v51, s6
	v_add3_u32 v10, v10, v60, s6
	v_add3_u32 v11, v11, v59, s6
	v_add3_u32 v14, v14, v68, s6
	v_add3_u32 v15, v15, v67, s6
	v_add3_u32 v22, v22, v72, s6
	v_add3_u32 v23, v23, v71, s6
	v_add3_u32 v32, v48, v76, s6
	v_add3_u32 v33, v49, v75, s6
	v_and_b32_e32 v5, 0xffff0000, v5
	v_and_b32_e32 v4, 0xffff0000, v4
	v_and_b32_e32 v47, 0xffff0000, v2
	v_and_b32_e32 v48, 0xffff0000, v3
	v_and_b32_e32 v12, 0xffff0000, v12
	v_and_b32_e32 v13, 0xffff0000, v13
	v_and_b32_e32 v17, 0xffff0000, v17
	v_and_b32_e32 v16, 0xffff0000, v16
	v_and_b32_e32 v25, 0xffff0000, v25
	v_and_b32_e32 v24, 0xffff0000, v24
	v_and_b32_e32 v30, 0xffff0000, v30
	v_and_b32_e32 v31, 0xffff0000, v31
	v_and_b32_e32 v19, 0xffff0000, v19
	v_and_b32_e32 v18, 0xffff0000, v18
	v_or_b32_sdwa v3, v9, v27 dst_sel:DWORD dst_unused:UNUSED_PAD src0_sel:DWORD src1_sel:WORD_1
	v_or_b32_sdwa v2, v8, v26 dst_sel:DWORD dst_unused:UNUSED_PAD src0_sel:DWORD src1_sel:WORD_1
	v_or_b32_sdwa v5, v5, v7 dst_sel:DWORD dst_unused:UNUSED_PAD src0_sel:DWORD src1_sel:WORD_1
	v_or_b32_sdwa v4, v4, v6 dst_sel:DWORD dst_unused:UNUSED_PAD src0_sel:DWORD src1_sel:WORD_1
	v_or_b32_sdwa v7, v47, v29 dst_sel:DWORD dst_unused:UNUSED_PAD src0_sel:DWORD src1_sel:WORD_1
	v_or_b32_sdwa v6, v48, v28 dst_sel:DWORD dst_unused:UNUSED_PAD src0_sel:DWORD src1_sel:WORD_1
	v_or_b32_sdwa v9, v12, v11 dst_sel:DWORD dst_unused:UNUSED_PAD src0_sel:DWORD src1_sel:WORD_1
	v_or_b32_sdwa v8, v13, v10 dst_sel:DWORD dst_unused:UNUSED_PAD src0_sel:DWORD src1_sel:WORD_1
	v_or_b32_sdwa v11, v17, v21 dst_sel:DWORD dst_unused:UNUSED_PAD src0_sel:DWORD src1_sel:WORD_1
	v_or_b32_sdwa v10, v16, v20 dst_sel:DWORD dst_unused:UNUSED_PAD src0_sel:DWORD src1_sel:WORD_1
	v_or_b32_sdwa v13, v25, v15 dst_sel:DWORD dst_unused:UNUSED_PAD src0_sel:DWORD src1_sel:WORD_1
	v_or_b32_sdwa v12, v24, v14 dst_sel:DWORD dst_unused:UNUSED_PAD src0_sel:DWORD src1_sel:WORD_1
	v_or_b32_sdwa v15, v30, v23 dst_sel:DWORD dst_unused:UNUSED_PAD src0_sel:DWORD src1_sel:WORD_1
	v_or_b32_sdwa v14, v31, v22 dst_sel:DWORD dst_unused:UNUSED_PAD src0_sel:DWORD src1_sel:WORD_1
	v_or_b32_sdwa v17, v19, v33 dst_sel:DWORD dst_unused:UNUSED_PAD src0_sel:DWORD src1_sel:WORD_1
	v_or_b32_sdwa v16, v18, v32 dst_sel:DWORD dst_unused:UNUSED_PAD src0_sel:DWORD src1_sel:WORD_1
	global_store_dwordx2 v[36:37], v[2:3], off
	global_store_dwordx2 v[36:37], v[4:5], off offset:512
	global_store_dwordx2 v[36:37], v[6:7], off offset:1024
	global_store_dwordx2 v[36:37], v[8:9], off offset:1536
	global_store_dwordx2 v[36:37], v[10:11], off offset:2048
	global_store_dwordx2 v[36:37], v[12:13], off offset:2560
	global_store_dwordx2 v[36:37], v[14:15], off offset:3072
	global_store_dwordx2 v[36:37], v[16:17], off offset:3584
	v_lshl_add_u64 v[36:37], v[36:37], 0, s[4:5]
	s_cbranch_scc1 .LBB0_191
